# nt policy: P3 stores, X f32 stores of P2/P6/P8, P9 output stores, PLE stores, P4 weight-conversion stores
# baseline (speedup 1.0000x reference)
; __device__ __forceinline__ void transpose_item(const float* __restrict__ W, int K, int N, const float* __restrict__ gain, bf16* WT, int mode, ldsp scr, int item, int lane) {
;     const int nblk = N / 32, kb = item / nblk, nb = item % nblk, k0 = 64 * kb, n0 = 32 * nb;
;     int r0;
;     if (mode == 0) r0 = n0;
;     else if (mode == 3) r0 = (n0 < 2048) ? ((n0 & ~255) + ((n0 >> 5) & 1) * 128 + ((n0 >> 6) & 3) * 32) : n0;
;     else r0 = (n0 >> 7) * 256 + (mode == 2 ? 128 : 0) + (n0 & 127);
;     float tv[32];
; #pragma unroll
;     for (int i = 0; i < 32; ++i) tv[i] = __builtin_nontemporal_load(&W[(size_t)(k0 + 2 * i + (lane >> 5)) * N + n0 + (lane & 31)]);
; __global__ void __launch_bounds__(512, 2) fwd_megakernel(Args a) {
;     ...
;             for (int it = gw; it < 2 * I_A + 2 * I_O + I_PP + 2 * I_GU + I_D; it += NGW) {
;                 int r = it;
;                 if (r < I_A) { transpose_item(a.in[18], 1024, DM, nullptr, Wa_t, 0, scr, r, lane); continue; } r -= I_A;
;                 if (r < I_A) { transpose_item(a.in[19], 1024, DM, nullptr, Wb_t, 0, scr, r, lane); continue; } r -= I_A;
;                 if (r < I_O) { transpose_item(a.in[20], DM, DM, nullptr, Wo_t, 0, scr, r, lane); continue; } r -= I_O;
;                 if (r < I_O) { transpose_item(a.in[26], DM, DM, a.in[25], Wpg_t, 0, scr, r, lane); continue; } r -= I_O;
;                 if (r < I_PP) { transpose_item(a.in[27], 256, DM, nullptr, Wpp_t, 0, scr, r, lane); continue; } r -= I_PP;
;                 if (r < I_GU) { transpose_item(a.in[22], DM, FF, a.in[21], Wgu_t, 1, scr, r, lane); continue; } r -= I_GU;
;                 if (r < I_GU) { transpose_item(a.in[23], DM, FF, a.in[21], Wgu_t, 2, scr, r, lane); continue; } r -= I_GU;
;                 transpose_item(a.in[24], FF, DM, nullptr, Wd_t, 0, scr, r, lane);
.LBB0_570:
	s_cmpk_gt_u32 s12, 0x7ff
	s_cbranch_scc0 .LBB0_680
	s_cmpk_gt_u32 s12, 0xfff
	s_cbranch_scc0 .LBB0_677
	s_cmpk_gt_u32 s12, 0x17ff
	s_cbranch_scc0 .LBB0_650
	s_cmpk_gt_u32 s12, 0x18ff
	s_cbranch_scc0 .LBB0_647
	s_cmpk_gt_u32 s12, 0x2eff
	s_cbranch_scc0 .LBB0_620
	s_cmpk_gt_u32 s12, 0x44ff
	s_cbranch_scc0 .LBB0_577
	s_add_i32 s2, s12, 0xbb00
	s_and_b32 s3, s2, 0xffc0
	s_and_b32 s2, s15, 0x7e0
	v_or_b32_e32 v0, s3, v50
	s_lshl_b32 s4, s2, 2
	v_lshl_add_u64 v[32:33], v[2:3], 0, s[4:5]
	v_lshlrev_b32_e32 v0, 13, v0
	v_lshl_add_u64 v[32:33], v[32:33], 0, v[0:1]
	v_add_co_u32_e32 v34, vcc, 0x4000, v32
	s_lshl_b32 s4, s3, 1
	s_nop 0
	v_addc_co_u32_e32 v35, vcc, 0, v33, vcc
	v_add_co_u32_e32 v36, vcc, 0x8000, v32
	s_nop 1
	v_addc_co_u32_e32 v37, vcc, 0, v33, vcc
	v_add_co_u32_e32 v38, vcc, 0xc000, v32
	s_nop 1
	v_addc_co_u32_e32 v39, vcc, 0, v33, vcc
	v_add_co_u32_e32 v40, vcc, 0x10000, v32
	s_nop 1
	v_addc_co_u32_e32 v41, vcc, 0, v33, vcc
	v_add_co_u32_e32 v42, vcc, 0x14000, v32
	s_nop 1
	v_addc_co_u32_e32 v43, vcc, 0, v33, vcc
	v_add_co_u32_e32 v44, vcc, 0x18000, v32
	s_nop 1
	v_addc_co_u32_e32 v45, vcc, 0, v33, vcc
	v_add_co_u32_e32 v46, vcc, 0x1c000, v32
	s_nop 1
	v_addc_co_u32_e32 v47, vcc, 0, v33, vcc
	global_load_dword v0, v[32:33], off nt
	global_load_dword v108, v[34:35], off nt
	global_load_dword v109, v[36:37], off nt
	global_load_dword v110, v[38:39], off nt
	global_load_dword v111, v[40:41], off nt
	global_load_dword v112, v[42:43], off nt
	global_load_dword v113, v[44:45], off nt
	global_load_dword v114, v[46:47], off nt
	v_add_co_u32_e32 v34, vcc, 0x20000, v32
	s_nop 1
	v_addc_co_u32_e32 v35, vcc, 0, v33, vcc
	v_add_co_u32_e32 v36, vcc, 0x24000, v32
	s_nop 1
	v_addc_co_u32_e32 v37, vcc, 0, v33, vcc
	v_add_co_u32_e32 v38, vcc, 0x28000, v32
	s_nop 1
	v_addc_co_u32_e32 v39, vcc, 0, v33, vcc
	v_add_co_u32_e32 v40, vcc, 0x2c000, v32
	s_nop 1
	v_addc_co_u32_e32 v41, vcc, 0, v33, vcc
	v_add_co_u32_e32 v42, vcc, 0x30000, v32
	s_nop 1
	v_addc_co_u32_e32 v43, vcc, 0, v33, vcc
	v_add_co_u32_e32 v44, vcc, 0x34000, v32
	s_nop 1
	v_addc_co_u32_e32 v45, vcc, 0, v33, vcc
	v_add_co_u32_e32 v46, vcc, 0x38000, v32
	s_nop 1
	v_addc_co_u32_e32 v47, vcc, 0, v33, vcc
	v_add_co_u32_e32 v48, vcc, 0x3c000, v32
	s_nop 1
	v_addc_co_u32_e32 v49, vcc, 0, v33, vcc
	global_load_dword v115, v[34:35], off nt
	global_load_dword v116, v[36:37], off nt
	global_load_dword v117, v[38:39], off nt
	global_load_dword v118, v[40:41], off nt
	global_load_dword v119, v[42:43], off nt
	global_load_dword v120, v[44:45], off nt
	global_load_dword v121, v[46:47], off nt
	global_load_dword v122, v[48:49], off nt
	v_add_co_u32_e32 v34, vcc, 0x40000, v32
	s_nop 1
	v_addc_co_u32_e32 v35, vcc, 0, v33, vcc
	v_add_co_u32_e32 v36, vcc, 0x44000, v32
	s_nop 1
	v_addc_co_u32_e32 v37, vcc, 0, v33, vcc
	v_add_co_u32_e32 v38, vcc, 0x48000, v32
	s_nop 1
	v_addc_co_u32_e32 v39, vcc, 0, v33, vcc
	v_add_co_u32_e32 v40, vcc, 0x4c000, v32
	s_nop 1
	v_addc_co_u32_e32 v41, vcc, 0, v33, vcc
	v_add_co_u32_e32 v42, vcc, 0x50000, v32
	s_nop 1
	v_addc_co_u32_e32 v43, vcc, 0, v33, vcc
	v_add_co_u32_e32 v44, vcc, 0x54000, v32
	s_nop 1
	v_addc_co_u32_e32 v45, vcc, 0, v33, vcc
	v_add_co_u32_e32 v46, vcc, 0x58000, v32
	s_nop 1
	v_addc_co_u32_e32 v47, vcc, 0, v33, vcc
	v_add_co_u32_e32 v48, vcc, 0x5c000, v32
	s_nop 1
	v_addc_co_u32_e32 v49, vcc, 0, v33, vcc
	global_load_dword v123, v[34:35], off nt
	global_load_dword v124, v[36:37], off nt
	global_load_dword v125, v[38:39], off nt
	global_load_dword v126, v[40:41], off nt
	global_load_dword v127, v[42:43], off nt
	s_nop 0
	global_load_dword v44, v[44:45], off nt
	s_nop 0
	global_load_dword v45, v[46:47], off nt
	s_nop 0
	global_load_dword v46, v[48:49], off nt
	v_add_co_u32_e32 v34, vcc, 0x60000, v32
	s_nop 1
	v_addc_co_u32_e32 v35, vcc, 0, v33, vcc
	v_add_co_u32_e32 v36, vcc, 0x64000, v32
	s_nop 1
	v_addc_co_u32_e32 v37, vcc, 0, v33, vcc
	global_load_dword v47, v[34:35], off nt
	global_load_dword v48, v[36:37], off nt
	v_add_co_u32_e32 v34, vcc, 0x68000, v32
	s_nop 1
	v_addc_co_u32_e32 v35, vcc, 0, v33, vcc
	v_add_co_u32_e32 v36, vcc, 0x6c000, v32
	s_nop 1
	v_addc_co_u32_e32 v37, vcc, 0, v33, vcc
	v_add_co_u32_e32 v38, vcc, 0x70000, v32
	s_nop 1
	v_addc_co_u32_e32 v39, vcc, 0, v33, vcc
	v_add_co_u32_e32 v40, vcc, 0x74000, v32
	s_nop 1
	v_addc_co_u32_e32 v41, vcc, 0, v33, vcc
	v_add_co_u32_e32 v42, vcc, 0x78000, v32
	s_nop 1
	v_addc_co_u32_e32 v43, vcc, 0, v33, vcc
	v_add_co_u32_e32 v32, vcc, 0x7c000, v32
	global_load_dword v34, v[34:35], off nt
	s_nop 0
	global_load_dword v35, v[36:37], off nt
	s_nop 0
	global_load_dword v36, v[38:39], off nt
	global_load_dword v37, v[40:41], off nt
	s_nop 0
	global_load_dword v38, v[42:43], off nt
	v_addc_co_u32_e32 v33, vcc, 0, v33, vcc
	global_load_dword v32, v[32:33], off nt
	v_add_u32_e32 v33, s14, v51
	s_waitcnt vmcnt(0)
; __device__ __forceinline__ unsigned cvtpk(float lo, float hi) { f32x2_t v = {lo, hi}; bf16x2_t b = __builtin_convertvector(v, bf16x2_t); return __builtin_bit_cast(unsigned, b); }
; __device__ __forceinline__ void transpose_item(const float* __restrict__ W, int K, int N, const float* __restrict__ gain, bf16* WT, int mode, ldsp scr, int item, int lane) {
;     ...
; #pragma unroll
;     for (int i = 0; i < 32; ++i) { const int kk = 2 * i + (lane >> 5); float v = tv[i]; if (gain) v *= gain[k0 + kk]; lds_st<float>(scr + 4 * (kk * 33 + (lane & 31)), v); }
;     asm volatile("s_waitcnt lgkmcnt(0)" ::: "memory");
;     const int c = lane & 7;
; #pragma unroll
;     for (int j = 0; j < 4; ++j) { const int n = (lane >> 3) + 8 * j; ldsp s = scr + 4 * ((8 * c) * 33 + n);
;         u32x4 o; o[0] = cvtpk(lds_ld<float>(s), lds_ld<float>(s + 132)); o[1] = cvtpk(lds_ld<float>(s + 264), lds_ld<float>(s + 396));
;         o[2] = cvtpk(lds_ld<float>(s + 528), lds_ld<float>(s + 660)); o[3] = cvtpk(lds_ld<float>(s + 792), lds_ld<float>(s + 924));
;         *(u32x4*)(WT + (size_t)(r0 + n) * K + k0 + 8 * c) = o; }
	ds_write_b32 v33, v0
	v_add_u32_e32 v0, s14, v52
	ds_write_b32 v0, v108
	v_add_u32_e32 v0, s14, v53
	ds_write_b32 v0, v109
	v_add_u32_e32 v0, s14, v54
	ds_write_b32 v0, v110
	v_add_u32_e32 v0, s14, v55
	ds_write_b32 v0, v111
	v_add_u32_e32 v0, s14, v56
	ds_write_b32 v0, v112
	v_add_u32_e32 v0, s14, v57
	ds_write_b32 v0, v113
	v_add_u32_e32 v0, s14, v58
	ds_write_b32 v0, v114
	v_add_u32_e32 v0, s14, v59
	ds_write_b32 v0, v115
	v_add_u32_e32 v0, s14, v60
	ds_write_b32 v0, v116
	v_add_u32_e32 v0, s14, v61
	ds_write_b32 v0, v117
	v_add_u32_e32 v0, s14, v62
	ds_write_b32 v0, v118
	v_add_u32_e32 v0, s14, v63
	ds_write_b32 v0, v119
	v_add_u32_e32 v0, s14, v64
	ds_write_b32 v0, v120
	v_add_u32_e32 v0, s14, v65
	ds_write_b32 v0, v121
	v_add_u32_e32 v0, s14, v66
	ds_write_b32 v0, v122
	v_add_u32_e32 v0, s14, v67
	ds_write_b32 v0, v123
	v_add_u32_e32 v0, s14, v68
	ds_write_b32 v0, v124
	v_add_u32_e32 v0, s14, v69
	ds_write_b32 v0, v125
	v_add_u32_e32 v0, s14, v70
	ds_write_b32 v0, v126
	v_add_u32_e32 v0, s14, v71
	ds_write_b32 v0, v127
	v_add_u32_e32 v0, s14, v72
	ds_write_b32 v0, v44
	v_add_u32_e32 v0, s14, v73
	ds_write_b32 v0, v45
	v_add_u32_e32 v0, s14, v74
	ds_write_b32 v0, v46
	v_add_u32_e32 v0, s14, v75
	ds_write_b32 v0, v47
	v_add_u32_e32 v0, s14, v76
	ds_write_b32 v0, v48
	v_add_u32_e32 v0, s14, v77
	v_lshl_add_u64 v[40:41], v[4:5], 0, s[4:5]
	ds_write_b32 v0, v34
	v_add_u32_e32 v0, s14, v78
	ds_write_b32 v0, v35
	v_add_u32_e32 v0, s14, v79
	ds_write_b32 v0, v36
	v_add_u32_e32 v0, s14, v80
	ds_write_b32 v0, v37
	v_add_u32_e32 v0, s14, v81
	ds_write_b32 v0, v38
	v_add_u32_e32 v0, s14, v82
	ds_write_b32 v0, v32
	s_waitcnt lgkmcnt(0)
	v_add_u32_e32 v0, s14, v84
	ds_read2_b32 v[32:33], v0 offset1:33
	ds_read2_b32 v[34:35], v0 offset0:66 offset1:99
	ds_read2_b32 v[36:37], v0 offset0:132 offset1:165
	ds_read2_b32 v[38:39], v0 offset0:198 offset1:231
	v_or_b32_e32 v0, s2, v83
	v_mul_u32_u24_e32 v0, 0x1600, v0
	v_lshlrev_b32_e32 v0, 1, v0
	s_waitcnt lgkmcnt(3)
	v_cvt_pk_bf16_f32 v32, v32, v33
	s_waitcnt lgkmcnt(2)
	v_cvt_pk_bf16_f32 v33, v34, v35
	s_waitcnt lgkmcnt(1)
	v_cvt_pk_bf16_f32 v34, v36, v37
	v_lshl_add_u64 v[36:37], v[40:41], 0, v[0:1]
	v_add_u32_e32 v0, s14, v86
	s_waitcnt lgkmcnt(0)
	v_cvt_pk_bf16_f32 v35, v38, v39
	ds_read2_b32 v[38:39], v0 offset1:33
	ds_read2_b32 v[42:43], v0 offset0:66 offset1:99
	ds_read2_b32 v[44:45], v0 offset0:132 offset1:165
	ds_read2_b32 v[46:47], v0 offset0:198 offset1:231
	v_or_b32_e32 v0, s2, v85
	v_mul_u32_u24_e32 v0, 0x1600, v0
	v_lshlrev_b32_e32 v0, 1, v0
	global_store_dwordx4 v[36:37], v[32:35], off nt
	v_lshl_add_u64 v[36:37], v[40:41], 0, v[0:1]
	v_add_u32_e32 v0, s14, v88
	s_waitcnt lgkmcnt(3)
	v_cvt_pk_bf16_f32 v32, v38, v39
	s_waitcnt lgkmcnt(2)
	v_cvt_pk_bf16_f32 v33, v42, v43
	s_waitcnt lgkmcnt(1)
	v_cvt_pk_bf16_f32 v34, v44, v45
	s_waitcnt lgkmcnt(0)
	v_cvt_pk_bf16_f32 v35, v46, v47
	ds_read2_b32 v[38:39], v0 offset1:33
	ds_read2_b32 v[42:43], v0 offset0:66 offset1:99
	ds_read2_b32 v[44:45], v0 offset0:132 offset1:165
	ds_read2_b32 v[46:47], v0 offset0:198 offset1:231
	v_or_b32_e32 v0, s2, v87
	v_mul_u32_u24_e32 v0, 0x1600, v0
	v_lshlrev_b32_e32 v0, 1, v0
	global_store_dwordx4 v[36:37], v[32:35], off nt
	v_lshl_add_u64 v[36:37], v[40:41], 0, v[0:1]
	v_add_u32_e32 v0, s14, v90
	s_waitcnt lgkmcnt(3)
	v_cvt_pk_bf16_f32 v32, v38, v39
	s_waitcnt lgkmcnt(2)
	v_cvt_pk_bf16_f32 v33, v42, v43
	s_waitcnt lgkmcnt(1)
	v_cvt_pk_bf16_f32 v34, v44, v45
	s_waitcnt lgkmcnt(0)
	v_cvt_pk_bf16_f32 v35, v46, v47
	ds_read2_b32 v[38:39], v0 offset1:33
	ds_read2_b32 v[42:43], v0 offset0:66 offset1:99
	ds_read2_b32 v[44:45], v0 offset0:132 offset1:165
	ds_read2_b32 v[46:47], v0 offset0:198 offset1:231
	v_or_b32_e32 v0, s2, v89
	v_mul_u32_u24_e32 v0, 0x1600, v0
	v_lshlrev_b32_e32 v0, 1, v0
	global_store_dwordx4 v[36:37], v[32:35], off nt
	v_lshl_add_u64 v[36:37], v[40:41], 0, v[0:1]
	s_mov_b64 s[2:3], 0
	s_waitcnt lgkmcnt(3)
	v_cvt_pk_bf16_f32 v32, v38, v39
	s_waitcnt lgkmcnt(2)
	v_cvt_pk_bf16_f32 v33, v42, v43
	s_waitcnt lgkmcnt(1)
	v_cvt_pk_bf16_f32 v34, v44, v45
	s_waitcnt lgkmcnt(0)
	v_cvt_pk_bf16_f32 v35, v46, v47
	global_store_dwordx4 v[36:37], v[32:35], off nt
	s_waitcnt lgkmcnt(0)

; __device__ __forceinline__ unsigned cvtpk(float lo, float hi) { f32x2_t v = {lo, hi}; bf16x2_t b = __builtin_convertvector(v, bf16x2_t); return __builtin_bit_cast(unsigned, b); }
; __device__ __forceinline__ void transpose_item(const float* __restrict__ W, int K, int N, const float* __restrict__ gain, bf16* WT, int mode, ldsp scr, int item, int lane) {
;     ...
; #pragma unroll
;     for (int i = 0; i < 32; ++i) { const int kk = 2 * i + (lane >> 5); float v = tv[i]; if (gain) v *= gain[k0 + kk]; lds_st<float>(scr + 4 * (kk * 33 + (lane & 31)), v); }
;     asm volatile("s_waitcnt lgkmcnt(0)" ::: "memory");
;     const int c = lane & 7;
; #pragma unroll
;     for (int j = 0; j < 4; ++j) { const int n = (lane >> 3) + 8 * j; ldsp s = scr + 4 * ((8 * c) * 33 + n);
;         u32x4 o; o[0] = cvtpk(lds_ld<float>(s), lds_ld<float>(s + 132)); o[1] = cvtpk(lds_ld<float>(s + 264), lds_ld<float>(s + 396));
;         o[2] = cvtpk(lds_ld<float>(s + 528), lds_ld<float>(s + 660)); o[3] = cvtpk(lds_ld<float>(s + 792), lds_ld<float>(s + 924));
;         *(u32x4*)(WT + (size_t)(r0 + n) * K + k0 + 8 * c) = o; }
.LBB0_618:
	s_waitcnt vmcnt(2)
	v_add_u32_e32 v0, s14, v81
	ds_write_b32 v0, v34
	v_add_u32_e32 v0, s14, v82
	s_lshl_b32 s2, s56, 5
	s_lshl_b32 s3, s56, 6
	ds_write_b32 v0, v35
	s_and_b32 s3, s3, 0x3f00
	s_and_b32 s2, s2, 0x60
	s_waitcnt lgkmcnt(0)
	v_add_u32_e32 v0, s14, v84
	s_or_b32 s2, s2, s3
	s_waitcnt vmcnt(0)
	ds_read2_b32 v[32:33], v0 offset1:33
	ds_read2_b32 v[34:35], v0 offset0:66 offset1:99
	ds_read2_b32 v[36:37], v0 offset0:132 offset1:165
	ds_read2_b32 v[38:39], v0 offset0:198 offset1:231
	s_bitset1_b32 s2, 7
	s_lshl_b32 s4, s55, 1
	v_or_b32_e32 v0, s2, v83
	v_lshl_add_u64 v[40:41], v[8:9], 0, s[4:5]
	v_lshlrev_b32_e32 v0, 12, v0
	s_waitcnt lgkmcnt(3)
	v_cvt_pk_bf16_f32 v32, v32, v33
	s_waitcnt lgkmcnt(2)
	v_cvt_pk_bf16_f32 v33, v34, v35
	s_waitcnt lgkmcnt(1)
	v_cvt_pk_bf16_f32 v34, v36, v37
	v_lshl_add_u64 v[36:37], v[40:41], 0, v[0:1]
	v_add_u32_e32 v0, s14, v86
	s_waitcnt lgkmcnt(0)
	v_cvt_pk_bf16_f32 v35, v38, v39
	ds_read2_b32 v[38:39], v0 offset1:33
	ds_read2_b32 v[42:43], v0 offset0:66 offset1:99
	ds_read2_b32 v[44:45], v0 offset0:132 offset1:165
	ds_read2_b32 v[46:47], v0 offset0:198 offset1:231
	v_or_b32_e32 v0, s2, v85
	v_lshlrev_b32_e32 v0, 12, v0
	global_store_dwordx4 v[36:37], v[32:35], off nt
	v_lshl_add_u64 v[36:37], v[40:41], 0, v[0:1]
	v_add_u32_e32 v0, s14, v88
	s_waitcnt lgkmcnt(3)
	v_cvt_pk_bf16_f32 v32, v38, v39
	s_waitcnt lgkmcnt(2)
	v_cvt_pk_bf16_f32 v33, v42, v43
	s_waitcnt lgkmcnt(1)
	v_cvt_pk_bf16_f32 v34, v44, v45
	s_waitcnt lgkmcnt(0)
	v_cvt_pk_bf16_f32 v35, v46, v47
	ds_read2_b32 v[38:39], v0 offset1:33
	ds_read2_b32 v[42:43], v0 offset0:66 offset1:99
	ds_read2_b32 v[44:45], v0 offset0:132 offset1:165
	ds_read2_b32 v[46:47], v0 offset0:198 offset1:231
	v_or_b32_e32 v0, s2, v87
	v_lshlrev_b32_e32 v0, 12, v0
	global_store_dwordx4 v[36:37], v[32:35], off nt
	v_lshl_add_u64 v[36:37], v[40:41], 0, v[0:1]
	v_add_u32_e32 v0, s14, v90
	s_waitcnt lgkmcnt(3)
	v_cvt_pk_bf16_f32 v32, v38, v39
	s_waitcnt lgkmcnt(2)
	v_cvt_pk_bf16_f32 v33, v42, v43
	s_waitcnt lgkmcnt(1)
	v_cvt_pk_bf16_f32 v34, v44, v45
	s_waitcnt lgkmcnt(0)
	v_cvt_pk_bf16_f32 v35, v46, v47
	ds_read2_b32 v[38:39], v0 offset1:33
	ds_read2_b32 v[42:43], v0 offset0:66 offset1:99
	ds_read2_b32 v[44:45], v0 offset0:132 offset1:165
	ds_read2_b32 v[46:47], v0 offset0:198 offset1:231
	v_or_b32_e32 v0, s2, v89
	v_lshlrev_b32_e32 v0, 12, v0
	global_store_dwordx4 v[36:37], v[32:35], off nt
	v_lshl_add_u64 v[36:37], v[40:41], 0, v[0:1]
	s_waitcnt lgkmcnt(3)
	v_cvt_pk_bf16_f32 v32, v38, v39
	s_waitcnt lgkmcnt(2)
	v_cvt_pk_bf16_f32 v33, v42, v43
	s_waitcnt lgkmcnt(1)
	v_cvt_pk_bf16_f32 v34, v44, v45
	s_waitcnt lgkmcnt(0)
	v_cvt_pk_bf16_f32 v35, v46, v47
	global_store_dwordx4 v[36:37], v[32:35], off nt
	s_waitcnt lgkmcnt(0)

; __device__ __forceinline__ unsigned cvtpk(float lo, float hi) { f32x2_t v = {lo, hi}; bf16x2_t b = __builtin_convertvector(v, bf16x2_t); return __builtin_bit_cast(unsigned, b); }
; __device__ __forceinline__ void transpose_item(const float* __restrict__ W, int K, int N, const float* __restrict__ gain, bf16* WT, int mode, ldsp scr, int item, int lane) {
;     ...
; #pragma unroll
;     for (int i = 0; i < 32; ++i) { const int kk = 2 * i + (lane >> 5); float v = tv[i]; if (gain) v *= gain[k0 + kk]; lds_st<float>(scr + 4 * (kk * 33 + (lane & 31)), v); }
;     asm volatile("s_waitcnt lgkmcnt(0)" ::: "memory");
;     const int c = lane & 7;
; #pragma unroll
;     for (int j = 0; j < 4; ++j) { const int n = (lane >> 3) + 8 * j; ldsp s = scr + 4 * ((8 * c) * 33 + n);
;         u32x4 o; o[0] = cvtpk(lds_ld<float>(s), lds_ld<float>(s + 132)); o[1] = cvtpk(lds_ld<float>(s + 264), lds_ld<float>(s + 396));
;         o[2] = cvtpk(lds_ld<float>(s + 528), lds_ld<float>(s + 660)); o[3] = cvtpk(lds_ld<float>(s + 792), lds_ld<float>(s + 924));
;         *(u32x4*)(WT + (size_t)(r0 + n) * K + k0 + 8 * c) = o; }
.LBB0_645:
	s_waitcnt vmcnt(2)
	v_add_u32_e32 v0, s14, v81
	ds_write_b32 v0, v34
	v_add_u32_e32 v0, s14, v82
	ds_write_b32 v0, v35
	s_lshl_b32 s2, s56, 5
	s_lshl_b32 s3, s56, 6
	s_waitcnt lgkmcnt(0)
	v_add_u32_e32 v0, s14, v84
	s_and_b32 s3, s3, 0x3f00
	s_and_b32 s2, s2, 0x60
	s_waitcnt vmcnt(0)
	ds_read2_b32 v[32:33], v0 offset1:33
	ds_read2_b32 v[34:35], v0 offset0:66 offset1:99
	ds_read2_b32 v[36:37], v0 offset0:132 offset1:165
	ds_read2_b32 v[38:39], v0 offset0:198 offset1:231
	s_or_b32 s2, s3, s2
	s_lshl_b32 s4, s55, 1
	v_or_b32_e32 v0, s2, v83
	v_lshl_add_u64 v[40:41], v[8:9], 0, s[4:5]
	v_lshlrev_b32_e32 v0, 12, v0
	s_waitcnt lgkmcnt(3)
	v_cvt_pk_bf16_f32 v32, v32, v33
	s_waitcnt lgkmcnt(2)
	v_cvt_pk_bf16_f32 v33, v34, v35
	s_waitcnt lgkmcnt(1)
	v_cvt_pk_bf16_f32 v34, v36, v37
	v_lshl_add_u64 v[36:37], v[40:41], 0, v[0:1]
	v_add_u32_e32 v0, s14, v86
	s_waitcnt lgkmcnt(0)
	v_cvt_pk_bf16_f32 v35, v38, v39
	ds_read2_b32 v[38:39], v0 offset1:33
	ds_read2_b32 v[42:43], v0 offset0:66 offset1:99
	ds_read2_b32 v[44:45], v0 offset0:132 offset1:165
	ds_read2_b32 v[46:47], v0 offset0:198 offset1:231
	v_or_b32_e32 v0, s2, v85
	v_lshlrev_b32_e32 v0, 12, v0
	global_store_dwordx4 v[36:37], v[32:35], off nt
	v_lshl_add_u64 v[36:37], v[40:41], 0, v[0:1]
	v_add_u32_e32 v0, s14, v88
	s_waitcnt lgkmcnt(3)
	v_cvt_pk_bf16_f32 v32, v38, v39
	s_waitcnt lgkmcnt(2)
	v_cvt_pk_bf16_f32 v33, v42, v43
	s_waitcnt lgkmcnt(1)
	v_cvt_pk_bf16_f32 v34, v44, v45
	s_waitcnt lgkmcnt(0)
	v_cvt_pk_bf16_f32 v35, v46, v47
	ds_read2_b32 v[38:39], v0 offset1:33
	ds_read2_b32 v[42:43], v0 offset0:66 offset1:99
	ds_read2_b32 v[44:45], v0 offset0:132 offset1:165
	ds_read2_b32 v[46:47], v0 offset0:198 offset1:231
	v_or_b32_e32 v0, s2, v87
	v_lshlrev_b32_e32 v0, 12, v0
	global_store_dwordx4 v[36:37], v[32:35], off nt
	v_lshl_add_u64 v[36:37], v[40:41], 0, v[0:1]
	v_add_u32_e32 v0, s14, v90
	s_waitcnt lgkmcnt(3)
	v_cvt_pk_bf16_f32 v32, v38, v39
	s_waitcnt lgkmcnt(2)
	v_cvt_pk_bf16_f32 v33, v42, v43
	s_waitcnt lgkmcnt(1)
	v_cvt_pk_bf16_f32 v34, v44, v45
	s_waitcnt lgkmcnt(0)
	v_cvt_pk_bf16_f32 v35, v46, v47
	ds_read2_b32 v[38:39], v0 offset1:33
	ds_read2_b32 v[42:43], v0 offset0:66 offset1:99
	ds_read2_b32 v[44:45], v0 offset0:132 offset1:165
	ds_read2_b32 v[46:47], v0 offset0:198 offset1:231
	v_or_b32_e32 v0, s2, v89
	v_lshlrev_b32_e32 v0, 12, v0
	global_store_dwordx4 v[36:37], v[32:35], off nt
	v_lshl_add_u64 v[36:37], v[40:41], 0, v[0:1]
	s_waitcnt lgkmcnt(3)
	v_cvt_pk_bf16_f32 v32, v38, v39
	s_waitcnt lgkmcnt(2)
	v_cvt_pk_bf16_f32 v33, v42, v43
	s_waitcnt lgkmcnt(1)
	v_cvt_pk_bf16_f32 v34, v44, v45
	s_waitcnt lgkmcnt(0)
	v_cvt_pk_bf16_f32 v35, v46, v47
	global_store_dwordx4 v[36:37], v[32:35], off nt
	s_waitcnt lgkmcnt(0)

; __device__ __forceinline__ void transpose_item(const float* __restrict__ W, int K, int N, const float* __restrict__ gain, bf16* WT, int mode, ldsp scr, int item, int lane) {
;     const int nblk = N / 32, kb = item / nblk, nb = item % nblk, k0 = 64 * kb, n0 = 32 * nb;
;     int r0;
;     if (mode == 0) r0 = n0;
;     else if (mode == 3) r0 = (n0 < 2048) ? ((n0 & ~255) + ((n0 >> 5) & 1) * 128 + ((n0 >> 6) & 3) * 32) : n0;
;     else r0 = (n0 >> 7) * 256 + (mode == 2 ? 128 : 0) + (n0 & 127);
;     float tv[32];
; #pragma unroll
;     for (int i = 0; i < 32; ++i) tv[i] = __builtin_nontemporal_load(&W[(size_t)(k0 + 2 * i + (lane >> 5)) * N + n0 + (lane & 31)]);
.LBB0_647:
	s_andn2_b64 vcc, exec, s[2:3]
	s_cbranch_vccnz .LBB0_649
	s_and_b32 s3, s12, 0xc0
	s_and_b32 s2, s15, 0x7e0
	v_or_b32_e32 v0, s3, v50
	s_lshl_b32 s4, s2, 2
	v_lshl_add_u64 v[32:33], v[12:13], 0, s[4:5]
	v_lshlrev_b32_e32 v0, 13, v0
	v_lshl_add_u64 v[32:33], v[32:33], 0, v[0:1]
	v_add_co_u32_e32 v34, vcc, 0x4000, v32
	s_lshl_b32 s4, s3, 1
	s_nop 0
	v_addc_co_u32_e32 v35, vcc, 0, v33, vcc
	v_add_co_u32_e32 v36, vcc, 0x8000, v32
	s_nop 1
	v_addc_co_u32_e32 v37, vcc, 0, v33, vcc
	v_add_co_u32_e32 v38, vcc, 0xc000, v32
	s_nop 1
	v_addc_co_u32_e32 v39, vcc, 0, v33, vcc
	v_add_co_u32_e32 v40, vcc, 0x10000, v32
	s_nop 1
	v_addc_co_u32_e32 v41, vcc, 0, v33, vcc
	v_add_co_u32_e32 v42, vcc, 0x14000, v32
	s_nop 1
	v_addc_co_u32_e32 v43, vcc, 0, v33, vcc
	v_add_co_u32_e32 v44, vcc, 0x18000, v32
	s_nop 1
	v_addc_co_u32_e32 v45, vcc, 0, v33, vcc
	v_add_co_u32_e32 v46, vcc, 0x1c000, v32
	s_nop 1
	v_addc_co_u32_e32 v47, vcc, 0, v33, vcc
	global_load_dword v0, v[32:33], off nt
	global_load_dword v108, v[34:35], off nt
	global_load_dword v109, v[36:37], off nt
	global_load_dword v110, v[38:39], off nt
	global_load_dword v111, v[40:41], off nt
	global_load_dword v112, v[42:43], off nt
	global_load_dword v113, v[44:45], off nt
	global_load_dword v114, v[46:47], off nt
	v_add_co_u32_e32 v34, vcc, 0x20000, v32
	s_nop 1
	v_addc_co_u32_e32 v35, vcc, 0, v33, vcc
	v_add_co_u32_e32 v36, vcc, 0x24000, v32
	s_nop 1
	v_addc_co_u32_e32 v37, vcc, 0, v33, vcc
	v_add_co_u32_e32 v38, vcc, 0x28000, v32
	s_nop 1
	v_addc_co_u32_e32 v39, vcc, 0, v33, vcc
	v_add_co_u32_e32 v40, vcc, 0x2c000, v32
	s_nop 1
	v_addc_co_u32_e32 v41, vcc, 0, v33, vcc
	v_add_co_u32_e32 v42, vcc, 0x30000, v32
	s_nop 1
	v_addc_co_u32_e32 v43, vcc, 0, v33, vcc
	v_add_co_u32_e32 v44, vcc, 0x34000, v32
	s_nop 1
	v_addc_co_u32_e32 v45, vcc, 0, v33, vcc
	v_add_co_u32_e32 v46, vcc, 0x38000, v32
	s_nop 1
	v_addc_co_u32_e32 v47, vcc, 0, v33, vcc
	v_add_co_u32_e32 v48, vcc, 0x3c000, v32
	s_nop 1
	v_addc_co_u32_e32 v49, vcc, 0, v33, vcc
	global_load_dword v115, v[34:35], off nt
	global_load_dword v116, v[36:37], off nt
	global_load_dword v117, v[38:39], off nt
	global_load_dword v118, v[40:41], off nt
	global_load_dword v119, v[42:43], off nt
	global_load_dword v120, v[44:45], off nt
	global_load_dword v121, v[46:47], off nt
	global_load_dword v122, v[48:49], off nt
	v_add_co_u32_e32 v34, vcc, 0x40000, v32
	s_nop 1
	v_addc_co_u32_e32 v35, vcc, 0, v33, vcc
	v_add_co_u32_e32 v36, vcc, 0x44000, v32
	s_nop 1
	v_addc_co_u32_e32 v37, vcc, 0, v33, vcc
	v_add_co_u32_e32 v38, vcc, 0x48000, v32
	s_nop 1
	v_addc_co_u32_e32 v39, vcc, 0, v33, vcc
	v_add_co_u32_e32 v40, vcc, 0x4c000, v32
	s_nop 1
	v_addc_co_u32_e32 v41, vcc, 0, v33, vcc
	v_add_co_u32_e32 v42, vcc, 0x50000, v32
	s_nop 1
	v_addc_co_u32_e32 v43, vcc, 0, v33, vcc
	v_add_co_u32_e32 v44, vcc, 0x54000, v32
	s_nop 1
	v_addc_co_u32_e32 v45, vcc, 0, v33, vcc
	v_add_co_u32_e32 v46, vcc, 0x58000, v32
	s_nop 1
	v_addc_co_u32_e32 v47, vcc, 0, v33, vcc
	v_add_co_u32_e32 v48, vcc, 0x5c000, v32
	s_nop 1
	v_addc_co_u32_e32 v49, vcc, 0, v33, vcc
	global_load_dword v123, v[34:35], off nt
	global_load_dword v124, v[36:37], off nt
	global_load_dword v125, v[38:39], off nt
	global_load_dword v126, v[40:41], off nt
	global_load_dword v127, v[42:43], off nt
	s_nop 0
	global_load_dword v44, v[44:45], off nt
	s_nop 0
	global_load_dword v45, v[46:47], off nt
	s_nop 0
	global_load_dword v46, v[48:49], off nt
	v_add_co_u32_e32 v34, vcc, 0x60000, v32
	s_nop 1
	v_addc_co_u32_e32 v35, vcc, 0, v33, vcc
	v_add_co_u32_e32 v36, vcc, 0x64000, v32
	s_nop 1
	v_addc_co_u32_e32 v37, vcc, 0, v33, vcc
	global_load_dword v47, v[34:35], off nt
	global_load_dword v48, v[36:37], off nt
	v_add_co_u32_e32 v34, vcc, 0x68000, v32
	s_nop 1
	v_addc_co_u32_e32 v35, vcc, 0, v33, vcc
	v_add_co_u32_e32 v36, vcc, 0x6c000, v32
	s_nop 1
	v_addc_co_u32_e32 v37, vcc, 0, v33, vcc
	v_add_co_u32_e32 v38, vcc, 0x70000, v32
	s_nop 1
	v_addc_co_u32_e32 v39, vcc, 0, v33, vcc
	v_add_co_u32_e32 v40, vcc, 0x74000, v32
	s_nop 1
	v_addc_co_u32_e32 v41, vcc, 0, v33, vcc
	v_add_co_u32_e32 v42, vcc, 0x78000, v32
	s_nop 1
	v_addc_co_u32_e32 v43, vcc, 0, v33, vcc
	v_add_co_u32_e32 v32, vcc, 0x7c000, v32
	global_load_dword v34, v[34:35], off nt
	s_nop 0
	global_load_dword v35, v[36:37], off nt
	s_nop 0
	global_load_dword v36, v[38:39], off nt
	global_load_dword v37, v[40:41], off nt
	s_nop 0
	global_load_dword v38, v[42:43], off nt
	v_addc_co_u32_e32 v33, vcc, 0, v33, vcc
	global_load_dword v32, v[32:33], off nt
	v_add_u32_e32 v33, s14, v51
	s_waitcnt vmcnt(0)
; __device__ __forceinline__ unsigned cvtpk(float lo, float hi) { f32x2_t v = {lo, hi}; bf16x2_t b = __builtin_convertvector(v, bf16x2_t); return __builtin_bit_cast(unsigned, b); }
; __device__ __forceinline__ void transpose_item(const float* __restrict__ W, int K, int N, const float* __restrict__ gain, bf16* WT, int mode, ldsp scr, int item, int lane) {
;     ...
; #pragma unroll
;     for (int i = 0; i < 32; ++i) { const int kk = 2 * i + (lane >> 5); float v = tv[i]; if (gain) v *= gain[k0 + kk]; lds_st<float>(scr + 4 * (kk * 33 + (lane & 31)), v); }
;     asm volatile("s_waitcnt lgkmcnt(0)" ::: "memory");
;     const int c = lane & 7;
; #pragma unroll
;     for (int j = 0; j < 4; ++j) { const int n = (lane >> 3) + 8 * j; ldsp s = scr + 4 * ((8 * c) * 33 + n);
;         u32x4 o; o[0] = cvtpk(lds_ld<float>(s), lds_ld<float>(s + 132)); o[1] = cvtpk(lds_ld<float>(s + 264), lds_ld<float>(s + 396));
;         o[2] = cvtpk(lds_ld<float>(s + 528), lds_ld<float>(s + 660)); o[3] = cvtpk(lds_ld<float>(s + 792), lds_ld<float>(s + 924));
;         *(u32x4*)(WT + (size_t)(r0 + n) * K + k0 + 8 * c) = o; }
	ds_write_b32 v33, v0
	v_add_u32_e32 v0, s14, v52
	ds_write_b32 v0, v108
	v_add_u32_e32 v0, s14, v53
	ds_write_b32 v0, v109
	v_add_u32_e32 v0, s14, v54
	ds_write_b32 v0, v110
	v_add_u32_e32 v0, s14, v55
	ds_write_b32 v0, v111
	v_add_u32_e32 v0, s14, v56
	ds_write_b32 v0, v112
	v_add_u32_e32 v0, s14, v57
	ds_write_b32 v0, v113
	v_add_u32_e32 v0, s14, v58
	ds_write_b32 v0, v114
	v_add_u32_e32 v0, s14, v59
	ds_write_b32 v0, v115
	v_add_u32_e32 v0, s14, v60
	ds_write_b32 v0, v116
	v_add_u32_e32 v0, s14, v61
	ds_write_b32 v0, v117
	v_add_u32_e32 v0, s14, v62
	ds_write_b32 v0, v118
	v_add_u32_e32 v0, s14, v63
	ds_write_b32 v0, v119
	v_add_u32_e32 v0, s14, v64
	ds_write_b32 v0, v120
	v_add_u32_e32 v0, s14, v65
	ds_write_b32 v0, v121
	v_add_u32_e32 v0, s14, v66
	ds_write_b32 v0, v122
	v_add_u32_e32 v0, s14, v67
	ds_write_b32 v0, v123
	v_add_u32_e32 v0, s14, v68
	ds_write_b32 v0, v124
	v_add_u32_e32 v0, s14, v69
	ds_write_b32 v0, v125
	v_add_u32_e32 v0, s14, v70
	ds_write_b32 v0, v126
	v_add_u32_e32 v0, s14, v71
	ds_write_b32 v0, v127
	v_add_u32_e32 v0, s14, v72
	ds_write_b32 v0, v44
	v_add_u32_e32 v0, s14, v73
	ds_write_b32 v0, v45
	v_add_u32_e32 v0, s14, v74
	ds_write_b32 v0, v46
	v_add_u32_e32 v0, s14, v75
	ds_write_b32 v0, v47
	v_add_u32_e32 v0, s14, v76
	ds_write_b32 v0, v48
	v_add_u32_e32 v0, s14, v77
	v_lshl_add_u64 v[40:41], v[14:15], 0, s[4:5]
	ds_write_b32 v0, v34
	v_add_u32_e32 v0, s14, v78
	ds_write_b32 v0, v35
	v_add_u32_e32 v0, s14, v79
	ds_write_b32 v0, v36
	v_add_u32_e32 v0, s14, v80
	ds_write_b32 v0, v37
	v_add_u32_e32 v0, s14, v81
	ds_write_b32 v0, v38
	v_add_u32_e32 v0, s14, v82
	ds_write_b32 v0, v32
	s_waitcnt lgkmcnt(0)
	v_add_u32_e32 v0, s14, v84
	ds_read2_b32 v[32:33], v0 offset1:33
	ds_read2_b32 v[34:35], v0 offset0:66 offset1:99
	ds_read2_b32 v[36:37], v0 offset0:132 offset1:165
	ds_read2_b32 v[38:39], v0 offset0:198 offset1:231
	v_or_b32_e32 v0, s2, v83
	v_lshlrev_b32_e32 v0, 9, v0
	s_waitcnt lgkmcnt(3)
	v_cvt_pk_bf16_f32 v32, v32, v33
	s_waitcnt lgkmcnt(2)
	v_cvt_pk_bf16_f32 v33, v34, v35
	s_waitcnt lgkmcnt(1)
	v_cvt_pk_bf16_f32 v34, v36, v37
	v_lshl_add_u64 v[36:37], v[40:41], 0, v[0:1]
	v_add_u32_e32 v0, s14, v86
	s_waitcnt lgkmcnt(0)
	v_cvt_pk_bf16_f32 v35, v38, v39
	ds_read2_b32 v[38:39], v0 offset1:33
	ds_read2_b32 v[42:43], v0 offset0:66 offset1:99
	ds_read2_b32 v[44:45], v0 offset0:132 offset1:165
	ds_read2_b32 v[46:47], v0 offset0:198 offset1:231
	v_or_b32_e32 v0, s2, v85
	v_lshlrev_b32_e32 v0, 9, v0
	global_store_dwordx4 v[36:37], v[32:35], off nt
	v_lshl_add_u64 v[36:37], v[40:41], 0, v[0:1]
	v_add_u32_e32 v0, s14, v88
	s_waitcnt lgkmcnt(3)
	v_cvt_pk_bf16_f32 v32, v38, v39
	s_waitcnt lgkmcnt(2)
	v_cvt_pk_bf16_f32 v33, v42, v43
	s_waitcnt lgkmcnt(1)
	v_cvt_pk_bf16_f32 v34, v44, v45
	s_waitcnt lgkmcnt(0)
	v_cvt_pk_bf16_f32 v35, v46, v47
	ds_read2_b32 v[38:39], v0 offset1:33
	ds_read2_b32 v[42:43], v0 offset0:66 offset1:99
	ds_read2_b32 v[44:45], v0 offset0:132 offset1:165
	ds_read2_b32 v[46:47], v0 offset0:198 offset1:231
	v_or_b32_e32 v0, s2, v87
	v_lshlrev_b32_e32 v0, 9, v0
	global_store_dwordx4 v[36:37], v[32:35], off nt
	v_lshl_add_u64 v[36:37], v[40:41], 0, v[0:1]
	v_add_u32_e32 v0, s14, v90
	s_waitcnt lgkmcnt(3)
	v_cvt_pk_bf16_f32 v32, v38, v39
	s_waitcnt lgkmcnt(2)
	v_cvt_pk_bf16_f32 v33, v42, v43
	s_waitcnt lgkmcnt(1)
	v_cvt_pk_bf16_f32 v34, v44, v45
	s_waitcnt lgkmcnt(0)
	v_cvt_pk_bf16_f32 v35, v46, v47
	ds_read2_b32 v[38:39], v0 offset1:33
	ds_read2_b32 v[42:43], v0 offset0:66 offset1:99
	ds_read2_b32 v[44:45], v0 offset0:132 offset1:165
	ds_read2_b32 v[46:47], v0 offset0:198 offset1:231
	v_or_b32_e32 v0, s2, v89
	v_lshlrev_b32_e32 v0, 9, v0
	global_store_dwordx4 v[36:37], v[32:35], off nt
	v_lshl_add_u64 v[36:37], v[40:41], 0, v[0:1]
	s_waitcnt lgkmcnt(3)
	v_cvt_pk_bf16_f32 v32, v38, v39
	s_waitcnt lgkmcnt(2)
	v_cvt_pk_bf16_f32 v33, v42, v43
	s_waitcnt lgkmcnt(1)
	v_cvt_pk_bf16_f32 v34, v44, v45
	s_waitcnt lgkmcnt(0)
	v_cvt_pk_bf16_f32 v35, v46, v47
	global_store_dwordx4 v[36:37], v[32:35], off nt
	s_waitcnt lgkmcnt(0)

; __device__ __forceinline__ unsigned cvtpk(float lo, float hi) { f32x2_t v = {lo, hi}; bf16x2_t b = __builtin_convertvector(v, bf16x2_t); return __builtin_bit_cast(unsigned, b); }
; __device__ __forceinline__ void transpose_item(const float* __restrict__ W, int K, int N, const float* __restrict__ gain, bf16* WT, int mode, ldsp scr, int item, int lane) {
;     ...
; #pragma unroll
;     for (int i = 0; i < 32; ++i) { const int kk = 2 * i + (lane >> 5); float v = tv[i]; if (gain) v *= gain[k0 + kk]; lds_st<float>(scr + 4 * (kk * 33 + (lane & 31)), v); }
;     asm volatile("s_waitcnt lgkmcnt(0)" ::: "memory");
;     const int c = lane & 7;
; #pragma unroll
;     for (int j = 0; j < 4; ++j) { const int n = (lane >> 3) + 8 * j; ldsp s = scr + 4 * ((8 * c) * 33 + n);
;         u32x4 o; o[0] = cvtpk(lds_ld<float>(s), lds_ld<float>(s + 132)); o[1] = cvtpk(lds_ld<float>(s + 264), lds_ld<float>(s + 396));
;         o[2] = cvtpk(lds_ld<float>(s + 528), lds_ld<float>(s + 660)); o[3] = cvtpk(lds_ld<float>(s + 792), lds_ld<float>(s + 924));
;         *(u32x4*)(WT + (size_t)(r0 + n) * K + k0 + 8 * c) = o; }
.LBB0_675:
	s_waitcnt vmcnt(3)
	v_add_u32_e32 v0, s14, v81
	ds_write_b32 v0, v34
	v_add_u32_e32 v0, s14, v82
	ds_write_b32 v0, v35
	s_waitcnt lgkmcnt(0)
	v_add_u32_e32 v0, s14, v84
	s_waitcnt vmcnt(0)
	ds_read2_b32 v[32:33], v0 offset1:33
	ds_read2_b32 v[34:35], v0 offset0:66 offset1:99
	ds_read2_b32 v[36:37], v0 offset0:132 offset1:165
	ds_read2_b32 v[38:39], v0 offset0:198 offset1:231
	s_lshl_b32 s4, s56, 1
	v_or_b32_e32 v0, s55, v83
	v_lshl_add_u64 v[40:41], v[18:19], 0, s[4:5]
	v_lshlrev_b32_e32 v0, 12, v0
	s_waitcnt lgkmcnt(3)
	v_cvt_pk_bf16_f32 v32, v32, v33
	s_waitcnt lgkmcnt(2)
	v_cvt_pk_bf16_f32 v33, v34, v35
	s_waitcnt lgkmcnt(1)
	v_cvt_pk_bf16_f32 v34, v36, v37
	v_lshl_add_u64 v[36:37], v[40:41], 0, v[0:1]
	v_add_u32_e32 v0, s14, v86
	s_waitcnt lgkmcnt(0)
	v_cvt_pk_bf16_f32 v35, v38, v39
	ds_read2_b32 v[38:39], v0 offset1:33
	ds_read2_b32 v[42:43], v0 offset0:66 offset1:99
	ds_read2_b32 v[44:45], v0 offset0:132 offset1:165
	ds_read2_b32 v[46:47], v0 offset0:198 offset1:231
	v_or_b32_e32 v0, s55, v85
	v_lshlrev_b32_e32 v0, 12, v0
	global_store_dwordx4 v[36:37], v[32:35], off nt
	v_lshl_add_u64 v[36:37], v[40:41], 0, v[0:1]
	v_add_u32_e32 v0, s14, v88
	s_waitcnt lgkmcnt(3)
	v_cvt_pk_bf16_f32 v32, v38, v39
	s_waitcnt lgkmcnt(2)
	v_cvt_pk_bf16_f32 v33, v42, v43
	s_waitcnt lgkmcnt(1)
	v_cvt_pk_bf16_f32 v34, v44, v45
	s_waitcnt lgkmcnt(0)
	v_cvt_pk_bf16_f32 v35, v46, v47
	ds_read2_b32 v[38:39], v0 offset1:33
	ds_read2_b32 v[42:43], v0 offset0:66 offset1:99
	ds_read2_b32 v[44:45], v0 offset0:132 offset1:165
	ds_read2_b32 v[46:47], v0 offset0:198 offset1:231
	v_or_b32_e32 v0, s55, v87
	v_lshlrev_b32_e32 v0, 12, v0
	global_store_dwordx4 v[36:37], v[32:35], off nt
	v_lshl_add_u64 v[36:37], v[40:41], 0, v[0:1]
	v_add_u32_e32 v0, s14, v90
	s_waitcnt lgkmcnt(3)
	v_cvt_pk_bf16_f32 v32, v38, v39
	s_waitcnt lgkmcnt(2)
	v_cvt_pk_bf16_f32 v33, v42, v43
	s_waitcnt lgkmcnt(1)
	v_cvt_pk_bf16_f32 v34, v44, v45
	s_waitcnt lgkmcnt(0)
	v_cvt_pk_bf16_f32 v35, v46, v47
	ds_read2_b32 v[38:39], v0 offset1:33
	ds_read2_b32 v[42:43], v0 offset0:66 offset1:99
	ds_read2_b32 v[44:45], v0 offset0:132 offset1:165
	ds_read2_b32 v[46:47], v0 offset0:198 offset1:231
	v_or_b32_e32 v0, s55, v89
	v_lshlrev_b32_e32 v0, 12, v0
	global_store_dwordx4 v[36:37], v[32:35], off nt
	v_lshl_add_u64 v[36:37], v[40:41], 0, v[0:1]
	s_waitcnt lgkmcnt(3)
	v_cvt_pk_bf16_f32 v32, v38, v39
	s_waitcnt lgkmcnt(2)
	v_cvt_pk_bf16_f32 v33, v42, v43
	s_waitcnt lgkmcnt(1)
	v_cvt_pk_bf16_f32 v34, v44, v45
	s_waitcnt lgkmcnt(0)
	v_cvt_pk_bf16_f32 v35, v46, v47
	global_store_dwordx4 v[36:37], v[32:35], off nt
	s_waitcnt lgkmcnt(0)

; __device__ __forceinline__ void transpose_item(const float* __restrict__ W, int K, int N, const float* __restrict__ gain, bf16* WT, int mode, ldsp scr, int item, int lane) {
;     const int nblk = N / 32, kb = item / nblk, nb = item % nblk, k0 = 64 * kb, n0 = 32 * nb;
;     int r0;
;     if (mode == 0) r0 = n0;
;     else if (mode == 3) r0 = (n0 < 2048) ? ((n0 & ~255) + ((n0 >> 5) & 1) * 128 + ((n0 >> 6) & 3) * 32) : n0;
;     else r0 = (n0 >> 7) * 256 + (mode == 2 ? 128 : 0) + (n0 & 127);
;     float tv[32];
; #pragma unroll
;     for (int i = 0; i < 32; ++i) tv[i] = __builtin_nontemporal_load(&W[(size_t)(k0 + 2 * i + (lane >> 5)) * N + n0 + (lane & 31)]);
.LBB0_677:
	s_andn2_b64 vcc, exec, s[2:3]
	s_cbranch_vccnz .LBB0_679
	s_add_i32 s2, s12, 0xf800
	s_and_b32 s3, s2, 0xffc0
	s_and_b32 s2, s15, 0x7e0
	v_or_b32_e32 v0, s3, v50
	s_lshl_b32 s4, s2, 2
	v_lshl_add_u64 v[32:33], v[20:21], 0, s[4:5]
	v_lshlrev_b32_e32 v0, 13, v0
	v_lshl_add_u64 v[32:33], v[32:33], 0, v[0:1]
	v_add_co_u32_e32 v34, vcc, 0x4000, v32
	s_lshl_b32 s4, s3, 1
	s_nop 0
	v_addc_co_u32_e32 v35, vcc, 0, v33, vcc
	v_add_co_u32_e32 v36, vcc, 0x8000, v32
	s_nop 1
	v_addc_co_u32_e32 v37, vcc, 0, v33, vcc
	v_add_co_u32_e32 v38, vcc, 0xc000, v32
	s_nop 1
	v_addc_co_u32_e32 v39, vcc, 0, v33, vcc
	v_add_co_u32_e32 v40, vcc, 0x10000, v32
	s_nop 1
	v_addc_co_u32_e32 v41, vcc, 0, v33, vcc
	v_add_co_u32_e32 v42, vcc, 0x14000, v32
	s_nop 1
	v_addc_co_u32_e32 v43, vcc, 0, v33, vcc
	v_add_co_u32_e32 v44, vcc, 0x18000, v32
	s_nop 1
	v_addc_co_u32_e32 v45, vcc, 0, v33, vcc
	v_add_co_u32_e32 v46, vcc, 0x1c000, v32
	s_nop 1
	v_addc_co_u32_e32 v47, vcc, 0, v33, vcc
	global_load_dword v0, v[32:33], off nt
	global_load_dword v108, v[34:35], off nt
	global_load_dword v109, v[36:37], off nt
	global_load_dword v110, v[38:39], off nt
	global_load_dword v111, v[40:41], off nt
	global_load_dword v112, v[42:43], off nt
	global_load_dword v113, v[44:45], off nt
	global_load_dword v114, v[46:47], off nt
	v_add_co_u32_e32 v34, vcc, 0x20000, v32
	s_nop 1
	v_addc_co_u32_e32 v35, vcc, 0, v33, vcc
	v_add_co_u32_e32 v36, vcc, 0x24000, v32
	s_nop 1
	v_addc_co_u32_e32 v37, vcc, 0, v33, vcc
	v_add_co_u32_e32 v38, vcc, 0x28000, v32
	s_nop 1
	v_addc_co_u32_e32 v39, vcc, 0, v33, vcc
	v_add_co_u32_e32 v40, vcc, 0x2c000, v32
	s_nop 1
	v_addc_co_u32_e32 v41, vcc, 0, v33, vcc
	v_add_co_u32_e32 v42, vcc, 0x30000, v32
	s_nop 1
	v_addc_co_u32_e32 v43, vcc, 0, v33, vcc
	v_add_co_u32_e32 v44, vcc, 0x34000, v32
	s_nop 1
	v_addc_co_u32_e32 v45, vcc, 0, v33, vcc
	v_add_co_u32_e32 v46, vcc, 0x38000, v32
	s_nop 1
	v_addc_co_u32_e32 v47, vcc, 0, v33, vcc
	v_add_co_u32_e32 v48, vcc, 0x3c000, v32
	s_nop 1
	v_addc_co_u32_e32 v49, vcc, 0, v33, vcc
	global_load_dword v115, v[34:35], off nt
	global_load_dword v116, v[36:37], off nt
	global_load_dword v117, v[38:39], off nt
	global_load_dword v118, v[40:41], off nt
	global_load_dword v119, v[42:43], off nt
	global_load_dword v120, v[44:45], off nt
	global_load_dword v121, v[46:47], off nt
	global_load_dword v122, v[48:49], off nt
	v_add_co_u32_e32 v34, vcc, 0x40000, v32
	s_nop 1
	v_addc_co_u32_e32 v35, vcc, 0, v33, vcc
	v_add_co_u32_e32 v36, vcc, 0x44000, v32
	s_nop 1
	v_addc_co_u32_e32 v37, vcc, 0, v33, vcc
	v_add_co_u32_e32 v38, vcc, 0x48000, v32
	s_nop 1
	v_addc_co_u32_e32 v39, vcc, 0, v33, vcc
	v_add_co_u32_e32 v40, vcc, 0x4c000, v32
	s_nop 1
	v_addc_co_u32_e32 v41, vcc, 0, v33, vcc
	v_add_co_u32_e32 v42, vcc, 0x50000, v32
	s_nop 1
	v_addc_co_u32_e32 v43, vcc, 0, v33, vcc
	v_add_co_u32_e32 v44, vcc, 0x54000, v32
	s_nop 1
	v_addc_co_u32_e32 v45, vcc, 0, v33, vcc
	v_add_co_u32_e32 v46, vcc, 0x58000, v32
	s_nop 1
	v_addc_co_u32_e32 v47, vcc, 0, v33, vcc
	v_add_co_u32_e32 v48, vcc, 0x5c000, v32
	s_nop 1
	v_addc_co_u32_e32 v49, vcc, 0, v33, vcc
	global_load_dword v123, v[34:35], off nt
	global_load_dword v124, v[36:37], off nt
	global_load_dword v125, v[38:39], off nt
	global_load_dword v126, v[40:41], off nt
	global_load_dword v127, v[42:43], off nt
	s_nop 0
	global_load_dword v44, v[44:45], off nt
	s_nop 0
	global_load_dword v45, v[46:47], off nt
	s_nop 0
	global_load_dword v46, v[48:49], off nt
	v_add_co_u32_e32 v34, vcc, 0x60000, v32
	s_nop 1
	v_addc_co_u32_e32 v35, vcc, 0, v33, vcc
	v_add_co_u32_e32 v36, vcc, 0x64000, v32
	s_nop 1
	v_addc_co_u32_e32 v37, vcc, 0, v33, vcc
	global_load_dword v47, v[34:35], off nt
	global_load_dword v48, v[36:37], off nt
	v_add_co_u32_e32 v34, vcc, 0x68000, v32
	s_nop 1
	v_addc_co_u32_e32 v35, vcc, 0, v33, vcc
	v_add_co_u32_e32 v36, vcc, 0x6c000, v32
	s_nop 1
	v_addc_co_u32_e32 v37, vcc, 0, v33, vcc
	v_add_co_u32_e32 v38, vcc, 0x70000, v32
	s_nop 1
	v_addc_co_u32_e32 v39, vcc, 0, v33, vcc
	v_add_co_u32_e32 v40, vcc, 0x74000, v32
	s_nop 1
	v_addc_co_u32_e32 v41, vcc, 0, v33, vcc
	v_add_co_u32_e32 v42, vcc, 0x78000, v32
	s_nop 1
	v_addc_co_u32_e32 v43, vcc, 0, v33, vcc
	v_add_co_u32_e32 v32, vcc, 0x7c000, v32
	global_load_dword v34, v[34:35], off nt
	s_nop 0
	global_load_dword v35, v[36:37], off nt
	s_nop 0
	global_load_dword v36, v[38:39], off nt
	global_load_dword v37, v[40:41], off nt
	s_nop 0
	global_load_dword v38, v[42:43], off nt
	v_addc_co_u32_e32 v33, vcc, 0, v33, vcc
	global_load_dword v32, v[32:33], off nt
	v_add_u32_e32 v33, s14, v51
	s_waitcnt vmcnt(0)
; __device__ __forceinline__ unsigned cvtpk(float lo, float hi) { f32x2_t v = {lo, hi}; bf16x2_t b = __builtin_convertvector(v, bf16x2_t); return __builtin_bit_cast(unsigned, b); }
; __device__ __forceinline__ void transpose_item(const float* __restrict__ W, int K, int N, const float* __restrict__ gain, bf16* WT, int mode, ldsp scr, int item, int lane) {
;     ...
; #pragma unroll
;     for (int i = 0; i < 32; ++i) { const int kk = 2 * i + (lane >> 5); float v = tv[i]; if (gain) v *= gain[k0 + kk]; lds_st<float>(scr + 4 * (kk * 33 + (lane & 31)), v); }
;     asm volatile("s_waitcnt lgkmcnt(0)" ::: "memory");
;     const int c = lane & 7;
; #pragma unroll
;     for (int j = 0; j < 4; ++j) { const int n = (lane >> 3) + 8 * j; ldsp s = scr + 4 * ((8 * c) * 33 + n);
;         u32x4 o; o[0] = cvtpk(lds_ld<float>(s), lds_ld<float>(s + 132)); o[1] = cvtpk(lds_ld<float>(s + 264), lds_ld<float>(s + 396));
;         o[2] = cvtpk(lds_ld<float>(s + 528), lds_ld<float>(s + 660)); o[3] = cvtpk(lds_ld<float>(s + 792), lds_ld<float>(s + 924));
;         *(u32x4*)(WT + (size_t)(r0 + n) * K + k0 + 8 * c) = o; }
	ds_write_b32 v33, v0
	v_add_u32_e32 v0, s14, v52
	ds_write_b32 v0, v108
	v_add_u32_e32 v0, s14, v53
	ds_write_b32 v0, v109
	v_add_u32_e32 v0, s14, v54
	ds_write_b32 v0, v110
	v_add_u32_e32 v0, s14, v55
	ds_write_b32 v0, v111
	v_add_u32_e32 v0, s14, v56
	ds_write_b32 v0, v112
	v_add_u32_e32 v0, s14, v57
	ds_write_b32 v0, v113
	v_add_u32_e32 v0, s14, v58
	ds_write_b32 v0, v114
	v_add_u32_e32 v0, s14, v59
	ds_write_b32 v0, v115
	v_add_u32_e32 v0, s14, v60
	ds_write_b32 v0, v116
	v_add_u32_e32 v0, s14, v61
	ds_write_b32 v0, v117
	v_add_u32_e32 v0, s14, v62
	ds_write_b32 v0, v118
	v_add_u32_e32 v0, s14, v63
	ds_write_b32 v0, v119
	v_add_u32_e32 v0, s14, v64
	ds_write_b32 v0, v120
	v_add_u32_e32 v0, s14, v65
	ds_write_b32 v0, v121
	v_add_u32_e32 v0, s14, v66
	ds_write_b32 v0, v122
	v_add_u32_e32 v0, s14, v67
	ds_write_b32 v0, v123
	v_add_u32_e32 v0, s14, v68
	ds_write_b32 v0, v124
	v_add_u32_e32 v0, s14, v69
	ds_write_b32 v0, v125
	v_add_u32_e32 v0, s14, v70
	ds_write_b32 v0, v126
	v_add_u32_e32 v0, s14, v71
	ds_write_b32 v0, v127
	v_add_u32_e32 v0, s14, v72
	ds_write_b32 v0, v44
	v_add_u32_e32 v0, s14, v73
	ds_write_b32 v0, v45
	v_add_u32_e32 v0, s14, v74
	ds_write_b32 v0, v46
	v_add_u32_e32 v0, s14, v75
	ds_write_b32 v0, v47
	v_add_u32_e32 v0, s14, v76
	ds_write_b32 v0, v48
	v_add_u32_e32 v0, s14, v77
	v_lshl_add_u64 v[40:41], v[22:23], 0, s[4:5]
	ds_write_b32 v0, v34
	v_add_u32_e32 v0, s14, v78
	ds_write_b32 v0, v35
	v_add_u32_e32 v0, s14, v79
	ds_write_b32 v0, v36
	v_add_u32_e32 v0, s14, v80
	ds_write_b32 v0, v37
	v_add_u32_e32 v0, s14, v81
	ds_write_b32 v0, v38
	v_add_u32_e32 v0, s14, v82
	ds_write_b32 v0, v32
	s_waitcnt lgkmcnt(0)
	v_add_u32_e32 v0, s14, v84
	ds_read2_b32 v[32:33], v0 offset1:33
	ds_read2_b32 v[34:35], v0 offset0:66 offset1:99
	ds_read2_b32 v[36:37], v0 offset0:132 offset1:165
	ds_read2_b32 v[38:39], v0 offset0:198 offset1:231
	v_or_b32_e32 v0, s2, v83
	v_lshlrev_b32_e32 v0, 12, v0
	s_waitcnt lgkmcnt(3)
	v_cvt_pk_bf16_f32 v32, v32, v33
	s_waitcnt lgkmcnt(2)
	v_cvt_pk_bf16_f32 v33, v34, v35
	s_waitcnt lgkmcnt(1)
	v_cvt_pk_bf16_f32 v34, v36, v37
	v_lshl_add_u64 v[36:37], v[40:41], 0, v[0:1]
	v_add_u32_e32 v0, s14, v86
	s_waitcnt lgkmcnt(0)
	v_cvt_pk_bf16_f32 v35, v38, v39
	ds_read2_b32 v[38:39], v0 offset1:33
	ds_read2_b32 v[42:43], v0 offset0:66 offset1:99
	ds_read2_b32 v[44:45], v0 offset0:132 offset1:165
	ds_read2_b32 v[46:47], v0 offset0:198 offset1:231
	v_or_b32_e32 v0, s2, v85
	v_lshlrev_b32_e32 v0, 12, v0
	global_store_dwordx4 v[36:37], v[32:35], off nt
	v_lshl_add_u64 v[36:37], v[40:41], 0, v[0:1]
	v_add_u32_e32 v0, s14, v88
	s_waitcnt lgkmcnt(3)
	v_cvt_pk_bf16_f32 v32, v38, v39
	s_waitcnt lgkmcnt(2)
	v_cvt_pk_bf16_f32 v33, v42, v43
	s_waitcnt lgkmcnt(1)
	v_cvt_pk_bf16_f32 v34, v44, v45
	s_waitcnt lgkmcnt(0)
	v_cvt_pk_bf16_f32 v35, v46, v47
	ds_read2_b32 v[38:39], v0 offset1:33
	ds_read2_b32 v[42:43], v0 offset0:66 offset1:99
	ds_read2_b32 v[44:45], v0 offset0:132 offset1:165
	ds_read2_b32 v[46:47], v0 offset0:198 offset1:231
	v_or_b32_e32 v0, s2, v87
	v_lshlrev_b32_e32 v0, 12, v0
	global_store_dwordx4 v[36:37], v[32:35], off nt
	v_lshl_add_u64 v[36:37], v[40:41], 0, v[0:1]
	v_add_u32_e32 v0, s14, v90
	s_waitcnt lgkmcnt(3)
	v_cvt_pk_bf16_f32 v32, v38, v39
	s_waitcnt lgkmcnt(2)
	v_cvt_pk_bf16_f32 v33, v42, v43
	s_waitcnt lgkmcnt(1)
	v_cvt_pk_bf16_f32 v34, v44, v45
	s_waitcnt lgkmcnt(0)
	v_cvt_pk_bf16_f32 v35, v46, v47
	ds_read2_b32 v[38:39], v0 offset1:33
	ds_read2_b32 v[42:43], v0 offset0:66 offset1:99
	ds_read2_b32 v[44:45], v0 offset0:132 offset1:165
	ds_read2_b32 v[46:47], v0 offset0:198 offset1:231
	v_or_b32_e32 v0, s2, v89
	v_lshlrev_b32_e32 v0, 12, v0
	global_store_dwordx4 v[36:37], v[32:35], off nt
	v_lshl_add_u64 v[36:37], v[40:41], 0, v[0:1]
	s_waitcnt lgkmcnt(3)
	v_cvt_pk_bf16_f32 v32, v38, v39
	s_waitcnt lgkmcnt(2)
	v_cvt_pk_bf16_f32 v33, v42, v43
	s_waitcnt lgkmcnt(1)
	v_cvt_pk_bf16_f32 v34, v44, v45
	s_waitcnt lgkmcnt(0)
	v_cvt_pk_bf16_f32 v35, v46, v47
	global_store_dwordx4 v[36:37], v[32:35], off nt
	s_waitcnt lgkmcnt(0)

; __device__ __forceinline__ void transpose_item(const float* __restrict__ W, int K, int N, const float* __restrict__ gain, bf16* WT, int mode, ldsp scr, int item, int lane) {
;     const int nblk = N / 32, kb = item / nblk, nb = item % nblk, k0 = 64 * kb, n0 = 32 * nb;
;     int r0;
;     if (mode == 0) r0 = n0;
;     else if (mode == 3) r0 = (n0 < 2048) ? ((n0 & ~255) + ((n0 >> 5) & 1) * 128 + ((n0 >> 6) & 3) * 32) : n0;
;     else r0 = (n0 >> 7) * 256 + (mode == 2 ? 128 : 0) + (n0 & 127);
;     float tv[32];
; #pragma unroll
;     for (int i = 0; i < 32; ++i) tv[i] = __builtin_nontemporal_load(&W[(size_t)(k0 + 2 * i + (lane >> 5)) * N + n0 + (lane & 31)]);
.LBB0_680:
	s_andn2_b64 vcc, exec, s[2:3]
	s_cbranch_vccnz .LBB0_682
	s_add_i32 s2, s12, 0xfc00
	s_and_b32 s3, s2, 0xffc0
	s_and_b32 s2, s15, 0x7e0
	v_or_b32_e32 v0, s3, v50
	s_lshl_b32 s4, s2, 2
	v_lshl_add_u64 v[32:33], v[24:25], 0, s[4:5]
	v_lshlrev_b32_e32 v0, 13, v0
	v_lshl_add_u64 v[32:33], v[32:33], 0, v[0:1]
	v_add_co_u32_e32 v34, vcc, 0x4000, v32
	s_lshl_b32 s4, s3, 1
	s_nop 0
	v_addc_co_u32_e32 v35, vcc, 0, v33, vcc
	v_add_co_u32_e32 v36, vcc, 0x8000, v32
	s_nop 1
	v_addc_co_u32_e32 v37, vcc, 0, v33, vcc
	v_add_co_u32_e32 v38, vcc, 0xc000, v32
	s_nop 1
	v_addc_co_u32_e32 v39, vcc, 0, v33, vcc
	v_add_co_u32_e32 v40, vcc, 0x10000, v32
	s_nop 1
	v_addc_co_u32_e32 v41, vcc, 0, v33, vcc
	v_add_co_u32_e32 v42, vcc, 0x14000, v32
	s_nop 1
	v_addc_co_u32_e32 v43, vcc, 0, v33, vcc
	v_add_co_u32_e32 v44, vcc, 0x18000, v32
	s_nop 1
	v_addc_co_u32_e32 v45, vcc, 0, v33, vcc
	v_add_co_u32_e32 v46, vcc, 0x1c000, v32
	s_nop 1
	v_addc_co_u32_e32 v47, vcc, 0, v33, vcc
	global_load_dword v0, v[32:33], off nt
	global_load_dword v108, v[34:35], off nt
	global_load_dword v109, v[36:37], off nt
	global_load_dword v110, v[38:39], off nt
	global_load_dword v111, v[40:41], off nt
	global_load_dword v112, v[42:43], off nt
	global_load_dword v113, v[44:45], off nt
	global_load_dword v114, v[46:47], off nt
	v_add_co_u32_e32 v34, vcc, 0x20000, v32
	s_nop 1
	v_addc_co_u32_e32 v35, vcc, 0, v33, vcc
	v_add_co_u32_e32 v36, vcc, 0x24000, v32
	s_nop 1
	v_addc_co_u32_e32 v37, vcc, 0, v33, vcc
	v_add_co_u32_e32 v38, vcc, 0x28000, v32
	s_nop 1
	v_addc_co_u32_e32 v39, vcc, 0, v33, vcc
	v_add_co_u32_e32 v40, vcc, 0x2c000, v32
	s_nop 1
	v_addc_co_u32_e32 v41, vcc, 0, v33, vcc
	v_add_co_u32_e32 v42, vcc, 0x30000, v32
	s_nop 1
	v_addc_co_u32_e32 v43, vcc, 0, v33, vcc
	v_add_co_u32_e32 v44, vcc, 0x34000, v32
	s_nop 1
	v_addc_co_u32_e32 v45, vcc, 0, v33, vcc
	v_add_co_u32_e32 v46, vcc, 0x38000, v32
	s_nop 1
	v_addc_co_u32_e32 v47, vcc, 0, v33, vcc
	v_add_co_u32_e32 v48, vcc, 0x3c000, v32
	s_nop 1
	v_addc_co_u32_e32 v49, vcc, 0, v33, vcc
	global_load_dword v115, v[34:35], off nt
	global_load_dword v116, v[36:37], off nt
	global_load_dword v117, v[38:39], off nt
	global_load_dword v118, v[40:41], off nt
	global_load_dword v119, v[42:43], off nt
	global_load_dword v120, v[44:45], off nt
	global_load_dword v121, v[46:47], off nt
	global_load_dword v122, v[48:49], off nt
	v_add_co_u32_e32 v34, vcc, 0x40000, v32
	s_nop 1
	v_addc_co_u32_e32 v35, vcc, 0, v33, vcc
	v_add_co_u32_e32 v36, vcc, 0x44000, v32
	s_nop 1
	v_addc_co_u32_e32 v37, vcc, 0, v33, vcc
	v_add_co_u32_e32 v38, vcc, 0x48000, v32
	s_nop 1
	v_addc_co_u32_e32 v39, vcc, 0, v33, vcc
	v_add_co_u32_e32 v40, vcc, 0x4c000, v32
	s_nop 1
	v_addc_co_u32_e32 v41, vcc, 0, v33, vcc
	v_add_co_u32_e32 v42, vcc, 0x50000, v32
	s_nop 1
	v_addc_co_u32_e32 v43, vcc, 0, v33, vcc
	v_add_co_u32_e32 v44, vcc, 0x54000, v32
	s_nop 1
	v_addc_co_u32_e32 v45, vcc, 0, v33, vcc
	v_add_co_u32_e32 v46, vcc, 0x58000, v32
	s_nop 1
	v_addc_co_u32_e32 v47, vcc, 0, v33, vcc
	v_add_co_u32_e32 v48, vcc, 0x5c000, v32
	s_nop 1
	v_addc_co_u32_e32 v49, vcc, 0, v33, vcc
	global_load_dword v123, v[34:35], off nt
	global_load_dword v124, v[36:37], off nt
	global_load_dword v125, v[38:39], off nt
	global_load_dword v126, v[40:41], off nt
	global_load_dword v127, v[42:43], off nt
	s_nop 0
	global_load_dword v44, v[44:45], off nt
	s_nop 0
	global_load_dword v45, v[46:47], off nt
	s_nop 0
	global_load_dword v46, v[48:49], off nt
	v_add_co_u32_e32 v34, vcc, 0x60000, v32
	s_nop 1
	v_addc_co_u32_e32 v35, vcc, 0, v33, vcc
	v_add_co_u32_e32 v36, vcc, 0x64000, v32
	s_nop 1
	v_addc_co_u32_e32 v37, vcc, 0, v33, vcc
	global_load_dword v47, v[34:35], off nt
	global_load_dword v48, v[36:37], off nt
	v_add_co_u32_e32 v34, vcc, 0x68000, v32
	s_nop 1
	v_addc_co_u32_e32 v35, vcc, 0, v33, vcc
	v_add_co_u32_e32 v36, vcc, 0x6c000, v32
	s_nop 1
	v_addc_co_u32_e32 v37, vcc, 0, v33, vcc
	v_add_co_u32_e32 v38, vcc, 0x70000, v32
	s_nop 1
	v_addc_co_u32_e32 v39, vcc, 0, v33, vcc
	v_add_co_u32_e32 v40, vcc, 0x74000, v32
	s_nop 1
	v_addc_co_u32_e32 v41, vcc, 0, v33, vcc
	v_add_co_u32_e32 v42, vcc, 0x78000, v32
	s_nop 1
	v_addc_co_u32_e32 v43, vcc, 0, v33, vcc
	v_add_co_u32_e32 v32, vcc, 0x7c000, v32
	global_load_dword v34, v[34:35], off nt
	s_nop 0
	global_load_dword v35, v[36:37], off nt
	s_nop 0
	global_load_dword v36, v[38:39], off nt
	global_load_dword v37, v[40:41], off nt
	s_nop 0
	global_load_dword v38, v[42:43], off nt
	v_addc_co_u32_e32 v33, vcc, 0, v33, vcc
	global_load_dword v32, v[32:33], off nt
	v_add_u32_e32 v33, s14, v51
	s_waitcnt vmcnt(0)
; __device__ __forceinline__ unsigned cvtpk(float lo, float hi) { f32x2_t v = {lo, hi}; bf16x2_t b = __builtin_convertvector(v, bf16x2_t); return __builtin_bit_cast(unsigned, b); }
; __device__ __forceinline__ void transpose_item(const float* __restrict__ W, int K, int N, const float* __restrict__ gain, bf16* WT, int mode, ldsp scr, int item, int lane) {
;     ...
; #pragma unroll
;     for (int i = 0; i < 32; ++i) { const int kk = 2 * i + (lane >> 5); float v = tv[i]; if (gain) v *= gain[k0 + kk]; lds_st<float>(scr + 4 * (kk * 33 + (lane & 31)), v); }
;     asm volatile("s_waitcnt lgkmcnt(0)" ::: "memory");
;     const int c = lane & 7;
; #pragma unroll
;     for (int j = 0; j < 4; ++j) { const int n = (lane >> 3) + 8 * j; ldsp s = scr + 4 * ((8 * c) * 33 + n);
;         u32x4 o; o[0] = cvtpk(lds_ld<float>(s), lds_ld<float>(s + 132)); o[1] = cvtpk(lds_ld<float>(s + 264), lds_ld<float>(s + 396));
;         o[2] = cvtpk(lds_ld<float>(s + 528), lds_ld<float>(s + 660)); o[3] = cvtpk(lds_ld<float>(s + 792), lds_ld<float>(s + 924));
;         *(u32x4*)(WT + (size_t)(r0 + n) * K + k0 + 8 * c) = o; }
	ds_write_b32 v33, v0
	v_add_u32_e32 v0, s14, v52
	ds_write_b32 v0, v108
	v_add_u32_e32 v0, s14, v53
	ds_write_b32 v0, v109
	v_add_u32_e32 v0, s14, v54
	ds_write_b32 v0, v110
	v_add_u32_e32 v0, s14, v55
	ds_write_b32 v0, v111
	v_add_u32_e32 v0, s14, v56
	ds_write_b32 v0, v112
	v_add_u32_e32 v0, s14, v57
	ds_write_b32 v0, v113
	v_add_u32_e32 v0, s14, v58
	ds_write_b32 v0, v114
	v_add_u32_e32 v0, s14, v59
	ds_write_b32 v0, v115
	v_add_u32_e32 v0, s14, v60
	ds_write_b32 v0, v116
	v_add_u32_e32 v0, s14, v61
	ds_write_b32 v0, v117
	v_add_u32_e32 v0, s14, v62
	ds_write_b32 v0, v118
	v_add_u32_e32 v0, s14, v63
	ds_write_b32 v0, v119
	v_add_u32_e32 v0, s14, v64
	ds_write_b32 v0, v120
	v_add_u32_e32 v0, s14, v65
	ds_write_b32 v0, v121
	v_add_u32_e32 v0, s14, v66
	ds_write_b32 v0, v122
	v_add_u32_e32 v0, s14, v67
	ds_write_b32 v0, v123
	v_add_u32_e32 v0, s14, v68
	ds_write_b32 v0, v124
	v_add_u32_e32 v0, s14, v69
	ds_write_b32 v0, v125
	v_add_u32_e32 v0, s14, v70
	ds_write_b32 v0, v126
	v_add_u32_e32 v0, s14, v71
	ds_write_b32 v0, v127
	v_add_u32_e32 v0, s14, v72
	ds_write_b32 v0, v44
	v_add_u32_e32 v0, s14, v73
	ds_write_b32 v0, v45
	v_add_u32_e32 v0, s14, v74
	ds_write_b32 v0, v46
	v_add_u32_e32 v0, s14, v75
	ds_write_b32 v0, v47
	v_add_u32_e32 v0, s14, v76
	ds_write_b32 v0, v48
	v_add_u32_e32 v0, s14, v77
	v_lshl_add_u64 v[40:41], v[26:27], 0, s[4:5]
	ds_write_b32 v0, v34
	v_add_u32_e32 v0, s14, v78
	ds_write_b32 v0, v35
	v_add_u32_e32 v0, s14, v79
	ds_write_b32 v0, v36
	v_add_u32_e32 v0, s14, v80
	ds_write_b32 v0, v37
	v_add_u32_e32 v0, s14, v81
	ds_write_b32 v0, v38
	v_add_u32_e32 v0, s14, v82
	ds_write_b32 v0, v32
	s_waitcnt lgkmcnt(0)
	v_add_u32_e32 v0, s14, v84
	ds_read2_b32 v[32:33], v0 offset1:33
	ds_read2_b32 v[34:35], v0 offset0:66 offset1:99
	ds_read2_b32 v[36:37], v0 offset0:132 offset1:165
	ds_read2_b32 v[38:39], v0 offset0:198 offset1:231
	v_or_b32_e32 v0, s2, v83
	v_lshlrev_b32_e32 v0, 11, v0
	s_waitcnt lgkmcnt(3)
	v_cvt_pk_bf16_f32 v32, v32, v33
	s_waitcnt lgkmcnt(2)
	v_cvt_pk_bf16_f32 v33, v34, v35
	s_waitcnt lgkmcnt(1)
	v_cvt_pk_bf16_f32 v34, v36, v37
	v_lshl_add_u64 v[36:37], v[40:41], 0, v[0:1]
	v_add_u32_e32 v0, s14, v86
	s_waitcnt lgkmcnt(0)
	v_cvt_pk_bf16_f32 v35, v38, v39
	ds_read2_b32 v[38:39], v0 offset1:33
	ds_read2_b32 v[42:43], v0 offset0:66 offset1:99
	ds_read2_b32 v[44:45], v0 offset0:132 offset1:165
	ds_read2_b32 v[46:47], v0 offset0:198 offset1:231
	v_or_b32_e32 v0, s2, v85
	v_lshlrev_b32_e32 v0, 11, v0
	global_store_dwordx4 v[36:37], v[32:35], off nt
	v_lshl_add_u64 v[36:37], v[40:41], 0, v[0:1]
	v_add_u32_e32 v0, s14, v88
	s_waitcnt lgkmcnt(3)
	v_cvt_pk_bf16_f32 v32, v38, v39
	s_waitcnt lgkmcnt(2)
	v_cvt_pk_bf16_f32 v33, v42, v43
	s_waitcnt lgkmcnt(1)
	v_cvt_pk_bf16_f32 v34, v44, v45
	s_waitcnt lgkmcnt(0)
	v_cvt_pk_bf16_f32 v35, v46, v47
	ds_read2_b32 v[38:39], v0 offset1:33
	ds_read2_b32 v[42:43], v0 offset0:66 offset1:99
	ds_read2_b32 v[44:45], v0 offset0:132 offset1:165
	ds_read2_b32 v[46:47], v0 offset0:198 offset1:231
	v_or_b32_e32 v0, s2, v87
	v_lshlrev_b32_e32 v0, 11, v0
	global_store_dwordx4 v[36:37], v[32:35], off nt
	v_lshl_add_u64 v[36:37], v[40:41], 0, v[0:1]
	v_add_u32_e32 v0, s14, v90
	s_waitcnt lgkmcnt(3)
	v_cvt_pk_bf16_f32 v32, v38, v39
	s_waitcnt lgkmcnt(2)
	v_cvt_pk_bf16_f32 v33, v42, v43
	s_waitcnt lgkmcnt(1)
	v_cvt_pk_bf16_f32 v34, v44, v45
	s_waitcnt lgkmcnt(0)
	v_cvt_pk_bf16_f32 v35, v46, v47
	ds_read2_b32 v[38:39], v0 offset1:33
	ds_read2_b32 v[42:43], v0 offset0:66 offset1:99
	ds_read2_b32 v[44:45], v0 offset0:132 offset1:165
	ds_read2_b32 v[46:47], v0 offset0:198 offset1:231
	v_or_b32_e32 v0, s2, v89
	v_lshlrev_b32_e32 v0, 11, v0
	global_store_dwordx4 v[36:37], v[32:35], off nt
	v_lshl_add_u64 v[36:37], v[40:41], 0, v[0:1]
	s_waitcnt lgkmcnt(3)
	v_cvt_pk_bf16_f32 v32, v38, v39
	s_waitcnt lgkmcnt(2)
	v_cvt_pk_bf16_f32 v33, v42, v43
	s_waitcnt lgkmcnt(1)
	v_cvt_pk_bf16_f32 v34, v44, v45
	s_waitcnt lgkmcnt(0)
	v_cvt_pk_bf16_f32 v35, v46, v47
	global_store_dwordx4 v[36:37], v[32:35], off nt
	s_waitcnt lgkmcnt(0)

; __device__ __forceinline__ void transpose_item(const float* __restrict__ W, int K, int N, const float* __restrict__ gain, bf16* WT, int mode, ldsp scr, int item, int lane) {
;     const int nblk = N / 32, kb = item / nblk, nb = item % nblk, k0 = 64 * kb, n0 = 32 * nb;
;     int r0;
;     if (mode == 0) r0 = n0;
;     else if (mode == 3) r0 = (n0 < 2048) ? ((n0 & ~255) + ((n0 >> 5) & 1) * 128 + ((n0 >> 6) & 3) * 32) : n0;
;     else r0 = (n0 >> 7) * 256 + (mode == 2 ? 128 : 0) + (n0 & 127);
;     float tv[32];
; #pragma unroll
;     for (int i = 0; i < 32; ++i) tv[i] = __builtin_nontemporal_load(&W[(size_t)(k0 + 2 * i + (lane >> 5)) * N + n0 + (lane & 31)]);
.LBB0_683:
	s_ashr_i32 s2, s12, 31
	s_lshr_b32 s2, s2, 26
	s_add_i32 s2, s12, s2
	s_and_b32 s10, s2, 0xffffffc0
	s_lshl_b32 s2, s2, 5
	s_and_b32 s2, s2, 0xfffff800
	s_sub_i32 s2, s15, s2
	v_or_b32_e32 v32, s10, v50
	s_ashr_i32 s3, s2, 31
	v_ashrrev_i32_e32 v33, 31, v32
	v_or_b32_e32 v38, 2, v32
	v_or_b32_e32 v40, 4, v32
	v_or_b32_e32 v42, 6, v32
	v_or_b32_e32 v44, 8, v32
	v_or_b32_e32 v46, 10, v32
	v_or_b32_e32 v48, 12, v32
	v_or_b32_e32 v108, 14, v32
	v_lshl_add_u64 v[34:35], s[2:3], 2, v[28:29]
	v_lshlrev_b64 v[36:37], 13, v[32:33]
	v_ashrrev_i32_e32 v39, 31, v38
	v_ashrrev_i32_e32 v41, 31, v40
	v_ashrrev_i32_e32 v43, 31, v42
	v_ashrrev_i32_e32 v45, 31, v44
	v_ashrrev_i32_e32 v47, 31, v46
	v_ashrrev_i32_e32 v49, 31, v48
	v_ashrrev_i32_e32 v109, 31, v108
	v_lshl_add_u64 v[36:37], v[34:35], 0, v[36:37]
	v_lshlrev_b64 v[38:39], 13, v[38:39]
	v_lshlrev_b64 v[40:41], 13, v[40:41]
	v_lshlrev_b64 v[42:43], 13, v[42:43]
	v_lshlrev_b64 v[44:45], 13, v[44:45]
	v_lshlrev_b64 v[46:47], 13, v[46:47]
	v_lshlrev_b64 v[48:49], 13, v[48:49]
	v_lshlrev_b64 v[108:109], 13, v[108:109]
	v_lshl_add_u64 v[38:39], v[34:35], 0, v[38:39]
	v_lshl_add_u64 v[40:41], v[34:35], 0, v[40:41]
	v_lshl_add_u64 v[42:43], v[34:35], 0, v[42:43]
	v_lshl_add_u64 v[44:45], v[34:35], 0, v[44:45]
	v_lshl_add_u64 v[46:47], v[34:35], 0, v[46:47]
	v_lshl_add_u64 v[48:49], v[34:35], 0, v[48:49]
	v_lshl_add_u64 v[108:109], v[34:35], 0, v[108:109]
	global_load_dword v0, v[36:37], off nt
	global_load_dword v110, v[38:39], off nt
	global_load_dword v111, v[40:41], off nt
	global_load_dword v112, v[42:43], off nt
	global_load_dword v113, v[44:45], off nt
	global_load_dword v114, v[46:47], off nt
	global_load_dword v115, v[48:49], off nt
	global_load_dword v116, v[108:109], off nt
	v_or_b32_e32 v36, 16, v32
	v_ashrrev_i32_e32 v37, 31, v36
	v_or_b32_e32 v38, 18, v32
	v_or_b32_e32 v40, 20, v32
	v_or_b32_e32 v42, 22, v32
	v_or_b32_e32 v44, 24, v32
	v_or_b32_e32 v46, 26, v32
	v_or_b32_e32 v48, 28, v32
	v_or_b32_e32 v108, 30, v32
	v_lshlrev_b64 v[36:37], 13, v[36:37]
	v_ashrrev_i32_e32 v39, 31, v38
	v_ashrrev_i32_e32 v41, 31, v40
	v_ashrrev_i32_e32 v43, 31, v42
	v_ashrrev_i32_e32 v45, 31, v44
	v_ashrrev_i32_e32 v47, 31, v46
	v_ashrrev_i32_e32 v49, 31, v48
	v_ashrrev_i32_e32 v109, 31, v108
	v_lshl_add_u64 v[36:37], v[34:35], 0, v[36:37]
	v_lshlrev_b64 v[38:39], 13, v[38:39]
	v_lshlrev_b64 v[40:41], 13, v[40:41]
	v_lshlrev_b64 v[42:43], 13, v[42:43]
	v_lshlrev_b64 v[44:45], 13, v[44:45]
	v_lshlrev_b64 v[46:47], 13, v[46:47]
	v_lshlrev_b64 v[48:49], 13, v[48:49]
	v_lshlrev_b64 v[108:109], 13, v[108:109]
	v_lshl_add_u64 v[38:39], v[34:35], 0, v[38:39]
	v_lshl_add_u64 v[40:41], v[34:35], 0, v[40:41]
	v_lshl_add_u64 v[42:43], v[34:35], 0, v[42:43]
	v_lshl_add_u64 v[44:45], v[34:35], 0, v[44:45]
	v_lshl_add_u64 v[46:47], v[34:35], 0, v[46:47]
	v_lshl_add_u64 v[48:49], v[34:35], 0, v[48:49]
	v_lshl_add_u64 v[108:109], v[34:35], 0, v[108:109]
	global_load_dword v117, v[36:37], off nt
	global_load_dword v118, v[38:39], off nt
	global_load_dword v119, v[40:41], off nt
	global_load_dword v120, v[42:43], off nt
	global_load_dword v121, v[44:45], off nt
	global_load_dword v122, v[46:47], off nt
	global_load_dword v123, v[48:49], off nt
	global_load_dword v124, v[108:109], off nt
	v_or_b32_e32 v36, 32, v32
	v_or_b32_e32 v38, 34, v32
	v_or_b32_e32 v44, 40, v32
	v_or_b32_e32 v46, 42, v32
	v_ashrrev_i32_e32 v37, 31, v36
	v_ashrrev_i32_e32 v39, 31, v38
	v_or_b32_e32 v40, 36, v32
	v_or_b32_e32 v42, 38, v32
	v_ashrrev_i32_e32 v45, 31, v44
	v_ashrrev_i32_e32 v47, 31, v46
	v_or_b32_e32 v48, 44, v32
	v_or_b32_e32 v108, 46, v32
	v_lshlrev_b64 v[36:37], 13, v[36:37]
	v_lshlrev_b64 v[38:39], 13, v[38:39]
	v_ashrrev_i32_e32 v41, 31, v40
	v_ashrrev_i32_e32 v43, 31, v42
	v_lshlrev_b64 v[44:45], 13, v[44:45]
	v_lshlrev_b64 v[46:47], 13, v[46:47]
	v_ashrrev_i32_e32 v49, 31, v48
	v_ashrrev_i32_e32 v109, 31, v108
	v_lshl_add_u64 v[36:37], v[34:35], 0, v[36:37]
	v_lshl_add_u64 v[38:39], v[34:35], 0, v[38:39]
	v_lshlrev_b64 v[40:41], 13, v[40:41]
	v_lshlrev_b64 v[42:43], 13, v[42:43]
	v_lshl_add_u64 v[44:45], v[34:35], 0, v[44:45]
	v_lshl_add_u64 v[46:47], v[34:35], 0, v[46:47]
	v_lshlrev_b64 v[48:49], 13, v[48:49]
	v_lshlrev_b64 v[108:109], 13, v[108:109]
	v_lshl_add_u64 v[40:41], v[34:35], 0, v[40:41]
	v_lshl_add_u64 v[42:43], v[34:35], 0, v[42:43]
	v_lshl_add_u64 v[48:49], v[34:35], 0, v[48:49]
	v_lshl_add_u64 v[108:109], v[34:35], 0, v[108:109]
	global_load_dword v125, v[36:37], off nt
	global_load_dword v126, v[38:39], off nt
	global_load_dword v127, v[40:41], off nt
	global_load_dword v128, v[42:43], off nt
	s_nop 0
	global_load_dword v44, v[44:45], off nt
	s_nop 0
	global_load_dword v45, v[46:47], off nt
	s_nop 0
	global_load_dword v46, v[48:49], off nt
	global_load_dword v47, v[108:109], off nt
	v_or_b32_e32 v36, 48, v32
	v_or_b32_e32 v38, 50, v32
	v_ashrrev_i32_e32 v37, 31, v36
	v_ashrrev_i32_e32 v39, 31, v38
	v_or_b32_e32 v40, 52, v32
	v_lshlrev_b64 v[36:37], 13, v[36:37]
	v_lshlrev_b64 v[38:39], 13, v[38:39]
	v_ashrrev_i32_e32 v41, 31, v40
	v_lshl_add_u64 v[36:37], v[34:35], 0, v[36:37]
	v_lshl_add_u64 v[38:39], v[34:35], 0, v[38:39]
	v_lshlrev_b64 v[40:41], 13, v[40:41]
	v_lshl_add_u64 v[40:41], v[34:35], 0, v[40:41]
	global_load_dword v48, v[36:37], off nt
	global_load_dword v49, v[38:39], off nt
	global_load_dword v108, v[40:41], off nt
	v_or_b32_e32 v36, 54, v32
	v_or_b32_e32 v38, 56, v32
	v_ashrrev_i32_e32 v37, 31, v36
	v_ashrrev_i32_e32 v39, 31, v38
	v_or_b32_e32 v40, 58, v32
	v_or_b32_e32 v42, 60, v32
	v_or_b32_e32 v32, 62, v32
	v_lshlrev_b64 v[36:37], 13, v[36:37]
	v_lshlrev_b64 v[38:39], 13, v[38:39]
	v_ashrrev_i32_e32 v41, 31, v40
	v_ashrrev_i32_e32 v43, 31, v42
	v_ashrrev_i32_e32 v33, 31, v32
	v_lshl_add_u64 v[36:37], v[34:35], 0, v[36:37]
	v_lshl_add_u64 v[38:39], v[34:35], 0, v[38:39]
	v_lshlrev_b64 v[40:41], 13, v[40:41]
	v_lshlrev_b64 v[42:43], 13, v[42:43]
	v_lshlrev_b64 v[32:33], 13, v[32:33]
	v_lshl_add_u64 v[40:41], v[34:35], 0, v[40:41]
	v_lshl_add_u64 v[42:43], v[34:35], 0, v[42:43]
	global_load_dword v36, v[36:37], off nt
	s_nop 0
	global_load_dword v37, v[38:39], off nt
	s_nop 0
	global_load_dword v38, v[40:41], off nt
	global_load_dword v39, v[42:43], off nt
	v_lshl_add_u64 v[32:33], v[34:35], 0, v[32:33]
	global_load_dword v32, v[32:33], off nt
	v_add_u32_e32 v33, s14, v51
	s_waitcnt vmcnt(0)
; __device__ __forceinline__ unsigned cvtpk(float lo, float hi) { f32x2_t v = {lo, hi}; bf16x2_t b = __builtin_convertvector(v, bf16x2_t); return __builtin_bit_cast(unsigned, b); }
; __device__ __forceinline__ void transpose_item(const float* __restrict__ W, int K, int N, const float* __restrict__ gain, bf16* WT, int mode, ldsp scr, int item, int lane) {
;     ...
; #pragma unroll
;     for (int i = 0; i < 32; ++i) { const int kk = 2 * i + (lane >> 5); float v = tv[i]; if (gain) v *= gain[k0 + kk]; lds_st<float>(scr + 4 * (kk * 33 + (lane & 31)), v); }
;     asm volatile("s_waitcnt lgkmcnt(0)" ::: "memory");
;     const int c = lane & 7;
; #pragma unroll
;     for (int j = 0; j < 4; ++j) { const int n = (lane >> 3) + 8 * j; ldsp s = scr + 4 * ((8 * c) * 33 + n);
;         u32x4 o; o[0] = cvtpk(lds_ld<float>(s), lds_ld<float>(s + 132)); o[1] = cvtpk(lds_ld<float>(s + 264), lds_ld<float>(s + 396));
;         o[2] = cvtpk(lds_ld<float>(s + 528), lds_ld<float>(s + 660)); o[3] = cvtpk(lds_ld<float>(s + 792), lds_ld<float>(s + 924));
;         *(u32x4*)(WT + (size_t)(r0 + n) * K + k0 + 8 * c) = o; }
	ds_write_b32 v33, v0
	v_add_u32_e32 v0, s14, v52
	ds_write_b32 v0, v110
	v_add_u32_e32 v0, s14, v53
	ds_write_b32 v0, v111
	v_add_u32_e32 v0, s14, v54
	ds_write_b32 v0, v112
	v_add_u32_e32 v0, s14, v55
	ds_write_b32 v0, v113
	v_add_u32_e32 v0, s14, v56
	ds_write_b32 v0, v114
	v_add_u32_e32 v0, s14, v57
	ds_write_b32 v0, v115
	v_add_u32_e32 v0, s14, v58
	ds_write_b32 v0, v116
	v_add_u32_e32 v0, s14, v59
	ds_write_b32 v0, v117
	v_add_u32_e32 v0, s14, v60
	ds_write_b32 v0, v118
	v_add_u32_e32 v0, s14, v61
	ds_write_b32 v0, v119
	v_add_u32_e32 v0, s14, v62
	ds_write_b32 v0, v120
	v_add_u32_e32 v0, s14, v63
	ds_write_b32 v0, v121
	v_add_u32_e32 v0, s14, v64
	ds_write_b32 v0, v122
	v_add_u32_e32 v0, s14, v65
	ds_write_b32 v0, v123
	v_add_u32_e32 v0, s14, v66
	ds_write_b32 v0, v124
	v_add_u32_e32 v0, s14, v67
	s_ashr_i32 s11, s10, 31
	v_lshl_add_u64 v[40:41], s[10:11], 1, v[30:31]
	ds_write_b32 v0, v125
	v_add_u32_e32 v0, s14, v68
	ds_write_b32 v0, v126
	v_add_u32_e32 v0, s14, v69
	ds_write_b32 v0, v127
	v_add_u32_e32 v0, s14, v70
	ds_write_b32 v0, v128
	v_add_u32_e32 v0, s14, v71
	ds_write_b32 v0, v44
	v_add_u32_e32 v0, s14, v72
	ds_write_b32 v0, v45
	v_add_u32_e32 v0, s14, v73
	ds_write_b32 v0, v46
	v_add_u32_e32 v0, s14, v74
	ds_write_b32 v0, v47
	v_add_u32_e32 v0, s14, v75
	ds_write_b32 v0, v48
	v_add_u32_e32 v0, s14, v76
	ds_write_b32 v0, v49
	v_add_u32_e32 v0, s14, v77
	ds_write_b32 v0, v108
	v_add_u32_e32 v0, s14, v78
	ds_write_b32 v0, v36
	v_add_u32_e32 v0, s14, v79
	ds_write_b32 v0, v37
	v_add_u32_e32 v0, s14, v80
	ds_write_b32 v0, v38
	v_add_u32_e32 v0, s14, v81
	ds_write_b32 v0, v39
	v_add_u32_e32 v0, s14, v82
	ds_write_b32 v0, v32
	s_waitcnt lgkmcnt(0)
	v_add_u32_e32 v0, s14, v84
	ds_read2_b32 v[32:33], v0 offset1:33
	ds_read2_b32 v[34:35], v0 offset0:66 offset1:99
	ds_read2_b32 v[36:37], v0 offset0:132 offset1:165
	ds_read2_b32 v[38:39], v0 offset0:198 offset1:231
	v_add_u32_e32 v0, s14, v86
	s_waitcnt lgkmcnt(3)
	v_cvt_pk_bf16_f32 v32, v32, v33
	s_waitcnt lgkmcnt(2)
	v_cvt_pk_bf16_f32 v33, v34, v35
	s_waitcnt lgkmcnt(1)
	v_cvt_pk_bf16_f32 v34, v36, v37
	v_add_u32_e32 v36, s2, v83
	ds_read2_b32 v[42:43], v0 offset1:33
	ds_read2_b32 v[44:45], v0 offset0:66 offset1:99
	ds_read2_b32 v[46:47], v0 offset0:132 offset1:165
	ds_read2_b32 v[48:49], v0 offset0:198 offset1:231
	v_ashrrev_i32_e32 v37, 31, v36
	s_waitcnt lgkmcnt(4)
	v_cvt_pk_bf16_f32 v35, v38, v39
	v_lshlrev_b64 v[38:39], 11, v[36:37]
	v_lshl_add_u64 v[38:39], v[40:41], 0, v[38:39]
	global_store_dwordx4 v[38:39], v[32:35], off nt
	v_add_u32_e32 v0, s14, v88
	v_add_u32_e32 v38, 8, v36
	s_waitcnt lgkmcnt(3)
	v_cvt_pk_bf16_f32 v32, v42, v43
	s_waitcnt lgkmcnt(2)
	v_cvt_pk_bf16_f32 v33, v44, v45
	s_waitcnt lgkmcnt(1)
	v_cvt_pk_bf16_f32 v34, v46, v47
	s_waitcnt lgkmcnt(0)
	v_cvt_pk_bf16_f32 v35, v48, v49
	ds_read2_b32 v[42:43], v0 offset1:33
	ds_read2_b32 v[44:45], v0 offset0:66 offset1:99
	ds_read2_b32 v[46:47], v0 offset0:132 offset1:165
	ds_read2_b32 v[48:49], v0 offset0:198 offset1:231
	v_ashrrev_i32_e32 v39, 31, v38
	v_lshlrev_b64 v[38:39], 11, v[38:39]
	v_lshl_add_u64 v[38:39], v[40:41], 0, v[38:39]
	global_store_dwordx4 v[38:39], v[32:35], off nt
	v_add_u32_e32 v0, s14, v90
	v_add_u32_e32 v38, 16, v36
	s_waitcnt lgkmcnt(3)
	v_cvt_pk_bf16_f32 v32, v42, v43
	s_waitcnt lgkmcnt(2)
	v_cvt_pk_bf16_f32 v33, v44, v45
	s_waitcnt lgkmcnt(1)
	v_cvt_pk_bf16_f32 v34, v46, v47
	s_waitcnt lgkmcnt(0)
	v_cvt_pk_bf16_f32 v35, v48, v49
	ds_read2_b32 v[42:43], v0 offset1:33
	ds_read2_b32 v[44:45], v0 offset0:66 offset1:99
	ds_read2_b32 v[46:47], v0 offset0:132 offset1:165
	ds_read2_b32 v[48:49], v0 offset0:198 offset1:231
	v_ashrrev_i32_e32 v39, 31, v38
	v_add_u32_e32 v36, 24, v36
	v_lshlrev_b64 v[38:39], 11, v[38:39]
	v_ashrrev_i32_e32 v37, 31, v36
	v_lshl_add_u64 v[38:39], v[40:41], 0, v[38:39]
	v_lshlrev_b64 v[36:37], 11, v[36:37]
	global_store_dwordx4 v[38:39], v[32:35], off nt
	v_lshl_add_u64 v[36:37], v[40:41], 0, v[36:37]
	s_waitcnt lgkmcnt(3)
	v_cvt_pk_bf16_f32 v32, v42, v43
	s_waitcnt lgkmcnt(2)
	v_cvt_pk_bf16_f32 v33, v44, v45
	s_waitcnt lgkmcnt(1)
	v_cvt_pk_bf16_f32 v34, v46, v47
	s_waitcnt lgkmcnt(0)
	v_cvt_pk_bf16_f32 v35, v48, v49
	global_store_dwordx4 v[36:37], v[32:35], off nt
	s_waitcnt lgkmcnt(0)
	s_branch .LBB0_567

; __device__ __forceinline__ unsigned cvtpk(float lo, float hi) { f32x2_t v = {lo, hi}; bf16x2_t b = __builtin_convertvector(v, bf16x2_t); return __builtin_bit_cast(unsigned, b); }
; __global__ void __launch_bounds__(512, 2) fwd_megakernel(Args a) {
;     ...
;             for (int i = (bx - nb0) * 512 + tid; i < TOK * 256 / 8; i += (G - nb0) * 512) {
;                 const f32x4 p0 = __builtin_nontemporal_load((const f32x4*)(a.in[1] + (size_t)i * 8)), p1 = __builtin_nontemporal_load((const f32x4*)(a.in[1] + (size_t)i * 8 + 4));
;                 u32x4 w4; w4[0] = cvtpk(p0[0], p0[1]); w4[1] = cvtpk(p0[2], p0[3]); w4[2] = cvtpk(p1[0], p1[1]); w4[3] = cvtpk(p1[2], p1[3]);
;                 *(u32x4*)(PB + (size_t)i * 8) = w4;
;             }
.LBB0_702:
	global_load_dwordx4 v[6:9], v[2:3], off offset:-16 nt
	global_load_dwordx4 v[10:13], v[2:3], off nt
	v_add_u32_e32 v0, s4, v0
	v_cmp_lt_i32_e32 vcc, s0, v0
	v_lshl_add_u64 v[2:3], v[2:3], 0, s[6:7]
	s_or_b64 s[10:11], vcc, s[10:11]
	s_waitcnt vmcnt(0)
	v_cvt_pk_bf16_f32 v6, v6, v7
	v_cvt_pk_bf16_f32 v7, v8, v9
	v_cvt_pk_bf16_f32 v8, v10, v11
	v_cvt_pk_bf16_f32 v9, v12, v13
	global_store_dwordx4 v[4:5], v[6:9], off nt
	v_lshl_add_u64 v[4:5], v[4:5], 0, s[8:9]
	s_andn2_b64 exec, exec, s[10:11]
	s_cbranch_execnz .LBB0_702

;     __device__ __forceinline__ void operator()(const pg8::f32x4 (&acc)[2][2][4][2], const pg8::Unit& u, int wr, int wc, int fr, int fq) const {
;         const int row0 = u.pm * 256 + wr * 64 + fr, colb = u.pn * 256 + wc * 32 + 8 * fq;
;         float s4[2][4], sp[2][4]; pg8::f32x4 gp[2][2];
; #pragma unroll
;         for (int ai = 0; ai < 2; ++ai)
; #pragma unroll
;             for (int m = 0; m < 4; ++m) { s4[ai][m] = ss4[row0 + ai * 128 + m * 16]; sp[ai][m] = ssp[row0 + ai * 128 + m * 16]; }
; #pragma unroll
;         for (int bj = 0; bj < 2; ++bj) { gp[bj][0] = *(const pg8::f32x4*)(gpost + colb + bj * 128); gp[bj][1] = *(const pg8::f32x4*)(gpost + colb + bj * 128 + 4); }
; #pragma unroll
;         for (int ai = 0; ai < 2; ++ai)
; #pragma unroll
;             for (int mp = 0; mp < 2; ++mp) {
;                 pg8::f32x4 xv[2][2][2]; u32x4 pl[2][2];
; #pragma unroll
;                 for (int mm = 0; mm < 2; ++mm)
; #pragma unroll
;                     for (int bj = 0; bj < 2; ++bj) { const size_t off = (size_t)(row0 + ai * 128 + (2 * mp + mm) * 16) * DM + colb + bj * 128;
;                         xv[mm][bj][0] = *(const pg8::f32x4*)(X + off); xv[mm][bj][1] = *(const pg8::f32x4*)(X + off + 4); pl[mm][bj] = *(const u32x4*)(PLE + off); }
; #pragma unroll
;                 for (int mm = 0; mm < 2; ++mm) {
;                     const int m = 2 * mp + mm;
;                     const float rs = rsqrtf(s4[ai][m] * (1.f / DM) + EPS), rp = rsqrtf(sp[ai][m] * (1.f / DM) + EPS);
; #pragma unroll
;                     for (int bj = 0; bj < 2; ++bj) {
;                         const size_t off = (size_t)(row0 + ai * 128 + m * 16) * DM + colb + bj * 128;
;                         const u32x4 pw = pl[mm][bj];
;                         const pg8::f32x4 g0 = gp[bj][0], g1 = gp[bj][1];
;                         pg8::f32x4 x0 = xv[mm][bj][0], x1 = xv[mm][bj][1];
;                         const pg8::f32x4 a0 = acc[ai][bj][m][0] * rs, a1 = acc[ai][bj][m][1] * rs;
;                         x0[0] += sigm(a0[0]) * (bflo(pw[0]) * rp * g0[0]); x0[1] += sigm(a0[1]) * (bfhi(pw[0]) * rp * g0[1]);
;                         x0[2] += sigm(a0[2]) * (bflo(pw[1]) * rp * g0[2]); x0[3] += sigm(a0[3]) * (bfhi(pw[1]) * rp * g0[3]);
;                         x1[0] += sigm(a1[0]) * (bflo(pw[2]) * rp * g1[0]); x1[1] += sigm(a1[1]) * (bfhi(pw[2]) * rp * g1[1]);
.LBB0_1298:
	v_lshl_add_u32 v56, s2, 8, v200
	v_ashrrev_i32_e32 v57, 31, v56
	v_lshlrev_b64 v[58:59], 2, v[56:57]
	v_lshl_add_u64 v[144:145], s[8:9], 0, v[58:59]
	v_lshl_add_u64 v[146:147], s[10:11], 0, v[58:59]
	global_load_dword v219, v[144:145], off
	global_load_dword v240, v[146:147], off
	v_lshl_or_b32 v190, s3, 8, v202
	v_ashrrev_i32_e32 v191, 31, v190
	v_lshlrev_b64 v[58:59], 11, v[56:57]
	v_lshl_add_u64 v[188:189], v[58:59], 0, v[190:191]
	v_lshlrev_b64 v[148:149], 1, v[188:189]
	v_lshl_add_u64 v[58:59], s[6:7], 0, v[148:149]
	global_load_dwordx4 v[220:223], v[58:59], off
	v_lshl_add_u64 v[64:65], v[190:191], 2, s[60:61]
	v_lshl_add_u64 v[198:199], v[188:189], 2, s[62:63]
	global_load_dwordx4 v[76:79], v[64:65], off
	global_load_dwordx4 v[72:75], v[64:65], off offset:16
	global_load_dwordx4 v[224:227], v[198:199], off offset:16
	global_load_dwordx4 v[228:231], v[198:199], off
	v_or_b32_e32 v150, 16, v56
	v_or_b32_e32 v194, 32, v56
	v_or_b32_e32 v192, 48, v56
	v_ashrrev_i32_e32 v151, 31, v150
	v_ashrrev_i32_e32 v195, 31, v194
	v_ashrrev_i32_e32 v193, 31, v192
	v_lshlrev_b64 v[152:153], 2, v[150:151]
	v_lshlrev_b64 v[154:155], 2, v[194:195]
	v_lshlrev_b64 v[156:157], 2, v[192:193]
	global_load_dwordx4 v[56:59], v[64:65], off offset:528
	s_nop 0
	global_load_dwordx4 v[64:67], v[64:65], off offset:512
	v_lshl_add_u64 v[158:159], s[8:9], 0, v[152:153]
	v_lshl_add_u64 v[152:153], s[10:11], 0, v[152:153]
	v_lshl_add_u64 v[160:161], s[8:9], 0, v[154:155]
	v_lshl_add_u64 v[154:155], s[10:11], 0, v[154:155]
	v_lshl_add_u64 v[162:163], s[8:9], 0, v[156:157]
	v_lshl_add_u64 v[156:157], s[10:11], 0, v[156:157]
	global_load_dword v214, v[144:145], off offset:512
	global_load_dword v213, v[146:147], off offset:512
	global_load_dword v212, v[144:145], off offset:576
	global_load_dword v211, v[146:147], off offset:576
	global_load_dword v210, v[144:145], off offset:640
	global_load_dword v207, v[144:145], off offset:704
	global_load_dword v209, v[146:147], off offset:640
	global_load_dword v243, v[158:159], off
	global_load_dword v246, v[152:153], off
	global_load_dword v218, v[160:161], off
	global_load_dword v217, v[154:155], off
	global_load_dword v216, v[162:163], off
	global_load_dword v215, v[156:157], off
	global_load_dword v208, v[146:147], off offset:704
	global_load_dwordx4 v[168:171], v[198:199], off offset:528
	global_load_dwordx4 v[232:235], v[198:199], off offset:512
	v_lshlrev_b64 v[150:151], 11, v[150:151]
	v_lshl_add_u64 v[144:145], v[150:151], 0, v[190:191]
	v_or_b32_e32 v148, 0x100, v148
	v_lshl_add_u64 v[196:197], v[144:145], 2, s[62:63]
	v_lshl_add_u64 v[148:149], s[6:7], 0, v[148:149]
	v_lshlrev_b64 v[150:151], 1, v[144:145]
	global_load_dwordx4 v[156:159], v[196:197], off offset:16
	global_load_dwordx4 v[164:167], v[196:197], off
	global_load_dwordx4 v[144:147], v[196:197], off offset:528
	global_load_dwordx4 v[152:155], v[196:197], off offset:512
	global_load_dwordx4 v[236:239], v[148:149], off
	v_lshl_add_u64 v[160:161], s[6:7], 0, v[150:151]
	v_or_b32_e32 v150, 0x100, v150
	v_lshl_add_u64 v[148:149], s[6:7], 0, v[150:151]
	global_load_dwordx4 v[160:163], v[160:161], off
	s_nop 0
	global_load_dwordx4 v[148:151], v[148:149], off
	s_waitcnt vmcnt(0)
	v_fmamk_f32 v219, v219, 0x3a000000, v206
	v_mul_f32_e32 v241, 0x4b800000, v219
	v_cmp_gt_f32_e32 vcc, s51, v219
	v_fmamk_f32 v240, v240, 0x3a000000, v206
	v_mul_f32_e32 v242, 0x4b800000, v240
	v_cndmask_b32_e32 v219, v219, v241, vcc
	v_rsq_f32_e32 v219, v219
	v_cmp_gt_f32_e64 s[2:3], s51, v240
	v_and_b32_e32 v241, 0xffff0000, v220
	s_nop 0
	v_cndmask_b32_e64 v240, v240, v242, s[2:3]
	v_rsq_f32_e32 v242, v240
	v_lshlrev_b32_e32 v240, 16, v220
	v_mul_f32_e32 v220, 0x45800000, v219
	v_cndmask_b32_e32 v220, v219, v220, vcc
	v_pk_mul_f32 v[140:141], v[140:141], v[220:221] op_sel_hi:[1,0]
	v_pk_mul_f32 v[142:143], v[142:143], v[220:221] op_sel_hi:[1,0]
	v_mul_f32_e32 v140, 0xbfb8aa3b, v140
	v_mul_f32_e32 v141, 0xbfb8aa3b, v141
	v_exp_f32_e32 v140, v140
	v_exp_f32_e32 v141, v141
	v_mul_f32_e32 v142, 0xbfb8aa3b, v142
	v_mul_f32_e32 v143, 0xbfb8aa3b, v143
	v_add_f32_e32 v140, 1.0, v140
	v_add_f32_e32 v141, 1.0, v141
	v_mul_f32_e32 v244, 0x45800000, v242
	v_exp_f32_e32 v142, v142
	v_rcp_f32_e32 v140, v140
	v_rcp_f32_e32 v141, v141
	v_exp_f32_e32 v143, v143
	v_cndmask_b32_e64 v242, v242, v244, s[2:3]
	v_pk_mul_f32 v[244:245], v[138:139], v[220:221] op_sel_hi:[1,0]
	v_pk_mul_f32 v[138:139], v[136:137], v[220:221] op_sel_hi:[1,0]
	v_pk_mul_f32 v[136:137], v[242:243], v[240:241] op_sel_hi:[0,1]
	v_pk_mul_f32 v[136:137], v[76:77], v[136:137]
	v_mul_f32_e32 v138, 0xbfb8aa3b, v138
	v_add_f32_e32 v142, 1.0, v142
	v_pk_fma_f32 v[136:137], v[140:141], v[136:137], v[228:229]
	v_add_f32_e32 v141, 1.0, v143
	v_exp_f32_e32 v219, v138
	v_mul_f32_e32 v138, 0xbfb8aa3b, v139
	v_rcp_f32_e32 v140, v142
	v_rcp_f32_e32 v141, v141
	v_lshlrev_b32_e32 v142, 16, v221
	v_and_b32_e32 v143, 0xffff0000, v221
	v_exp_f32_e32 v221, v138
	v_pk_mul_f32 v[142:143], v[242:243], v[142:143] op_sel_hi:[0,1]
	v_pk_mul_f32 v[142:143], v[78:79], v[142:143]
	s_nop 0
	v_pk_fma_f32 v[138:139], v[140:141], v[142:143], v[230:231]
	v_add_f32_e32 v140, 1.0, v219
	v_add_f32_e32 v141, 1.0, v221
	v_mul_f32_e32 v219, 0xbfb8aa3b, v244
	v_mul_f32_e32 v221, 0xbfb8aa3b, v245
	v_rcp_f32_e32 v140, v140
	v_rcp_f32_e32 v141, v141
	v_exp_f32_e32 v219, v219
	v_exp_f32_e32 v221, v221
	v_lshlrev_b32_e32 v142, 16, v222
	v_and_b32_e32 v143, 0xffff0000, v222
	v_pk_mul_f32 v[142:143], v[242:243], v[142:143] op_sel_hi:[0,1]
	v_pk_mul_f32 v[142:143], v[72:73], v[142:143]
	v_lshlrev_b32_e32 v222, 16, v223
	v_pk_fma_f32 v[140:141], v[140:141], v[142:143], v[224:225]
; __device__ __forceinline__ float bflo(unsigned w) { return __uint_as_float(w << 16); }
; __device__ __forceinline__ float bfhi(unsigned w) { return __uint_as_float(w & 0xffff0000u); }
; __device__ __forceinline__ float sigm(float x) { return __builtin_amdgcn_rcpf(1.f + __builtin_amdgcn_exp2f(-x * LOG2E)); }
;     __device__ __forceinline__ void operator()(const pg8::f32x4 (&acc)[2][2][4][2], const pg8::Unit& u, int wr, int wc, int fr, int fq) const {
;     ...
;                     for (int bj = 0; bj < 2; ++bj) {
;                         const size_t off = (size_t)(row0 + ai * 128 + m * 16) * DM + colb + bj * 128;
;                         const u32x4 pw = pl[mm][bj];
;                         const pg8::f32x4 g0 = gp[bj][0], g1 = gp[bj][1];
;                         pg8::f32x4 x0 = xv[mm][bj][0], x1 = xv[mm][bj][1];
;                         const pg8::f32x4 a0 = acc[ai][bj][m][0] * rs, a1 = acc[ai][bj][m][1] * rs;
;                         x0[0] += sigm(a0[0]) * (bflo(pw[0]) * rp * g0[0]); x0[1] += sigm(a0[1]) * (bfhi(pw[0]) * rp * g0[1]);
;                         x0[2] += sigm(a0[2]) * (bflo(pw[1]) * rp * g0[2]); x0[3] += sigm(a0[3]) * (bfhi(pw[1]) * rp * g0[3]);
;                         x1[0] += sigm(a1[0]) * (bflo(pw[2]) * rp * g1[0]); x1[1] += sigm(a1[1]) * (bfhi(pw[2]) * rp * g1[1]);
;                         x1[2] += sigm(a1[2]) * (bflo(pw[3]) * rp * g1[2]); x1[3] += sigm(a1[3]) * (bfhi(pw[3]) * rp * g1[3]);
;                         *(pg8::f32x4*)(X + off) = x0; *(pg8::f32x4*)(X + off + 4) = x1;
	v_add_f32_e32 v142, 1.0, v219
	v_add_f32_e32 v143, 1.0, v221
	v_rcp_f32_e32 v142, v142
	v_rcp_f32_e32 v143, v143
	v_and_b32_e32 v223, 0xffff0000, v223
	v_pk_mul_f32 v[222:223], v[242:243], v[222:223] op_sel_hi:[0,1]
	v_pk_mul_f32 v[222:223], v[74:75], v[222:223]
	v_pk_mul_f32 v[132:133], v[132:133], v[220:221] op_sel_hi:[1,0]
	v_pk_fma_f32 v[142:143], v[142:143], v[222:223], v[226:227]
	global_store_dwordx4 v[198:199], v[136:139], off nt
	global_store_dwordx4 v[198:199], v[140:143], off offset:16 nt
	v_pk_mul_f32 v[134:135], v[134:135], v[220:221] op_sel_hi:[1,0]
	v_pk_mul_f32 v[136:137], v[130:131], v[220:221] op_sel_hi:[1,0]
	v_mul_f32_e32 v130, 0xbfb8aa3b, v132
	v_exp_f32_e32 v132, v130
	v_mul_f32_e32 v130, 0xbfb8aa3b, v133
	v_exp_f32_e32 v133, v130
	v_pk_mul_f32 v[130:131], v[128:129], v[220:221] op_sel_hi:[1,0]
	v_add_f32_e32 v128, 1.0, v132
	v_mul_f32_e32 v134, 0xbfb8aa3b, v134
	v_add_f32_e32 v129, 1.0, v133
	v_mul_f32_e32 v135, 0xbfb8aa3b, v135
	v_rcp_f32_e32 v128, v128
	v_rcp_f32_e32 v129, v129
	v_exp_f32_e32 v134, v134
	v_exp_f32_e32 v135, v135
	v_lshlrev_b32_e32 v132, 16, v236
	v_and_b32_e32 v133, 0xffff0000, v236
	v_pk_mul_f32 v[132:133], v[242:243], v[132:133] op_sel_hi:[0,1]
	v_pk_mul_f32 v[132:133], v[64:65], v[132:133]
	v_mul_f32_e32 v130, 0xbfb8aa3b, v130
	v_pk_fma_f32 v[128:129], v[128:129], v[132:133], v[232:233]
	v_add_f32_e32 v132, 1.0, v134
	v_add_f32_e32 v133, 1.0, v135
	v_exp_f32_e32 v138, v130
	v_mul_f32_e32 v130, 0xbfb8aa3b, v131
	v_rcp_f32_e32 v132, v132
	v_rcp_f32_e32 v133, v133
	v_exp_f32_e32 v139, v130
	v_lshlrev_b32_e32 v134, 16, v237
	v_and_b32_e32 v135, 0xffff0000, v237
	v_pk_mul_f32 v[134:135], v[242:243], v[134:135] op_sel_hi:[0,1]
	v_pk_mul_f32 v[134:135], v[66:67], v[134:135]
	v_mul_f32_e32 v136, 0xbfb8aa3b, v136
	v_pk_fma_f32 v[130:131], v[132:133], v[134:135], v[234:235]
	v_add_f32_e32 v132, 1.0, v138
	v_add_f32_e32 v133, 1.0, v139
	v_mul_f32_e32 v137, 0xbfb8aa3b, v137
	v_rcp_f32_e32 v132, v132
	v_rcp_f32_e32 v133, v133
	v_exp_f32_e32 v136, v136
	v_exp_f32_e32 v137, v137
	global_store_dwordx4 v[198:199], v[128:131], off offset:512 nt
	v_lshlrev_b32_e32 v134, 16, v238
	v_and_b32_e32 v135, 0xffff0000, v238
	v_fmamk_f32 v128, v243, 0x3a000000, v206
	v_mul_f32_e32 v129, 0x4b800000, v128
	v_cmp_gt_f32_e32 vcc, s51, v128
	v_pk_mul_f32 v[134:135], v[242:243], v[134:135] op_sel_hi:[0,1]
	v_pk_mul_f32 v[134:135], v[56:57], v[134:135]
	v_cndmask_b32_e32 v128, v128, v129, vcc
	v_fmamk_f32 v129, v246, 0x3a000000, v206
	v_rsq_f32_e32 v128, v128
	v_mul_f32_e32 v130, 0x4b800000, v129
	v_cmp_gt_f32_e64 s[2:3], s51, v129
	v_pk_fma_f32 v[132:133], v[132:133], v[134:135], v[168:169]
	v_add_f32_e32 v134, 1.0, v136
	v_add_f32_e32 v135, 1.0, v137
	v_cndmask_b32_e64 v129, v129, v130, s[2:3]
	v_rcp_f32_e32 v134, v134
	v_rcp_f32_e32 v135, v135
	v_rsq_f32_e32 v129, v129
	v_lshlrev_b32_e32 v136, 16, v239
	v_and_b32_e32 v137, 0xffff0000, v239
	v_pk_mul_f32 v[136:137], v[242:243], v[136:137] op_sel_hi:[0,1]
	v_mul_f32_e32 v130, 0x45800000, v128
	v_pk_mul_f32 v[136:137], v[58:59], v[136:137]
	v_cndmask_b32_e32 v128, v128, v130, vcc
	v_pk_fma_f32 v[134:135], v[134:135], v[136:137], v[170:171]
	v_pk_mul_f32 v[124:125], v[124:125], v[128:129] op_sel_hi:[1,0]
	global_store_dwordx4 v[198:199], v[132:135], off offset:528 nt
	v_pk_mul_f32 v[126:127], v[126:127], v[128:129] op_sel_hi:[1,0]
	v_mul_f32_e32 v130, 0x45800000, v129
	v_pk_mul_f32 v[132:133], v[122:123], v[128:129] op_sel_hi:[1,0]
	v_mul_f32_e32 v122, 0xbfb8aa3b, v124
	v_exp_f32_e32 v124, v122
	v_mul_f32_e32 v122, 0xbfb8aa3b, v125
	v_exp_f32_e32 v125, v122
	v_pk_mul_f32 v[122:123], v[120:121], v[128:129] op_sel_hi:[1,0]
	v_add_f32_e32 v120, 1.0, v124
	v_mul_f32_e32 v126, 0xbfb8aa3b, v126
	v_add_f32_e32 v121, 1.0, v125
	v_mul_f32_e32 v127, 0xbfb8aa3b, v127
	v_rcp_f32_e32 v120, v120
	v_rcp_f32_e32 v121, v121
	v_exp_f32_e32 v126, v126
	v_exp_f32_e32 v127, v127
	v_cndmask_b32_e64 v130, v129, v130, s[2:3]
	v_lshlrev_b32_e32 v124, 16, v160
	v_and_b32_e32 v125, 0xffff0000, v160
	v_pk_mul_f32 v[124:125], v[130:131], v[124:125] op_sel_hi:[0,1]
	v_pk_mul_f32 v[124:125], v[76:77], v[124:125]
	v_mul_f32_e32 v122, 0xbfb8aa3b, v122
	v_pk_fma_f32 v[120:121], v[120:121], v[124:125], v[164:165]
	v_add_f32_e32 v124, 1.0, v126
	v_add_f32_e32 v125, 1.0, v127
	v_rcp_f32_e32 v124, v124
	v_rcp_f32_e32 v125, v125
	v_lshlrev_b32_e32 v126, 16, v161
	v_and_b32_e32 v127, 0xffff0000, v161
	v_exp_f32_e32 v129, v122
	v_mul_f32_e32 v122, 0xbfb8aa3b, v123
	v_pk_mul_f32 v[126:127], v[130:131], v[126:127] op_sel_hi:[0,1]
	v_exp_f32_e32 v131, v122
	v_pk_mul_f32 v[126:127], v[78:79], v[126:127]
	s_nop 0
	v_pk_fma_f32 v[122:123], v[124:125], v[126:127], v[166:167]
	v_lshlrev_b32_e32 v126, 16, v162
	v_and_b32_e32 v127, 0xffff0000, v162
	v_add_f32_e32 v124, 1.0, v129
	v_add_f32_e32 v125, 1.0, v131
	v_pk_mul_f32 v[126:127], v[130:131], v[126:127] op_sel_hi:[0,1]
	v_mul_f32_e32 v129, 0xbfb8aa3b, v132
	v_mul_f32_e32 v131, 0xbfb8aa3b, v133
	v_rcp_f32_e32 v124, v124
	v_rcp_f32_e32 v125, v125
	v_exp_f32_e32 v129, v129
	v_exp_f32_e32 v131, v131
	v_pk_mul_f32 v[126:127], v[72:73], v[126:127]
	v_lshlrev_b32_e32 v132, 16, v163
	v_pk_fma_f32 v[124:125], v[124:125], v[126:127], v[156:157]
	v_add_f32_e32 v126, 1.0, v129
	v_add_f32_e32 v127, 1.0, v131
	v_rcp_f32_e32 v126, v126
	v_rcp_f32_e32 v127, v127
	v_and_b32_e32 v133, 0xffff0000, v163
	v_pk_mul_f32 v[132:133], v[130:131], v[132:133] op_sel_hi:[0,1]
	v_pk_mul_f32 v[132:133], v[74:75], v[132:133]
	v_pk_mul_f32 v[116:117], v[116:117], v[128:129] op_sel_hi:[1,0]
	v_pk_fma_f32 v[126:127], v[126:127], v[132:133], v[158:159]
	global_store_dwordx4 v[196:197], v[120:123], off nt
; __device__ __forceinline__ float bflo(unsigned w) { return __uint_as_float(w << 16); }
; __device__ __forceinline__ float bfhi(unsigned w) { return __uint_as_float(w & 0xffff0000u); }
; __device__ __forceinline__ float sigm(float x) { return __builtin_amdgcn_rcpf(1.f + __builtin_amdgcn_exp2f(-x * LOG2E)); }
;     __device__ __forceinline__ void operator()(const pg8::f32x4 (&acc)[2][2][4][2], const pg8::Unit& u, int wr, int wc, int fr, int fq) const {
;     ...
;                 for (int mm = 0; mm < 2; ++mm)
; #pragma unroll
;                     for (int bj = 0; bj < 2; ++bj) { const size_t off = (size_t)(row0 + ai * 128 + (2 * mp + mm) * 16) * DM + colb + bj * 128;
;                         xv[mm][bj][0] = *(const pg8::f32x4*)(X + off); xv[mm][bj][1] = *(const pg8::f32x4*)(X + off + 4); pl[mm][bj] = *(const u32x4*)(PLE + off); }
;     ...
;                     for (int bj = 0; bj < 2; ++bj) {
;                         const size_t off = (size_t)(row0 + ai * 128 + m * 16) * DM + colb + bj * 128;
;                         const u32x4 pw = pl[mm][bj];
;                         const pg8::f32x4 g0 = gp[bj][0], g1 = gp[bj][1];
;                         pg8::f32x4 x0 = xv[mm][bj][0], x1 = xv[mm][bj][1];
;                         const pg8::f32x4 a0 = acc[ai][bj][m][0] * rs, a1 = acc[ai][bj][m][1] * rs;
;                         x0[0] += sigm(a0[0]) * (bflo(pw[0]) * rp * g0[0]); x0[1] += sigm(a0[1]) * (bfhi(pw[0]) * rp * g0[1]);
;                         x0[2] += sigm(a0[2]) * (bflo(pw[1]) * rp * g0[2]); x0[3] += sigm(a0[3]) * (bfhi(pw[1]) * rp * g0[3]);
;                         x1[0] += sigm(a1[0]) * (bflo(pw[2]) * rp * g1[0]); x1[1] += sigm(a1[1]) * (bfhi(pw[2]) * rp * g1[1]);
;                         x1[2] += sigm(a1[2]) * (bflo(pw[3]) * rp * g1[2]); x1[3] += sigm(a1[3]) * (bfhi(pw[3]) * rp * g1[3]);
;                         *(pg8::f32x4*)(X + off) = x0; *(pg8::f32x4*)(X + off + 4) = x1;
	global_store_dwordx4 v[196:197], v[124:127], off offset:16 nt
	v_pk_mul_f32 v[118:119], v[118:119], v[128:129] op_sel_hi:[1,0]
	v_pk_mul_f32 v[120:121], v[114:115], v[128:129] op_sel_hi:[1,0]
	v_mul_f32_e32 v114, 0xbfb8aa3b, v116
	v_exp_f32_e32 v116, v114
	v_mul_f32_e32 v114, 0xbfb8aa3b, v117
	v_exp_f32_e32 v117, v114
	v_pk_mul_f32 v[114:115], v[112:113], v[128:129] op_sel_hi:[1,0]
	v_add_f32_e32 v112, 1.0, v116
	v_mul_f32_e32 v118, 0xbfb8aa3b, v118
	v_add_f32_e32 v113, 1.0, v117
	v_mul_f32_e32 v119, 0xbfb8aa3b, v119
	v_rcp_f32_e32 v112, v112
	v_rcp_f32_e32 v113, v113
	v_exp_f32_e32 v118, v118
	v_exp_f32_e32 v119, v119
	v_lshlrev_b32_e32 v116, 16, v148
	v_and_b32_e32 v117, 0xffff0000, v148
	v_pk_mul_f32 v[116:117], v[130:131], v[116:117] op_sel_hi:[0,1]
	v_pk_mul_f32 v[116:117], v[64:65], v[116:117]
	v_mul_f32_e32 v114, 0xbfb8aa3b, v114
	v_pk_fma_f32 v[112:113], v[112:113], v[116:117], v[152:153]
	v_add_f32_e32 v116, 1.0, v118
	v_add_f32_e32 v117, 1.0, v119
	v_exp_f32_e32 v122, v114
	v_mul_f32_e32 v114, 0xbfb8aa3b, v115
	v_rcp_f32_e32 v116, v116
	v_rcp_f32_e32 v117, v117
	v_exp_f32_e32 v123, v114
	v_lshlrev_b32_e32 v118, 16, v149
	v_and_b32_e32 v119, 0xffff0000, v149
	v_pk_mul_f32 v[118:119], v[130:131], v[118:119] op_sel_hi:[0,1]
	v_pk_mul_f32 v[118:119], v[66:67], v[118:119]
	v_mul_f32_e32 v120, 0xbfb8aa3b, v120
	v_pk_fma_f32 v[114:115], v[116:117], v[118:119], v[154:155]
	v_add_f32_e32 v116, 1.0, v122
	v_add_f32_e32 v117, 1.0, v123
	v_mul_f32_e32 v121, 0xbfb8aa3b, v121
	v_rcp_f32_e32 v116, v116
	v_rcp_f32_e32 v117, v117
	v_exp_f32_e32 v120, v120
	v_exp_f32_e32 v121, v121
	v_lshlrev_b32_e32 v118, 16, v150
	v_and_b32_e32 v119, 0xffff0000, v150
	v_pk_mul_f32 v[118:119], v[130:131], v[118:119] op_sel_hi:[0,1]
	v_pk_mul_f32 v[118:119], v[56:57], v[118:119]
	v_fmamk_f32 v128, v218, 0x3a000000, v206
	v_pk_fma_f32 v[116:117], v[116:117], v[118:119], v[144:145]
	v_add_f32_e32 v118, 1.0, v120
	v_add_f32_e32 v119, 1.0, v121
	v_rcp_f32_e32 v118, v118
	v_rcp_f32_e32 v119, v119
	v_lshlrev_b32_e32 v120, 16, v151
	v_and_b32_e32 v121, 0xffff0000, v151
	v_pk_mul_f32 v[120:121], v[130:131], v[120:121] op_sel_hi:[0,1]
	v_pk_mul_f32 v[120:121], v[58:59], v[120:121]
	v_mul_f32_e32 v129, 0x4b800000, v128
	v_pk_fma_f32 v[118:119], v[118:119], v[120:121], v[146:147]
	global_store_dwordx4 v[196:197], v[112:115], off offset:512 nt
	global_store_dwordx4 v[196:197], v[116:119], off offset:528 nt
	v_cmp_gt_f32_e32 vcc, s51, v128
	v_lshlrev_b64 v[112:113], 11, v[194:195]
	v_lshl_add_u64 v[112:113], v[112:113], 0, v[190:191]
	v_lshlrev_b64 v[114:115], 1, v[112:113]
	v_lshl_add_u64 v[116:117], s[6:7], 0, v[114:115]
	global_load_dwordx4 v[140:143], v[116:117], off
	v_lshl_add_u64 v[138:139], v[112:113], 2, s[62:63]
	global_load_dwordx4 v[144:147], v[138:139], off
	global_load_dwordx4 v[148:151], v[138:139], off offset:16
	global_load_dwordx4 v[152:155], v[138:139], off offset:528
	global_load_dwordx4 v[156:159], v[138:139], off offset:512
	v_or_b32_e32 v114, 0x100, v114
	v_lshl_add_u64 v[112:113], s[6:7], 0, v[114:115]
	global_load_dwordx4 v[160:163], v[112:113], off
	v_lshlrev_b64 v[112:113], 11, v[192:193]
	v_lshl_add_u64 v[112:113], v[112:113], 0, v[190:191]
	v_cndmask_b32_e32 v128, v128, v129, vcc
	v_lshlrev_b64 v[116:117], 1, v[112:113]
	v_rsq_f32_e32 v164, v128
	v_fmamk_f32 v128, v217, 0x3a000000, v206
	v_lshl_add_u64 v[118:119], s[6:7], 0, v[116:117]
	v_or_b32_e32 v116, 0x100, v116
	v_mul_f32_e32 v129, 0x4b800000, v128
	v_cmp_gt_f32_e64 s[2:3], s51, v128
	v_lshl_add_u64 v[136:137], v[112:113], 2, s[62:63]
	v_lshl_add_u64 v[116:117], s[6:7], 0, v[116:117]
	v_cndmask_b32_e64 v128, v128, v129, s[2:3]
	global_load_dwordx4 v[124:127], v[136:137], off offset:16
	global_load_dwordx4 v[132:135], v[136:137], off
	global_load_dwordx4 v[112:115], v[136:137], off offset:528
	global_load_dwordx4 v[120:123], v[136:137], off offset:512
	v_rsq_f32_e32 v165, v128
	global_load_dwordx4 v[128:131], v[118:119], off
	s_nop 0
	global_load_dwordx4 v[116:119], v[116:117], off
	v_mul_f32_e32 v166, 0x45800000, v164
	v_cndmask_b32_e32 v164, v164, v166, vcc
	v_pk_mul_f32 v[108:109], v[108:109], v[164:165] op_sel_hi:[1,0]
	v_pk_mul_f32 v[168:169], v[106:107], v[164:165] op_sel_hi:[1,0]
	v_mul_f32_e32 v106, 0xbfb8aa3b, v108
	v_exp_f32_e32 v108, v106
	v_mul_f32_e32 v106, 0xbfb8aa3b, v109
	v_exp_f32_e32 v109, v106
	v_pk_mul_f32 v[110:111], v[110:111], v[164:165] op_sel_hi:[1,0]
	v_pk_mul_f32 v[106:107], v[104:105], v[164:165] op_sel_hi:[1,0]
	v_add_f32_e32 v104, 1.0, v108
	v_add_f32_e32 v105, 1.0, v109
	v_mul_f32_e32 v110, 0xbfb8aa3b, v110
	v_mul_f32_e32 v111, 0xbfb8aa3b, v111
	v_mul_f32_e32 v166, 0x45800000, v165
	v_rcp_f32_e32 v104, v104
	v_rcp_f32_e32 v105, v105
	v_exp_f32_e32 v110, v110
	v_exp_f32_e32 v111, v111
	v_cndmask_b32_e64 v166, v165, v166, s[2:3]
	v_mul_f32_e32 v106, 0xbfb8aa3b, v106
	v_pk_mul_f32 v[100:101], v[100:101], v[164:165] op_sel_hi:[1,0]
	v_pk_mul_f32 v[102:103], v[102:103], v[164:165] op_sel_hi:[1,0]
	s_waitcnt vmcnt(11)
	v_lshlrev_b32_e32 v108, 16, v140
	v_and_b32_e32 v109, 0xffff0000, v140
	v_pk_mul_f32 v[108:109], v[166:167], v[108:109] op_sel_hi:[0,1]
	v_pk_mul_f32 v[108:109], v[76:77], v[108:109]
	v_exp_f32_e32 v140, v106
	s_waitcnt vmcnt(10)
; __device__ __forceinline__ float bflo(unsigned w) { return __uint_as_float(w << 16); }
; __device__ __forceinline__ float bfhi(unsigned w) { return __uint_as_float(w & 0xffff0000u); }
; __device__ __forceinline__ float sigm(float x) { return __builtin_amdgcn_rcpf(1.f + __builtin_amdgcn_exp2f(-x * LOG2E)); }
;     __device__ __forceinline__ void operator()(const pg8::f32x4 (&acc)[2][2][4][2], const pg8::Unit& u, int wr, int wc, int fr, int fq) const {
;     ...
;                     for (int bj = 0; bj < 2; ++bj) {
;                         const size_t off = (size_t)(row0 + ai * 128 + m * 16) * DM + colb + bj * 128;
;                         const u32x4 pw = pl[mm][bj];
;                         const pg8::f32x4 g0 = gp[bj][0], g1 = gp[bj][1];
;                         pg8::f32x4 x0 = xv[mm][bj][0], x1 = xv[mm][bj][1];
;                         const pg8::f32x4 a0 = acc[ai][bj][m][0] * rs, a1 = acc[ai][bj][m][1] * rs;
;                         x0[0] += sigm(a0[0]) * (bflo(pw[0]) * rp * g0[0]); x0[1] += sigm(a0[1]) * (bfhi(pw[0]) * rp * g0[1]);
;                         x0[2] += sigm(a0[2]) * (bflo(pw[1]) * rp * g0[2]); x0[3] += sigm(a0[3]) * (bfhi(pw[1]) * rp * g0[3]);
;                         x1[0] += sigm(a1[0]) * (bflo(pw[2]) * rp * g1[0]); x1[1] += sigm(a1[1]) * (bfhi(pw[2]) * rp * g1[1]);
;                         x1[2] += sigm(a1[2]) * (bflo(pw[3]) * rp * g1[2]); x1[3] += sigm(a1[3]) * (bfhi(pw[3]) * rp * g1[3]);
;                         *(pg8::f32x4*)(X + off) = x0; *(pg8::f32x4*)(X + off + 4) = x1;
	v_pk_fma_f32 v[104:105], v[104:105], v[108:109], v[144:145]
	v_add_f32_e32 v108, 1.0, v110
	v_add_f32_e32 v109, 1.0, v111
	v_mul_f32_e32 v106, 0xbfb8aa3b, v107
	v_rcp_f32_e32 v108, v108
	v_rcp_f32_e32 v109, v109
	v_lshlrev_b32_e32 v110, 16, v141
	v_and_b32_e32 v111, 0xffff0000, v141
	v_exp_f32_e32 v141, v106
	v_pk_mul_f32 v[110:111], v[166:167], v[110:111] op_sel_hi:[0,1]
	v_pk_mul_f32 v[110:111], v[78:79], v[110:111]
	v_mul_f32_e32 v102, 0xbfb8aa3b, v102
	v_pk_fma_f32 v[106:107], v[108:109], v[110:111], v[146:147]
	v_add_f32_e32 v108, 1.0, v140
	v_add_f32_e32 v109, 1.0, v141
	v_mul_f32_e32 v140, 0xbfb8aa3b, v168
	v_mul_f32_e32 v141, 0xbfb8aa3b, v169
	v_rcp_f32_e32 v108, v108
	v_rcp_f32_e32 v109, v109
	v_exp_f32_e32 v140, v140
	v_exp_f32_e32 v141, v141
	v_lshlrev_b32_e32 v110, 16, v142
	v_and_b32_e32 v111, 0xffff0000, v142
	v_pk_mul_f32 v[110:111], v[166:167], v[110:111] op_sel_hi:[0,1]
	v_pk_mul_f32 v[110:111], v[72:73], v[110:111]
	v_mul_f32_e32 v103, 0xbfb8aa3b, v103
	s_waitcnt vmcnt(9)
	v_pk_fma_f32 v[108:109], v[108:109], v[110:111], v[148:149]
	v_add_f32_e32 v110, 1.0, v140
	v_add_f32_e32 v111, 1.0, v141
	v_rcp_f32_e32 v110, v110
	v_rcp_f32_e32 v111, v111
	v_lshlrev_b32_e32 v140, 16, v143
	v_and_b32_e32 v141, 0xffff0000, v143
	v_pk_mul_f32 v[140:141], v[166:167], v[140:141] op_sel_hi:[0,1]
	v_pk_mul_f32 v[140:141], v[74:75], v[140:141]
	v_exp_f32_e32 v102, v102
	v_pk_fma_f32 v[110:111], v[110:111], v[140:141], v[150:151]
	global_store_dwordx4 v[138:139], v[104:107], off nt
	global_store_dwordx4 v[138:139], v[108:111], off offset:16 nt
	v_exp_f32_e32 v103, v103
	v_pk_mul_f32 v[104:105], v[98:99], v[164:165] op_sel_hi:[1,0]
	v_mul_f32_e32 v98, 0xbfb8aa3b, v100
	v_exp_f32_e32 v100, v98
	v_mul_f32_e32 v98, 0xbfb8aa3b, v101
	v_exp_f32_e32 v101, v98
	v_pk_mul_f32 v[98:99], v[96:97], v[164:165] op_sel_hi:[1,0]
	v_add_f32_e32 v96, 1.0, v100
	v_rcp_f32_e32 v96, v96
	v_add_f32_e32 v97, 1.0, v101
	v_rcp_f32_e32 v97, v97
	s_waitcnt vmcnt(8)
	v_lshlrev_b32_e32 v100, 16, v160
	v_and_b32_e32 v101, 0xffff0000, v160
	v_pk_mul_f32 v[100:101], v[166:167], v[100:101] op_sel_hi:[0,1]
	v_pk_mul_f32 v[100:101], v[64:65], v[100:101]
	v_mul_f32_e32 v98, 0xbfb8aa3b, v98
	v_pk_fma_f32 v[96:97], v[96:97], v[100:101], v[156:157]
	v_add_f32_e32 v100, 1.0, v102
	v_add_f32_e32 v101, 1.0, v103
	v_exp_f32_e32 v106, v98
	v_mul_f32_e32 v98, 0xbfb8aa3b, v99
	v_rcp_f32_e32 v100, v100
	v_rcp_f32_e32 v101, v101
	v_exp_f32_e32 v107, v98
	v_lshlrev_b32_e32 v102, 16, v161
	v_and_b32_e32 v103, 0xffff0000, v161
	v_pk_mul_f32 v[102:103], v[166:167], v[102:103] op_sel_hi:[0,1]
	v_pk_mul_f32 v[102:103], v[66:67], v[102:103]
	v_mul_f32_e32 v104, 0xbfb8aa3b, v104
	v_pk_fma_f32 v[98:99], v[100:101], v[102:103], v[158:159]
	v_add_f32_e32 v100, 1.0, v106
	v_add_f32_e32 v101, 1.0, v107
	v_mul_f32_e32 v105, 0xbfb8aa3b, v105
	v_rcp_f32_e32 v100, v100
	v_rcp_f32_e32 v101, v101
	v_exp_f32_e32 v104, v104
	v_exp_f32_e32 v105, v105
	global_store_dwordx4 v[138:139], v[96:99], off offset:512 nt
	v_lshlrev_b32_e32 v102, 16, v162
	v_and_b32_e32 v103, 0xffff0000, v162
	v_fmamk_f32 v96, v216, 0x3a000000, v206
	v_mul_f32_e32 v97, 0x4b800000, v96
	v_cmp_gt_f32_e32 vcc, s51, v96
	v_pk_mul_f32 v[102:103], v[166:167], v[102:103] op_sel_hi:[0,1]
	v_pk_mul_f32 v[102:103], v[56:57], v[102:103]
	v_cndmask_b32_e32 v96, v96, v97, vcc
	v_fmamk_f32 v97, v215, 0x3a000000, v206
	v_rsq_f32_e32 v96, v96
	v_mul_f32_e32 v98, 0x4b800000, v97
	v_cmp_gt_f32_e64 s[2:3], s51, v97
	v_pk_fma_f32 v[100:101], v[100:101], v[102:103], v[152:153]
	v_add_f32_e32 v102, 1.0, v104
	v_add_f32_e32 v103, 1.0, v105
	v_cndmask_b32_e64 v97, v97, v98, s[2:3]
	v_rcp_f32_e32 v102, v102
	v_rcp_f32_e32 v103, v103
	v_rsq_f32_e32 v97, v97
	v_lshlrev_b32_e32 v104, 16, v163
	v_and_b32_e32 v105, 0xffff0000, v163
	v_pk_mul_f32 v[104:105], v[166:167], v[104:105] op_sel_hi:[0,1]
	v_mul_f32_e32 v98, 0x45800000, v96
	v_pk_mul_f32 v[104:105], v[58:59], v[104:105]
	v_cndmask_b32_e32 v96, v96, v98, vcc
	v_pk_fma_f32 v[102:103], v[102:103], v[104:105], v[154:155]
	v_pk_mul_f32 v[92:93], v[92:93], v[96:97] op_sel_hi:[1,0]
	global_store_dwordx4 v[138:139], v[100:103], off offset:528 nt
	v_pk_mul_f32 v[94:95], v[94:95], v[96:97] op_sel_hi:[1,0]
	v_mul_f32_e32 v98, 0x45800000, v97
	v_pk_mul_f32 v[100:101], v[90:91], v[96:97] op_sel_hi:[1,0]
	v_mul_f32_e32 v90, 0xbfb8aa3b, v92
	v_exp_f32_e32 v92, v90
	v_mul_f32_e32 v90, 0xbfb8aa3b, v93
	v_exp_f32_e32 v93, v90
	v_pk_mul_f32 v[90:91], v[88:89], v[96:97] op_sel_hi:[1,0]
	v_add_f32_e32 v88, 1.0, v92
	v_mul_f32_e32 v94, 0xbfb8aa3b, v94
	v_add_f32_e32 v89, 1.0, v93
	v_mul_f32_e32 v95, 0xbfb8aa3b, v95
	v_rcp_f32_e32 v88, v88
	v_rcp_f32_e32 v89, v89
	v_exp_f32_e32 v94, v94
	v_exp_f32_e32 v95, v95
	v_cndmask_b32_e64 v98, v97, v98, s[2:3]
	s_waitcnt vmcnt(5)
; __device__ __forceinline__ float bflo(unsigned w) { return __uint_as_float(w << 16); }
; __device__ __forceinline__ float bfhi(unsigned w) { return __uint_as_float(w & 0xffff0000u); }
; __device__ __forceinline__ float sigm(float x) { return __builtin_amdgcn_rcpf(1.f + __builtin_amdgcn_exp2f(-x * LOG2E)); }
;     __device__ __forceinline__ void operator()(const pg8::f32x4 (&acc)[2][2][4][2], const pg8::Unit& u, int wr, int wc, int fr, int fq) const {
;     ...
;                 for (int mm = 0; mm < 2; ++mm)
; #pragma unroll
;                     for (int bj = 0; bj < 2; ++bj) { const size_t off = (size_t)(row0 + ai * 128 + (2 * mp + mm) * 16) * DM + colb + bj * 128;
;                         xv[mm][bj][0] = *(const pg8::f32x4*)(X + off); xv[mm][bj][1] = *(const pg8::f32x4*)(X + off + 4); pl[mm][bj] = *(const u32x4*)(PLE + off); }
;     ...
;                     for (int bj = 0; bj < 2; ++bj) {
;                         const size_t off = (size_t)(row0 + ai * 128 + m * 16) * DM + colb + bj * 128;
;                         const u32x4 pw = pl[mm][bj];
;                         const pg8::f32x4 g0 = gp[bj][0], g1 = gp[bj][1];
;                         pg8::f32x4 x0 = xv[mm][bj][0], x1 = xv[mm][bj][1];
;                         const pg8::f32x4 a0 = acc[ai][bj][m][0] * rs, a1 = acc[ai][bj][m][1] * rs;
;                         x0[0] += sigm(a0[0]) * (bflo(pw[0]) * rp * g0[0]); x0[1] += sigm(a0[1]) * (bfhi(pw[0]) * rp * g0[1]);
;                         x0[2] += sigm(a0[2]) * (bflo(pw[1]) * rp * g0[2]); x0[3] += sigm(a0[3]) * (bfhi(pw[1]) * rp * g0[3]);
;                         x1[0] += sigm(a1[0]) * (bflo(pw[2]) * rp * g1[0]); x1[1] += sigm(a1[1]) * (bfhi(pw[2]) * rp * g1[1]);
;                         x1[2] += sigm(a1[2]) * (bflo(pw[3]) * rp * g1[2]); x1[3] += sigm(a1[3]) * (bfhi(pw[3]) * rp * g1[3]);
;                         *(pg8::f32x4*)(X + off) = x0; *(pg8::f32x4*)(X + off + 4) = x1;
	v_lshlrev_b32_e32 v92, 16, v128
	v_and_b32_e32 v93, 0xffff0000, v128
	v_pk_mul_f32 v[92:93], v[98:99], v[92:93] op_sel_hi:[0,1]
	v_pk_mul_f32 v[92:93], v[76:77], v[92:93]
	v_mul_f32_e32 v90, 0xbfb8aa3b, v90
	v_pk_fma_f32 v[88:89], v[88:89], v[92:93], v[132:133]
	v_add_f32_e32 v92, 1.0, v94
	v_add_f32_e32 v93, 1.0, v95
	v_rcp_f32_e32 v92, v92
	v_rcp_f32_e32 v93, v93
	v_lshlrev_b32_e32 v94, 16, v129
	v_and_b32_e32 v95, 0xffff0000, v129
	v_exp_f32_e32 v97, v90
	v_mul_f32_e32 v90, 0xbfb8aa3b, v91
	v_pk_mul_f32 v[94:95], v[98:99], v[94:95] op_sel_hi:[0,1]
	v_exp_f32_e32 v99, v90
	v_pk_mul_f32 v[94:95], v[78:79], v[94:95]
	s_nop 0
	v_pk_fma_f32 v[90:91], v[92:93], v[94:95], v[134:135]
	v_lshlrev_b32_e32 v94, 16, v130
	v_and_b32_e32 v95, 0xffff0000, v130
	v_add_f32_e32 v92, 1.0, v97
	v_add_f32_e32 v93, 1.0, v99
	v_pk_mul_f32 v[94:95], v[98:99], v[94:95] op_sel_hi:[0,1]
	v_mul_f32_e32 v97, 0xbfb8aa3b, v100
	v_mul_f32_e32 v99, 0xbfb8aa3b, v101
	v_rcp_f32_e32 v92, v92
	v_rcp_f32_e32 v93, v93
	v_exp_f32_e32 v97, v97
	v_exp_f32_e32 v99, v99
	v_pk_mul_f32 v[94:95], v[72:73], v[94:95]
	v_lshlrev_b32_e32 v100, 16, v131
	v_pk_fma_f32 v[92:93], v[92:93], v[94:95], v[124:125]
	v_add_f32_e32 v94, 1.0, v97
	v_add_f32_e32 v95, 1.0, v99
	v_rcp_f32_e32 v94, v94
	v_rcp_f32_e32 v95, v95
	v_and_b32_e32 v101, 0xffff0000, v131
	v_pk_mul_f32 v[100:101], v[98:99], v[100:101] op_sel_hi:[0,1]
	v_pk_mul_f32 v[100:101], v[74:75], v[100:101]
	v_pk_mul_f32 v[84:85], v[84:85], v[96:97] op_sel_hi:[1,0]
	v_pk_fma_f32 v[94:95], v[94:95], v[100:101], v[126:127]
	global_store_dwordx4 v[136:137], v[88:91], off nt
	global_store_dwordx4 v[136:137], v[92:95], off offset:16 nt
	v_pk_mul_f32 v[86:87], v[86:87], v[96:97] op_sel_hi:[1,0]
	v_pk_mul_f32 v[88:89], v[82:83], v[96:97] op_sel_hi:[1,0]
	v_mul_f32_e32 v82, 0xbfb8aa3b, v84
	v_exp_f32_e32 v84, v82
	v_mul_f32_e32 v82, 0xbfb8aa3b, v85
	v_exp_f32_e32 v85, v82
	v_pk_mul_f32 v[82:83], v[80:81], v[96:97] op_sel_hi:[1,0]
	v_add_f32_e32 v80, 1.0, v84
	v_mul_f32_e32 v86, 0xbfb8aa3b, v86
	v_add_f32_e32 v81, 1.0, v85
	v_mul_f32_e32 v87, 0xbfb8aa3b, v87
	v_rcp_f32_e32 v80, v80
	v_rcp_f32_e32 v81, v81
	v_exp_f32_e32 v86, v86
	v_exp_f32_e32 v87, v87
	s_waitcnt vmcnt(6)
	v_lshlrev_b32_e32 v84, 16, v116
	v_and_b32_e32 v85, 0xffff0000, v116
	v_pk_mul_f32 v[84:85], v[98:99], v[84:85] op_sel_hi:[0,1]
	v_pk_mul_f32 v[84:85], v[64:65], v[84:85]
	v_mul_f32_e32 v82, 0xbfb8aa3b, v82
	v_pk_fma_f32 v[80:81], v[80:81], v[84:85], v[120:121]
	v_add_f32_e32 v84, 1.0, v86
	v_add_f32_e32 v85, 1.0, v87
	v_exp_f32_e32 v90, v82
	v_mul_f32_e32 v82, 0xbfb8aa3b, v83
	v_rcp_f32_e32 v84, v84
	v_rcp_f32_e32 v85, v85
	v_exp_f32_e32 v91, v82
	v_lshlrev_b32_e32 v86, 16, v117
	v_and_b32_e32 v87, 0xffff0000, v117
	v_pk_mul_f32 v[86:87], v[98:99], v[86:87] op_sel_hi:[0,1]
	v_pk_mul_f32 v[86:87], v[66:67], v[86:87]
	v_mul_f32_e32 v88, 0xbfb8aa3b, v88
	v_pk_fma_f32 v[82:83], v[84:85], v[86:87], v[122:123]
	v_add_f32_e32 v84, 1.0, v90
	v_add_f32_e32 v85, 1.0, v91
	v_mul_f32_e32 v89, 0xbfb8aa3b, v89
	v_rcp_f32_e32 v84, v84
	v_rcp_f32_e32 v85, v85
	v_exp_f32_e32 v88, v88
	v_exp_f32_e32 v89, v89
	v_lshlrev_b32_e32 v86, 16, v118
	v_and_b32_e32 v87, 0xffff0000, v118
	v_pk_mul_f32 v[86:87], v[98:99], v[86:87] op_sel_hi:[0,1]
	v_pk_mul_f32 v[86:87], v[56:57], v[86:87]
	v_fmamk_f32 v96, v214, 0x3a000000, v206
	v_pk_fma_f32 v[84:85], v[84:85], v[86:87], v[112:113]
	v_add_f32_e32 v86, 1.0, v88
	v_add_f32_e32 v87, 1.0, v89
	v_rcp_f32_e32 v86, v86
	v_rcp_f32_e32 v87, v87
	v_lshlrev_b32_e32 v88, 16, v119
	v_and_b32_e32 v89, 0xffff0000, v119
	v_pk_mul_f32 v[88:89], v[98:99], v[88:89] op_sel_hi:[0,1]
	v_pk_mul_f32 v[88:89], v[58:59], v[88:89]
	v_mul_f32_e32 v97, 0x4b800000, v96
	v_pk_fma_f32 v[86:87], v[86:87], v[88:89], v[114:115]
	global_store_dwordx4 v[136:137], v[80:83], off offset:512 nt
	global_store_dwordx4 v[136:137], v[84:87], off offset:528 nt
	v_cmp_gt_f32_e32 vcc, s51, v96
	v_lshl_add_u64 v[80:81], v[188:189], 0, s[14:15]
	v_lshlrev_b64 v[82:83], 1, v[80:81]
	v_lshl_add_u64 v[84:85], s[6:7], 0, v[82:83]
	global_load_dwordx4 v[108:111], v[84:85], off
	v_lshl_add_u64 v[106:107], v[80:81], 2, s[62:63]
	global_load_dwordx4 v[112:115], v[106:107], off
	global_load_dwordx4 v[116:119], v[106:107], off offset:16
	global_load_dwordx4 v[120:123], v[106:107], off offset:528
	global_load_dwordx4 v[124:127], v[106:107], off offset:512
	v_or_b32_e32 v82, 0x100, v82
	v_lshl_add_u64 v[80:81], s[6:7], 0, v[82:83]
	global_load_dwordx4 v[128:131], v[80:81], off
	v_lshl_add_u64 v[80:81], v[188:189], 0, s[18:19]
	v_cndmask_b32_e32 v96, v96, v97, vcc
	v_lshlrev_b64 v[84:85], 1, v[80:81]
	v_rsq_f32_e32 v132, v96
	v_fmamk_f32 v96, v213, 0x3a000000, v206
	v_lshl_add_u64 v[86:87], s[6:7], 0, v[84:85]
	v_or_b32_e32 v84, 0x100, v84
	v_mul_f32_e32 v97, 0x4b800000, v96
	v_cmp_gt_f32_e64 s[2:3], s51, v96
	v_lshl_add_u64 v[104:105], v[80:81], 2, s[62:63]
	v_lshl_add_u64 v[84:85], s[6:7], 0, v[84:85]
	v_cndmask_b32_e64 v96, v96, v97, s[2:3]
	global_load_dwordx4 v[92:95], v[104:105], off offset:16
	global_load_dwordx4 v[100:103], v[104:105], off
	global_load_dwordx4 v[80:83], v[104:105], off offset:528
	global_load_dwordx4 v[88:91], v[104:105], off offset:512
	v_rsq_f32_e32 v133, v96
	global_load_dwordx4 v[96:99], v[86:87], off
	s_nop 0
	global_load_dwordx4 v[84:87], v[84:85], off
	v_mul_f32_e32 v134, 0x45800000, v132
	v_cndmask_b32_e32 v132, v132, v134, vcc
	v_pk_mul_f32 v[68:69], v[68:69], v[132:133] op_sel_hi:[1,0]
	v_pk_mul_f32 v[136:137], v[62:63], v[132:133] op_sel_hi:[1,0]
	v_mul_f32_e32 v62, 0xbfb8aa3b, v68
	v_exp_f32_e32 v68, v62
	v_mul_f32_e32 v62, 0xbfb8aa3b, v69
	v_exp_f32_e32 v69, v62
	v_pk_mul_f32 v[70:71], v[70:71], v[132:133] op_sel_hi:[1,0]
	v_pk_mul_f32 v[62:63], v[60:61], v[132:133] op_sel_hi:[1,0]
	v_add_f32_e32 v60, 1.0, v68
	v_add_f32_e32 v61, 1.0, v69
	v_mul_f32_e32 v70, 0xbfb8aa3b, v70
	v_mul_f32_e32 v71, 0xbfb8aa3b, v71
	v_mul_f32_e32 v134, 0x45800000, v133
	v_rcp_f32_e32 v60, v60
	v_rcp_f32_e32 v61, v61
	v_exp_f32_e32 v70, v70
	v_exp_f32_e32 v71, v71
	v_cndmask_b32_e64 v134, v133, v134, s[2:3]
	v_mul_f32_e32 v62, 0xbfb8aa3b, v62
	v_pk_mul_f32 v[52:53], v[52:53], v[132:133] op_sel_hi:[1,0]
	v_pk_mul_f32 v[54:55], v[54:55], v[132:133] op_sel_hi:[1,0]
	s_waitcnt vmcnt(11)
; __device__ __forceinline__ float bflo(unsigned w) { return __uint_as_float(w << 16); }
; __device__ __forceinline__ float bfhi(unsigned w) { return __uint_as_float(w & 0xffff0000u); }
; __device__ __forceinline__ float sigm(float x) { return __builtin_amdgcn_rcpf(1.f + __builtin_amdgcn_exp2f(-x * LOG2E)); }
;     __device__ __forceinline__ void operator()(const pg8::f32x4 (&acc)[2][2][4][2], const pg8::Unit& u, int wr, int wc, int fr, int fq) const {
;     ...
;                     for (int bj = 0; bj < 2; ++bj) {
;                         const size_t off = (size_t)(row0 + ai * 128 + m * 16) * DM + colb + bj * 128;
;                         const u32x4 pw = pl[mm][bj];
;                         const pg8::f32x4 g0 = gp[bj][0], g1 = gp[bj][1];
;                         pg8::f32x4 x0 = xv[mm][bj][0], x1 = xv[mm][bj][1];
;                         const pg8::f32x4 a0 = acc[ai][bj][m][0] * rs, a1 = acc[ai][bj][m][1] * rs;
;                         x0[0] += sigm(a0[0]) * (bflo(pw[0]) * rp * g0[0]); x0[1] += sigm(a0[1]) * (bfhi(pw[0]) * rp * g0[1]);
;                         x0[2] += sigm(a0[2]) * (bflo(pw[1]) * rp * g0[2]); x0[3] += sigm(a0[3]) * (bfhi(pw[1]) * rp * g0[3]);
;                         x1[0] += sigm(a1[0]) * (bflo(pw[2]) * rp * g1[0]); x1[1] += sigm(a1[1]) * (bfhi(pw[2]) * rp * g1[1]);
;                         x1[2] += sigm(a1[2]) * (bflo(pw[3]) * rp * g1[2]); x1[3] += sigm(a1[3]) * (bfhi(pw[3]) * rp * g1[3]);
;                         *(pg8::f32x4*)(X + off) = x0; *(pg8::f32x4*)(X + off + 4) = x1;
	v_lshlrev_b32_e32 v68, 16, v108
	v_and_b32_e32 v69, 0xffff0000, v108
	v_pk_mul_f32 v[68:69], v[134:135], v[68:69] op_sel_hi:[0,1]
	v_pk_mul_f32 v[68:69], v[76:77], v[68:69]
	v_exp_f32_e32 v108, v62
	s_waitcnt vmcnt(10)
	v_pk_fma_f32 v[60:61], v[60:61], v[68:69], v[112:113]
	v_add_f32_e32 v68, 1.0, v70
	v_add_f32_e32 v69, 1.0, v71
	v_mul_f32_e32 v62, 0xbfb8aa3b, v63
	v_rcp_f32_e32 v68, v68
	v_rcp_f32_e32 v69, v69
	v_lshlrev_b32_e32 v70, 16, v109
	v_and_b32_e32 v71, 0xffff0000, v109
	v_exp_f32_e32 v109, v62
	v_pk_mul_f32 v[70:71], v[134:135], v[70:71] op_sel_hi:[0,1]
	v_pk_mul_f32 v[70:71], v[78:79], v[70:71]
	v_mul_f32_e32 v54, 0xbfb8aa3b, v54
	v_pk_fma_f32 v[62:63], v[68:69], v[70:71], v[114:115]
	v_add_f32_e32 v68, 1.0, v108
	v_add_f32_e32 v69, 1.0, v109
	v_mul_f32_e32 v108, 0xbfb8aa3b, v136
	v_mul_f32_e32 v109, 0xbfb8aa3b, v137
	v_rcp_f32_e32 v68, v68
	v_rcp_f32_e32 v69, v69
	v_exp_f32_e32 v108, v108
	v_exp_f32_e32 v109, v109
	v_lshlrev_b32_e32 v70, 16, v110
	v_and_b32_e32 v71, 0xffff0000, v110
	v_pk_mul_f32 v[70:71], v[134:135], v[70:71] op_sel_hi:[0,1]
	v_pk_mul_f32 v[70:71], v[72:73], v[70:71]
	v_mul_f32_e32 v55, 0xbfb8aa3b, v55
	s_waitcnt vmcnt(9)
	v_pk_fma_f32 v[68:69], v[68:69], v[70:71], v[116:117]
	v_add_f32_e32 v70, 1.0, v108
	v_add_f32_e32 v71, 1.0, v109
	v_rcp_f32_e32 v70, v70
	v_rcp_f32_e32 v71, v71
	v_lshlrev_b32_e32 v108, 16, v111
	v_and_b32_e32 v109, 0xffff0000, v111
	v_pk_mul_f32 v[108:109], v[134:135], v[108:109] op_sel_hi:[0,1]
	v_pk_mul_f32 v[108:109], v[74:75], v[108:109]
	v_exp_f32_e32 v54, v54
	v_pk_fma_f32 v[70:71], v[70:71], v[108:109], v[118:119]
	global_store_dwordx4 v[106:107], v[60:63], off nt
	global_store_dwordx4 v[106:107], v[68:71], off offset:16 nt
	v_exp_f32_e32 v55, v55
	v_pk_mul_f32 v[60:61], v[50:51], v[132:133] op_sel_hi:[1,0]
	v_mul_f32_e32 v50, 0xbfb8aa3b, v52
	v_exp_f32_e32 v52, v50
	v_mul_f32_e32 v50, 0xbfb8aa3b, v53
	v_exp_f32_e32 v53, v50
	v_pk_mul_f32 v[50:51], v[48:49], v[132:133] op_sel_hi:[1,0]
	v_add_f32_e32 v48, 1.0, v52
	v_rcp_f32_e32 v48, v48
	v_add_f32_e32 v49, 1.0, v53
	v_rcp_f32_e32 v49, v49
	s_waitcnt vmcnt(8)
	v_lshlrev_b32_e32 v52, 16, v128
	v_and_b32_e32 v53, 0xffff0000, v128
	v_pk_mul_f32 v[52:53], v[134:135], v[52:53] op_sel_hi:[0,1]
	v_pk_mul_f32 v[52:53], v[64:65], v[52:53]
	v_mul_f32_e32 v50, 0xbfb8aa3b, v50
	v_pk_fma_f32 v[48:49], v[48:49], v[52:53], v[124:125]
	v_add_f32_e32 v52, 1.0, v54
	v_add_f32_e32 v53, 1.0, v55
	v_exp_f32_e32 v62, v50
	v_mul_f32_e32 v50, 0xbfb8aa3b, v51
	v_rcp_f32_e32 v52, v52
	v_rcp_f32_e32 v53, v53
	v_exp_f32_e32 v63, v50
	v_lshlrev_b32_e32 v54, 16, v129
	v_and_b32_e32 v55, 0xffff0000, v129
	v_pk_mul_f32 v[54:55], v[134:135], v[54:55] op_sel_hi:[0,1]
	v_pk_mul_f32 v[54:55], v[66:67], v[54:55]
	v_mul_f32_e32 v60, 0xbfb8aa3b, v60
	v_pk_fma_f32 v[50:51], v[52:53], v[54:55], v[126:127]
	v_add_f32_e32 v52, 1.0, v62
	v_add_f32_e32 v53, 1.0, v63
	v_mul_f32_e32 v61, 0xbfb8aa3b, v61
	v_rcp_f32_e32 v52, v52
	v_rcp_f32_e32 v53, v53
	v_exp_f32_e32 v60, v60
	v_exp_f32_e32 v61, v61
	global_store_dwordx4 v[106:107], v[48:51], off offset:512 nt
	v_lshlrev_b32_e32 v54, 16, v130
	v_and_b32_e32 v55, 0xffff0000, v130
	v_fmamk_f32 v48, v212, 0x3a000000, v206
	v_mul_f32_e32 v49, 0x4b800000, v48
	v_cmp_gt_f32_e32 vcc, s51, v48
	v_pk_mul_f32 v[54:55], v[134:135], v[54:55] op_sel_hi:[0,1]
	v_pk_mul_f32 v[54:55], v[56:57], v[54:55]
	v_cndmask_b32_e32 v48, v48, v49, vcc
	v_fmamk_f32 v49, v211, 0x3a000000, v206
	v_rsq_f32_e32 v48, v48
	v_mul_f32_e32 v50, 0x4b800000, v49
	v_cmp_gt_f32_e64 s[2:3], s51, v49
	v_pk_fma_f32 v[52:53], v[52:53], v[54:55], v[120:121]
	v_add_f32_e32 v54, 1.0, v60
	v_add_f32_e32 v55, 1.0, v61
	v_cndmask_b32_e64 v49, v49, v50, s[2:3]
	v_rcp_f32_e32 v54, v54
	v_rcp_f32_e32 v55, v55
	v_rsq_f32_e32 v49, v49
	v_lshlrev_b32_e32 v60, 16, v131
	v_and_b32_e32 v61, 0xffff0000, v131
	v_pk_mul_f32 v[60:61], v[134:135], v[60:61] op_sel_hi:[0,1]
	v_mul_f32_e32 v50, 0x45800000, v48
	v_pk_mul_f32 v[60:61], v[58:59], v[60:61]
	v_cndmask_b32_e32 v48, v48, v50, vcc
	v_pk_fma_f32 v[54:55], v[54:55], v[60:61], v[122:123]
	v_pk_mul_f32 v[44:45], v[44:45], v[48:49] op_sel_hi:[1,0]
	global_store_dwordx4 v[106:107], v[52:55], off offset:528 nt
	v_pk_mul_f32 v[46:47], v[46:47], v[48:49] op_sel_hi:[1,0]
	v_mul_f32_e32 v50, 0x45800000, v49
	v_pk_mul_f32 v[52:53], v[42:43], v[48:49] op_sel_hi:[1,0]
	v_mul_f32_e32 v42, 0xbfb8aa3b, v44
	v_exp_f32_e32 v44, v42
	v_mul_f32_e32 v42, 0xbfb8aa3b, v45
	v_exp_f32_e32 v45, v42
	v_pk_mul_f32 v[42:43], v[40:41], v[48:49] op_sel_hi:[1,0]
	v_add_f32_e32 v40, 1.0, v44
	v_mul_f32_e32 v46, 0xbfb8aa3b, v46
	v_add_f32_e32 v41, 1.0, v45
	v_mul_f32_e32 v47, 0xbfb8aa3b, v47
	v_rcp_f32_e32 v40, v40
	v_rcp_f32_e32 v41, v41
	v_exp_f32_e32 v46, v46
	v_exp_f32_e32 v47, v47
	v_cndmask_b32_e64 v50, v49, v50, s[2:3]
	s_waitcnt vmcnt(5)
; __device__ __forceinline__ float bflo(unsigned w) { return __uint_as_float(w << 16); }
; __device__ __forceinline__ float bfhi(unsigned w) { return __uint_as_float(w & 0xffff0000u); }
; __device__ __forceinline__ float sigm(float x) { return __builtin_amdgcn_rcpf(1.f + __builtin_amdgcn_exp2f(-x * LOG2E)); }
;     __device__ __forceinline__ void operator()(const pg8::f32x4 (&acc)[2][2][4][2], const pg8::Unit& u, int wr, int wc, int fr, int fq) const {
;     ...
;                 for (int mm = 0; mm < 2; ++mm)
; #pragma unroll
;                     for (int bj = 0; bj < 2; ++bj) { const size_t off = (size_t)(row0 + ai * 128 + (2 * mp + mm) * 16) * DM + colb + bj * 128;
;                         xv[mm][bj][0] = *(const pg8::f32x4*)(X + off); xv[mm][bj][1] = *(const pg8::f32x4*)(X + off + 4); pl[mm][bj] = *(const u32x4*)(PLE + off); }
;     ...
;                     for (int bj = 0; bj < 2; ++bj) {
;                         const size_t off = (size_t)(row0 + ai * 128 + m * 16) * DM + colb + bj * 128;
;                         const u32x4 pw = pl[mm][bj];
;                         const pg8::f32x4 g0 = gp[bj][0], g1 = gp[bj][1];
;                         pg8::f32x4 x0 = xv[mm][bj][0], x1 = xv[mm][bj][1];
;                         const pg8::f32x4 a0 = acc[ai][bj][m][0] * rs, a1 = acc[ai][bj][m][1] * rs;
;                         x0[0] += sigm(a0[0]) * (bflo(pw[0]) * rp * g0[0]); x0[1] += sigm(a0[1]) * (bfhi(pw[0]) * rp * g0[1]);
;                         x0[2] += sigm(a0[2]) * (bflo(pw[1]) * rp * g0[2]); x0[3] += sigm(a0[3]) * (bfhi(pw[1]) * rp * g0[3]);
;                         x1[0] += sigm(a1[0]) * (bflo(pw[2]) * rp * g1[0]); x1[1] += sigm(a1[1]) * (bfhi(pw[2]) * rp * g1[1]);
;                         x1[2] += sigm(a1[2]) * (bflo(pw[3]) * rp * g1[2]); x1[3] += sigm(a1[3]) * (bfhi(pw[3]) * rp * g1[3]);
;                         *(pg8::f32x4*)(X + off) = x0; *(pg8::f32x4*)(X + off + 4) = x1;
	v_lshlrev_b32_e32 v44, 16, v96
	v_and_b32_e32 v45, 0xffff0000, v96
	v_pk_mul_f32 v[44:45], v[50:51], v[44:45] op_sel_hi:[0,1]
	v_pk_mul_f32 v[44:45], v[76:77], v[44:45]
	v_mul_f32_e32 v42, 0xbfb8aa3b, v42
	v_pk_fma_f32 v[40:41], v[40:41], v[44:45], v[100:101]
	v_add_f32_e32 v44, 1.0, v46
	v_add_f32_e32 v45, 1.0, v47
	v_rcp_f32_e32 v44, v44
	v_rcp_f32_e32 v45, v45
	v_lshlrev_b32_e32 v46, 16, v97
	v_and_b32_e32 v47, 0xffff0000, v97
	v_exp_f32_e32 v49, v42
	v_mul_f32_e32 v42, 0xbfb8aa3b, v43
	v_pk_mul_f32 v[46:47], v[50:51], v[46:47] op_sel_hi:[0,1]
	v_exp_f32_e32 v51, v42
	v_pk_mul_f32 v[46:47], v[78:79], v[46:47]
	s_nop 0
	v_pk_fma_f32 v[42:43], v[44:45], v[46:47], v[102:103]
	v_lshlrev_b32_e32 v46, 16, v98
	v_and_b32_e32 v47, 0xffff0000, v98
	v_add_f32_e32 v44, 1.0, v49
	v_add_f32_e32 v45, 1.0, v51
	v_pk_mul_f32 v[46:47], v[50:51], v[46:47] op_sel_hi:[0,1]
	v_mul_f32_e32 v49, 0xbfb8aa3b, v52
	v_mul_f32_e32 v51, 0xbfb8aa3b, v53
	v_rcp_f32_e32 v44, v44
	v_rcp_f32_e32 v45, v45
	v_exp_f32_e32 v49, v49
	v_exp_f32_e32 v51, v51
	v_pk_mul_f32 v[46:47], v[72:73], v[46:47]
	v_lshlrev_b32_e32 v52, 16, v99
	v_pk_fma_f32 v[44:45], v[44:45], v[46:47], v[92:93]
	v_add_f32_e32 v46, 1.0, v49
	v_add_f32_e32 v47, 1.0, v51
	v_rcp_f32_e32 v46, v46
	v_rcp_f32_e32 v47, v47
	v_and_b32_e32 v53, 0xffff0000, v99
	v_pk_mul_f32 v[52:53], v[50:51], v[52:53] op_sel_hi:[0,1]
	v_pk_mul_f32 v[52:53], v[74:75], v[52:53]
	v_pk_mul_f32 v[36:37], v[36:37], v[48:49] op_sel_hi:[1,0]
	v_pk_fma_f32 v[46:47], v[46:47], v[52:53], v[94:95]
	global_store_dwordx4 v[104:105], v[40:43], off nt
	global_store_dwordx4 v[104:105], v[44:47], off offset:16 nt
	v_pk_mul_f32 v[38:39], v[38:39], v[48:49] op_sel_hi:[1,0]
	v_pk_mul_f32 v[40:41], v[34:35], v[48:49] op_sel_hi:[1,0]
	v_mul_f32_e32 v34, 0xbfb8aa3b, v36
	v_exp_f32_e32 v36, v34
	v_mul_f32_e32 v34, 0xbfb8aa3b, v37
	v_exp_f32_e32 v37, v34
	v_pk_mul_f32 v[34:35], v[32:33], v[48:49] op_sel_hi:[1,0]
	v_add_f32_e32 v32, 1.0, v36
	v_mul_f32_e32 v38, 0xbfb8aa3b, v38
	v_add_f32_e32 v33, 1.0, v37
	v_mul_f32_e32 v39, 0xbfb8aa3b, v39
	v_rcp_f32_e32 v32, v32
	v_rcp_f32_e32 v33, v33
	v_exp_f32_e32 v38, v38
	v_exp_f32_e32 v39, v39
	s_waitcnt vmcnt(6)
	v_lshlrev_b32_e32 v36, 16, v84
	v_and_b32_e32 v37, 0xffff0000, v84
	v_pk_mul_f32 v[36:37], v[50:51], v[36:37] op_sel_hi:[0,1]
	v_pk_mul_f32 v[36:37], v[64:65], v[36:37]
	v_mul_f32_e32 v34, 0xbfb8aa3b, v34
	v_pk_fma_f32 v[32:33], v[32:33], v[36:37], v[88:89]
	v_add_f32_e32 v36, 1.0, v38
	v_add_f32_e32 v37, 1.0, v39
	v_exp_f32_e32 v42, v34
	v_mul_f32_e32 v34, 0xbfb8aa3b, v35
	v_rcp_f32_e32 v36, v36
	v_rcp_f32_e32 v37, v37
	v_exp_f32_e32 v43, v34
	v_lshlrev_b32_e32 v38, 16, v85
	v_and_b32_e32 v39, 0xffff0000, v85
	v_pk_mul_f32 v[38:39], v[50:51], v[38:39] op_sel_hi:[0,1]
	v_pk_mul_f32 v[38:39], v[66:67], v[38:39]
	v_mul_f32_e32 v40, 0xbfb8aa3b, v40
	v_pk_fma_f32 v[34:35], v[36:37], v[38:39], v[90:91]
	v_add_f32_e32 v36, 1.0, v42
	v_add_f32_e32 v37, 1.0, v43
	v_mul_f32_e32 v41, 0xbfb8aa3b, v41
	v_rcp_f32_e32 v36, v36
	v_rcp_f32_e32 v37, v37
	v_exp_f32_e32 v40, v40
	v_exp_f32_e32 v41, v41
	v_lshlrev_b32_e32 v38, 16, v86
	v_and_b32_e32 v39, 0xffff0000, v86
	v_pk_mul_f32 v[38:39], v[50:51], v[38:39] op_sel_hi:[0,1]
	v_pk_mul_f32 v[38:39], v[56:57], v[38:39]
	v_fmamk_f32 v48, v210, 0x3a000000, v206
	v_pk_fma_f32 v[36:37], v[36:37], v[38:39], v[80:81]
	v_add_f32_e32 v38, 1.0, v40
	v_add_f32_e32 v39, 1.0, v41
	v_rcp_f32_e32 v38, v38
	v_rcp_f32_e32 v39, v39
	v_lshlrev_b32_e32 v40, 16, v87
	v_and_b32_e32 v41, 0xffff0000, v87
	v_pk_mul_f32 v[40:41], v[50:51], v[40:41] op_sel_hi:[0,1]
	v_pk_mul_f32 v[40:41], v[58:59], v[40:41]
	v_mul_f32_e32 v49, 0x4b800000, v48
	v_pk_fma_f32 v[38:39], v[38:39], v[40:41], v[82:83]
	global_store_dwordx4 v[104:105], v[32:35], off offset:512 nt
	global_store_dwordx4 v[104:105], v[36:39], off offset:528 nt
	v_cmp_gt_f32_e32 vcc, s51, v48
	v_lshl_add_u64 v[32:33], v[188:189], 0, s[20:21]
	v_lshlrev_b64 v[34:35], 1, v[32:33]
	v_lshl_add_u64 v[36:37], s[6:7], 0, v[34:35]
	global_load_dwordx4 v[68:71], v[36:37], off
	v_lshl_add_u64 v[62:63], v[32:33], 2, s[62:63]
	global_load_dwordx4 v[80:83], v[62:63], off
	global_load_dwordx4 v[84:87], v[62:63], off offset:16
	global_load_dwordx4 v[88:91], v[62:63], off offset:528
	global_load_dwordx4 v[92:95], v[62:63], off offset:512
	v_or_b32_e32 v34, 0x100, v34
	v_lshl_add_u64 v[32:33], s[6:7], 0, v[34:35]
	global_load_dwordx4 v[96:99], v[32:33], off
	v_lshl_add_u64 v[32:33], v[188:189], 0, s[22:23]
	v_cndmask_b32_e32 v48, v48, v49, vcc
	v_lshlrev_b64 v[36:37], 1, v[32:33]
	v_rsq_f32_e32 v100, v48
	v_fmamk_f32 v48, v209, 0x3a000000, v206
	v_lshl_add_u64 v[38:39], s[6:7], 0, v[36:37]
	v_or_b32_e32 v36, 0x100, v36
	v_mul_f32_e32 v49, 0x4b800000, v48
	v_cmp_gt_f32_e64 s[2:3], s51, v48
	v_lshl_add_u64 v[60:61], v[32:33], 2, s[62:63]
	v_lshl_add_u64 v[36:37], s[6:7], 0, v[36:37]
	v_cndmask_b32_e64 v48, v48, v49, s[2:3]
	global_load_dwordx4 v[44:47], v[60:61], off offset:16
	global_load_dwordx4 v[52:55], v[60:61], off
	global_load_dwordx4 v[32:35], v[60:61], off offset:528
	global_load_dwordx4 v[40:43], v[60:61], off offset:512
	v_rsq_f32_e32 v101, v48
	global_load_dwordx4 v[48:51], v[38:39], off
	s_nop 0
	global_load_dwordx4 v[36:39], v[36:37], off
	v_mul_f32_e32 v102, 0x45800000, v100
	v_cndmask_b32_e32 v100, v100, v102, vcc
	v_pk_mul_f32 v[28:29], v[28:29], v[100:101] op_sel_hi:[1,0]
	v_pk_mul_f32 v[104:105], v[26:27], v[100:101] op_sel_hi:[1,0]
	v_mul_f32_e32 v26, 0xbfb8aa3b, v28
	v_exp_f32_e32 v28, v26
	v_mul_f32_e32 v26, 0xbfb8aa3b, v29
	v_exp_f32_e32 v29, v26
	v_pk_mul_f32 v[30:31], v[30:31], v[100:101] op_sel_hi:[1,0]
	v_pk_mul_f32 v[26:27], v[24:25], v[100:101] op_sel_hi:[1,0]
	v_add_f32_e32 v24, 1.0, v28
	v_add_f32_e32 v25, 1.0, v29
	v_mul_f32_e32 v30, 0xbfb8aa3b, v30
	v_mul_f32_e32 v31, 0xbfb8aa3b, v31
	v_mul_f32_e32 v102, 0x45800000, v101
	v_rcp_f32_e32 v24, v24
	v_rcp_f32_e32 v25, v25
	v_exp_f32_e32 v30, v30
	v_exp_f32_e32 v31, v31
	v_cndmask_b32_e64 v102, v101, v102, s[2:3]
	v_mul_f32_e32 v26, 0xbfb8aa3b, v26
	v_pk_mul_f32 v[20:21], v[20:21], v[100:101] op_sel_hi:[1,0]
	v_pk_mul_f32 v[22:23], v[22:23], v[100:101] op_sel_hi:[1,0]
	s_waitcnt vmcnt(11)
; __device__ __forceinline__ float bflo(unsigned w) { return __uint_as_float(w << 16); }
; __device__ __forceinline__ float bfhi(unsigned w) { return __uint_as_float(w & 0xffff0000u); }
; __device__ __forceinline__ float sigm(float x) { return __builtin_amdgcn_rcpf(1.f + __builtin_amdgcn_exp2f(-x * LOG2E)); }
;     __device__ __forceinline__ void operator()(const pg8::f32x4 (&acc)[2][2][4][2], const pg8::Unit& u, int wr, int wc, int fr, int fq) const {
;     ...
;                     for (int bj = 0; bj < 2; ++bj) {
;                         const size_t off = (size_t)(row0 + ai * 128 + m * 16) * DM + colb + bj * 128;
;                         const u32x4 pw = pl[mm][bj];
;                         const pg8::f32x4 g0 = gp[bj][0], g1 = gp[bj][1];
;                         pg8::f32x4 x0 = xv[mm][bj][0], x1 = xv[mm][bj][1];
;                         const pg8::f32x4 a0 = acc[ai][bj][m][0] * rs, a1 = acc[ai][bj][m][1] * rs;
;                         x0[0] += sigm(a0[0]) * (bflo(pw[0]) * rp * g0[0]); x0[1] += sigm(a0[1]) * (bfhi(pw[0]) * rp * g0[1]);
;                         x0[2] += sigm(a0[2]) * (bflo(pw[1]) * rp * g0[2]); x0[3] += sigm(a0[3]) * (bfhi(pw[1]) * rp * g0[3]);
;                         x1[0] += sigm(a1[0]) * (bflo(pw[2]) * rp * g1[0]); x1[1] += sigm(a1[1]) * (bfhi(pw[2]) * rp * g1[1]);
;                         x1[2] += sigm(a1[2]) * (bflo(pw[3]) * rp * g1[2]); x1[3] += sigm(a1[3]) * (bfhi(pw[3]) * rp * g1[3]);
;                         *(pg8::f32x4*)(X + off) = x0; *(pg8::f32x4*)(X + off + 4) = x1;
	v_lshlrev_b32_e32 v28, 16, v68
	v_and_b32_e32 v29, 0xffff0000, v68
	v_pk_mul_f32 v[28:29], v[102:103], v[28:29] op_sel_hi:[0,1]
	v_pk_mul_f32 v[28:29], v[76:77], v[28:29]
	v_exp_f32_e32 v68, v26
	s_waitcnt vmcnt(10)
	v_pk_fma_f32 v[24:25], v[24:25], v[28:29], v[80:81]
	v_add_f32_e32 v28, 1.0, v30
	v_add_f32_e32 v29, 1.0, v31
	v_mul_f32_e32 v26, 0xbfb8aa3b, v27
	v_rcp_f32_e32 v28, v28
	v_rcp_f32_e32 v29, v29
	v_lshlrev_b32_e32 v30, 16, v69
	v_and_b32_e32 v31, 0xffff0000, v69
	v_exp_f32_e32 v69, v26
	v_pk_mul_f32 v[30:31], v[102:103], v[30:31] op_sel_hi:[0,1]
	v_pk_mul_f32 v[30:31], v[78:79], v[30:31]
	v_mul_f32_e32 v22, 0xbfb8aa3b, v22
	v_pk_fma_f32 v[26:27], v[28:29], v[30:31], v[82:83]
	v_add_f32_e32 v28, 1.0, v68
	v_add_f32_e32 v29, 1.0, v69
	v_mul_f32_e32 v68, 0xbfb8aa3b, v104
	v_mul_f32_e32 v69, 0xbfb8aa3b, v105
	v_rcp_f32_e32 v28, v28
	v_rcp_f32_e32 v29, v29
	v_exp_f32_e32 v68, v68
	v_exp_f32_e32 v69, v69
	v_lshlrev_b32_e32 v30, 16, v70
	v_and_b32_e32 v31, 0xffff0000, v70
	v_pk_mul_f32 v[30:31], v[102:103], v[30:31] op_sel_hi:[0,1]
	v_pk_mul_f32 v[30:31], v[72:73], v[30:31]
	v_mul_f32_e32 v23, 0xbfb8aa3b, v23
	s_waitcnt vmcnt(9)
	v_pk_fma_f32 v[28:29], v[28:29], v[30:31], v[84:85]
	v_add_f32_e32 v30, 1.0, v68
	v_add_f32_e32 v31, 1.0, v69
	v_rcp_f32_e32 v30, v30
	v_rcp_f32_e32 v31, v31
	v_lshlrev_b32_e32 v68, 16, v71
	v_and_b32_e32 v69, 0xffff0000, v71
	v_pk_mul_f32 v[68:69], v[102:103], v[68:69] op_sel_hi:[0,1]
	v_pk_mul_f32 v[68:69], v[74:75], v[68:69]
	v_exp_f32_e32 v22, v22
	v_pk_fma_f32 v[30:31], v[30:31], v[68:69], v[86:87]
	global_store_dwordx4 v[62:63], v[24:27], off nt
	global_store_dwordx4 v[62:63], v[28:31], off offset:16 nt
	v_exp_f32_e32 v23, v23
	v_pk_mul_f32 v[24:25], v[18:19], v[100:101] op_sel_hi:[1,0]
	v_mul_f32_e32 v18, 0xbfb8aa3b, v20
	v_exp_f32_e32 v20, v18
	v_mul_f32_e32 v18, 0xbfb8aa3b, v21
	v_exp_f32_e32 v21, v18
	v_pk_mul_f32 v[18:19], v[16:17], v[100:101] op_sel_hi:[1,0]
	v_add_f32_e32 v16, 1.0, v20
	v_rcp_f32_e32 v16, v16
	v_add_f32_e32 v17, 1.0, v21
	v_rcp_f32_e32 v17, v17
	s_waitcnt vmcnt(8)
	v_lshlrev_b32_e32 v20, 16, v96
	v_and_b32_e32 v21, 0xffff0000, v96
	v_pk_mul_f32 v[20:21], v[102:103], v[20:21] op_sel_hi:[0,1]
	v_pk_mul_f32 v[20:21], v[64:65], v[20:21]
	v_mul_f32_e32 v18, 0xbfb8aa3b, v18
	v_pk_fma_f32 v[16:17], v[16:17], v[20:21], v[92:93]
	v_add_f32_e32 v20, 1.0, v22
	v_add_f32_e32 v21, 1.0, v23
	v_exp_f32_e32 v26, v18
	v_mul_f32_e32 v18, 0xbfb8aa3b, v19
	v_rcp_f32_e32 v20, v20
	v_rcp_f32_e32 v21, v21
	v_exp_f32_e32 v27, v18
	v_lshlrev_b32_e32 v22, 16, v97
	v_and_b32_e32 v23, 0xffff0000, v97
	v_pk_mul_f32 v[22:23], v[102:103], v[22:23] op_sel_hi:[0,1]
	v_pk_mul_f32 v[22:23], v[66:67], v[22:23]
	v_mul_f32_e32 v24, 0xbfb8aa3b, v24
	v_pk_fma_f32 v[18:19], v[20:21], v[22:23], v[94:95]
	v_add_f32_e32 v20, 1.0, v26
	v_add_f32_e32 v21, 1.0, v27
	v_mul_f32_e32 v25, 0xbfb8aa3b, v25
	v_rcp_f32_e32 v20, v20
	v_rcp_f32_e32 v21, v21
	v_exp_f32_e32 v24, v24
	v_exp_f32_e32 v25, v25
	global_store_dwordx4 v[62:63], v[16:19], off offset:512 nt
	v_lshlrev_b32_e32 v22, 16, v98
	v_and_b32_e32 v23, 0xffff0000, v98
	v_fmamk_f32 v16, v207, 0x3a000000, v206
	v_mul_f32_e32 v17, 0x4b800000, v16
	v_cmp_gt_f32_e32 vcc, s51, v16
	v_pk_mul_f32 v[22:23], v[102:103], v[22:23] op_sel_hi:[0,1]
	v_pk_mul_f32 v[22:23], v[56:57], v[22:23]
	v_cndmask_b32_e32 v16, v16, v17, vcc
	v_fmamk_f32 v17, v208, 0x3a000000, v206
	v_rsq_f32_e32 v16, v16
	v_mul_f32_e32 v18, 0x4b800000, v17
	v_cmp_gt_f32_e64 s[2:3], s51, v17
	v_pk_fma_f32 v[20:21], v[20:21], v[22:23], v[88:89]
	v_add_f32_e32 v22, 1.0, v24
	v_add_f32_e32 v23, 1.0, v25
	v_cndmask_b32_e64 v17, v17, v18, s[2:3]
	v_rcp_f32_e32 v22, v22
	v_rcp_f32_e32 v23, v23
	v_rsq_f32_e32 v17, v17
	v_lshlrev_b32_e32 v24, 16, v99
	v_and_b32_e32 v25, 0xffff0000, v99
	v_pk_mul_f32 v[24:25], v[102:103], v[24:25] op_sel_hi:[0,1]
	v_mul_f32_e32 v18, 0x45800000, v16
	v_pk_mul_f32 v[24:25], v[58:59], v[24:25]
	v_cndmask_b32_e32 v16, v16, v18, vcc
	v_pk_fma_f32 v[22:23], v[22:23], v[24:25], v[90:91]
	v_pk_mul_f32 v[12:13], v[12:13], v[16:17] op_sel_hi:[1,0]
	global_store_dwordx4 v[62:63], v[20:23], off offset:528 nt
	v_pk_mul_f32 v[14:15], v[14:15], v[16:17] op_sel_hi:[1,0]
	v_mul_f32_e32 v18, 0x45800000, v17
	v_pk_mul_f32 v[20:21], v[10:11], v[16:17] op_sel_hi:[1,0]
	v_mul_f32_e32 v10, 0xbfb8aa3b, v12
	v_exp_f32_e32 v12, v10
	v_mul_f32_e32 v10, 0xbfb8aa3b, v13
	v_exp_f32_e32 v13, v10
	v_pk_mul_f32 v[10:11], v[8:9], v[16:17] op_sel_hi:[1,0]
	v_add_f32_e32 v8, 1.0, v12
	v_mul_f32_e32 v14, 0xbfb8aa3b, v14
	v_add_f32_e32 v9, 1.0, v13
	v_mul_f32_e32 v15, 0xbfb8aa3b, v15
	v_rcp_f32_e32 v8, v8
	v_rcp_f32_e32 v9, v9
	v_exp_f32_e32 v14, v14
	v_exp_f32_e32 v15, v15
	v_cndmask_b32_e64 v18, v17, v18, s[2:3]
	s_waitcnt vmcnt(5)
; #define PG8_BAR __builtin_amdgcn_s_barrier()
; __device__ __forceinline__ float bflo(unsigned w) { return __uint_as_float(w << 16); }
; __device__ __forceinline__ float bfhi(unsigned w) { return __uint_as_float(w & 0xffff0000u); }
; __device__ __forceinline__ float sigm(float x) { return __builtin_amdgcn_rcpf(1.f + __builtin_amdgcn_exp2f(-x * LOG2E)); }
; template <class Epi, class Sched, bool ALIGN_EPI = false, bool SP2 = false>
; __device__ __forceinline__ void gemm_phase(PG8_LAS unsigned char* lds, const Gemm g, const Sched& S, const Epi& E) {
;     ...
;         if (!has_next) break;
; #pragma unroll
;         for (int a = 0; a < 2; ++a)
; #pragma unroll
;             for (int b = 0; b < 2; ++b)
; #pragma unroll
;                 for (int m = 0; m < 4; ++m)
; #pragma unroll
;                     for (int n = 0; n < 2; ++n) acc[a][b][m][n] = (f32x4){0.f, 0.f, 0.f, 0.f};
;         cur = nxt; cA = nA; cB = nB; ++ui;
;         if constexpr (ALIGN_EPI) { if (wr == 1) PG8_BAR; }
;     __device__ __forceinline__ void operator()(const pg8::f32x4 (&acc)[2][2][4][2], const pg8::Unit& u, int wr, int wc, int fr, int fq) const {
;     ...
;                     for (int bj = 0; bj < 2; ++bj) {
;                         const size_t off = (size_t)(row0 + ai * 128 + m * 16) * DM + colb + bj * 128;
;                         const u32x4 pw = pl[mm][bj];
;                         const pg8::f32x4 g0 = gp[bj][0], g1 = gp[bj][1];
;                         pg8::f32x4 x0 = xv[mm][bj][0], x1 = xv[mm][bj][1];
;                         const pg8::f32x4 a0 = acc[ai][bj][m][0] * rs, a1 = acc[ai][bj][m][1] * rs;
;                         x0[0] += sigm(a0[0]) * (bflo(pw[0]) * rp * g0[0]); x0[1] += sigm(a0[1]) * (bfhi(pw[0]) * rp * g0[1]);
;                         x0[2] += sigm(a0[2]) * (bflo(pw[1]) * rp * g0[2]); x0[3] += sigm(a0[3]) * (bfhi(pw[1]) * rp * g0[3]);
;                         x1[0] += sigm(a1[0]) * (bflo(pw[2]) * rp * g1[0]); x1[1] += sigm(a1[1]) * (bfhi(pw[2]) * rp * g1[1]);
;                         x1[2] += sigm(a1[2]) * (bflo(pw[3]) * rp * g1[2]); x1[3] += sigm(a1[3]) * (bfhi(pw[3]) * rp * g1[3]);
;                         *(pg8::f32x4*)(X + off) = x0; *(pg8::f32x4*)(X + off + 4) = x1;
;                     }
;                 }
;             }
	v_lshlrev_b32_e32 v12, 16, v48
	v_and_b32_e32 v13, 0xffff0000, v48
	v_pk_mul_f32 v[12:13], v[18:19], v[12:13] op_sel_hi:[0,1]
	v_pk_mul_f32 v[12:13], v[76:77], v[12:13]
	v_mul_f32_e32 v10, 0xbfb8aa3b, v10
	v_pk_fma_f32 v[8:9], v[8:9], v[12:13], v[52:53]
	v_add_f32_e32 v12, 1.0, v14
	v_add_f32_e32 v13, 1.0, v15
	v_rcp_f32_e32 v12, v12
	v_rcp_f32_e32 v13, v13
	v_lshlrev_b32_e32 v14, 16, v49
	v_and_b32_e32 v15, 0xffff0000, v49
	v_exp_f32_e32 v17, v10
	v_mul_f32_e32 v10, 0xbfb8aa3b, v11
	v_pk_mul_f32 v[14:15], v[18:19], v[14:15] op_sel_hi:[0,1]
	v_exp_f32_e32 v19, v10
	v_pk_mul_f32 v[14:15], v[78:79], v[14:15]
	s_andn2_b64 vcc, exec, s[0:1]
	v_pk_fma_f32 v[10:11], v[12:13], v[14:15], v[54:55]
	v_lshlrev_b32_e32 v14, 16, v50
	v_and_b32_e32 v15, 0xffff0000, v50
	v_add_f32_e32 v12, 1.0, v17
	v_add_f32_e32 v13, 1.0, v19
	v_pk_mul_f32 v[14:15], v[18:19], v[14:15] op_sel_hi:[0,1]
	v_mul_f32_e32 v17, 0xbfb8aa3b, v20
	v_mul_f32_e32 v19, 0xbfb8aa3b, v21
	v_rcp_f32_e32 v12, v12
	v_rcp_f32_e32 v13, v13
	v_exp_f32_e32 v17, v17
	v_exp_f32_e32 v19, v19
	v_pk_mul_f32 v[14:15], v[72:73], v[14:15]
	v_lshlrev_b32_e32 v20, 16, v51
	v_pk_fma_f32 v[12:13], v[12:13], v[14:15], v[44:45]
	v_add_f32_e32 v14, 1.0, v17
	v_add_f32_e32 v15, 1.0, v19
	v_rcp_f32_e32 v14, v14
	v_rcp_f32_e32 v15, v15
	v_and_b32_e32 v21, 0xffff0000, v51
	v_pk_mul_f32 v[20:21], v[18:19], v[20:21] op_sel_hi:[0,1]
	v_pk_mul_f32 v[20:21], v[74:75], v[20:21]
	v_pk_mul_f32 v[4:5], v[4:5], v[16:17] op_sel_hi:[1,0]
	v_pk_fma_f32 v[14:15], v[14:15], v[20:21], v[46:47]
	global_store_dwordx4 v[60:61], v[8:11], off nt
	global_store_dwordx4 v[60:61], v[12:15], off offset:16 nt
	v_pk_mul_f32 v[6:7], v[6:7], v[16:17] op_sel_hi:[1,0]
	v_pk_mul_f32 v[8:9], v[2:3], v[16:17] op_sel_hi:[1,0]
	v_mul_f32_e32 v2, 0xbfb8aa3b, v4
	v_exp_f32_e32 v4, v2
	v_mul_f32_e32 v2, 0xbfb8aa3b, v5
	v_exp_f32_e32 v5, v2
	v_pk_mul_f32 v[2:3], v[0:1], v[16:17] op_sel_hi:[1,0]
	v_add_f32_e32 v0, 1.0, v4
	v_mul_f32_e32 v6, 0xbfb8aa3b, v6
	v_add_f32_e32 v1, 1.0, v5
	v_mul_f32_e32 v7, 0xbfb8aa3b, v7
	v_rcp_f32_e32 v0, v0
	v_rcp_f32_e32 v1, v1
	v_exp_f32_e32 v6, v6
	v_exp_f32_e32 v7, v7
	s_waitcnt vmcnt(6)
	v_lshlrev_b32_e32 v4, 16, v36
	v_and_b32_e32 v5, 0xffff0000, v36
	v_pk_mul_f32 v[4:5], v[18:19], v[4:5] op_sel_hi:[0,1]
	v_pk_mul_f32 v[4:5], v[64:65], v[4:5]
	v_mul_f32_e32 v2, 0xbfb8aa3b, v2
	v_pk_fma_f32 v[0:1], v[0:1], v[4:5], v[40:41]
	v_add_f32_e32 v4, 1.0, v6
	v_add_f32_e32 v5, 1.0, v7
	v_exp_f32_e32 v10, v2
	v_mul_f32_e32 v2, 0xbfb8aa3b, v3
	v_rcp_f32_e32 v4, v4
	v_rcp_f32_e32 v5, v5
	v_exp_f32_e32 v11, v2
	v_lshlrev_b32_e32 v6, 16, v37
	v_and_b32_e32 v7, 0xffff0000, v37
	v_pk_mul_f32 v[6:7], v[18:19], v[6:7] op_sel_hi:[0,1]
	v_pk_mul_f32 v[6:7], v[66:67], v[6:7]
	v_mul_f32_e32 v8, 0xbfb8aa3b, v8
	v_pk_fma_f32 v[2:3], v[4:5], v[6:7], v[42:43]
	v_add_f32_e32 v4, 1.0, v10
	v_add_f32_e32 v5, 1.0, v11
	v_mul_f32_e32 v9, 0xbfb8aa3b, v9
	v_rcp_f32_e32 v4, v4
	v_rcp_f32_e32 v5, v5
	v_exp_f32_e32 v8, v8
	v_exp_f32_e32 v9, v9
	v_lshlrev_b32_e32 v6, 16, v38
	v_and_b32_e32 v7, 0xffff0000, v38
	v_pk_mul_f32 v[6:7], v[18:19], v[6:7] op_sel_hi:[0,1]
	v_pk_mul_f32 v[6:7], v[56:57], v[6:7]
	s_mov_b64 s[0:1], -1
	v_pk_fma_f32 v[4:5], v[4:5], v[6:7], v[32:33]
	v_add_f32_e32 v6, 1.0, v8
	v_add_f32_e32 v7, 1.0, v9
	v_rcp_f32_e32 v6, v6
	v_rcp_f32_e32 v7, v7
	v_lshlrev_b32_e32 v8, 16, v39
	v_and_b32_e32 v9, 0xffff0000, v39
	v_pk_mul_f32 v[8:9], v[18:19], v[8:9] op_sel_hi:[0,1]
	v_pk_mul_f32 v[8:9], v[58:59], v[8:9]
	s_nop 0
	v_pk_fma_f32 v[6:7], v[6:7], v[8:9], v[34:35]
	global_store_dwordx4 v[60:61], v[0:3], off offset:512 nt
	global_store_dwordx4 v[60:61], v[4:7], off offset:528 nt
	s_cbranch_vccnz .LBB0_1287
	s_andn2_b64 vcc, exec, s[4:5]
	s_cbranch_vccnz .LBB0_1286
	s_barrier
	s_branch .LBB0_1286
